# 27 further xor-16/32 lane exchanges feeding a single add/max converted from ds_bpermute to v_permlane16/32_swap (E and G epilogue row sums and attention reductions)
# baseline (speedup 1.0000x reference)
; __device__ __forceinline__ u32x2 pack4(f32x4 v) { u32x2 r; r.x = cvt_pk(v[0], v[1]); r.y = cvt_pk(v[2], v[3]); return r; }
; __device__ __forceinline__ void phaseA(const Params& p, const int wv, const int rep) {
;     ...
;       const int r = r_ >= T + 2048 ? r_ - (T + 2048) : r_;
;       const float* w = r < T ? p.in[7] : p.in[19];
;       u16* dst = r < T ? XN + (size_t)r * 1024 : MN + (size_t)(r - T) * 1024;
;       float ss = 0.f;
; #pragma unroll
;       for (int i = 0; i < 4; ++i) ss += v[i][0] * v[i][0] + v[i][1] * v[i][1] + v[i][2] * v[i][2] + v[i][3] * v[i][3];
;       ss = wave_sum(ss);
;       const float rstd = rsqrtf(ss * (1.f / 1024.f) + EPS);
; #pragma unroll
;       for (int i = 0; i < 4; ++i) { f32x4 wv4 = *(const f32x4*)(w + (i * 64 + lane) * 4); *(u32x2*)(dst + (i * 64 + lane) * 4) = pack4(v[i] * rstd * wv4); }
; #pragma unroll
;       for (int i = 0; i < 4; ++i) v[i] = vn[i];
;       r_ = rn;
;     }
.LBB0_100:
	s_add_i32 s0, s18, 0xffffb780
	s_cmpk_gt_i32 s18, 0x487f
	s_cselect_b32 s0, s0, s18
	s_add_i32 s8, s0, 0xffffbf80
	s_ashr_i32 s9, s0, 31
	v_readlane_b32 s56, v251, 6
	v_readlane_b32 s12, v251, 22
	s_cmpk_lt_i32 s0, 0x4080
	v_readlane_b32 s70, v251, 20
	v_readlane_b32 s71, v251, 21
	v_readlane_b32 s18, v251, 28
	v_readlane_b32 s19, v251, 29
	s_cselect_b32 s10, s71, s19
	s_cselect_b32 s11, s70, s18
	v_mov_b32_e32 v42, s11
	v_mov_b32_e32 v43, s10
	v_lshl_add_u64 v[42:43], v[34:35], 2, v[42:43]
	v_pk_mul_f32 v[44:45], v[38:39], v[38:39]
	v_pk_mul_f32 v[48:49], v[36:37], v[36:37]
	v_mbcnt_lo_u32_b32 v62, -1, 0
	v_mbcnt_hi_u32_b32 v62, -1, v62
	v_mbcnt_lo_u32_b32 v63, -1, 0
	v_mbcnt_hi_u32_b32 v63, -1, v63
	v_mbcnt_lo_u32_b32 v64, -1, 0
	v_mbcnt_hi_u32_b32 v64, -1, v64
	v_mbcnt_lo_u32_b32 v65, -1, 0
	v_mbcnt_hi_u32_b32 v65, -1, v65
	v_mbcnt_lo_u32_b32 v66, -1, 0
	v_mbcnt_hi_u32_b32 v66, -1, v66
	v_mbcnt_lo_u32_b32 v67, -1, 0
	v_mbcnt_hi_u32_b32 v67, -1, v67
	global_load_dwordx4 v[36:39], v[42:43], off
	v_pk_mul_f32 v[56:57], v[14:15], v[14:15]
	v_pk_mul_f32 v[58:59], v[10:11], v[10:11]
	v_pk_mul_f32 v[52:53], v[16:17], v[16:17]
	v_pk_mul_f32 v[54:55], v[12:13], v[12:13]
	v_mov_b32_e32 v60, v56
	v_mov_b32_e32 v61, v58
	v_mov_b32_e32 v58, v57
	v_pk_add_f32 v[56:57], v[60:61], v[58:59]
	v_mov_b32_e32 v58, v52
	v_mov_b32_e32 v59, v54
	v_pk_mul_f32 v[50:51], v[6:7], v[6:7]
	v_pk_add_f32 v[56:57], v[58:59], v[56:57]
	v_mov_b32_e32 v54, v53
	v_pk_mul_f32 v[46:47], v[8:9], v[8:9]
	v_pk_add_f32 v[52:53], v[54:55], v[56:57]
	v_mov_b32_e32 v54, v48
	v_mov_b32_e32 v55, v50
	v_mov_b32_e32 v50, v49
	v_pk_add_f32 v[48:49], v[54:55], v[50:51]
	v_mov_b32_e32 v50, v44
	v_mov_b32_e32 v51, v46
	v_pk_add_f32 v[48:49], v[50:51], v[48:49]
	v_mov_b32_e32 v46, v45
	v_pk_add_f32 v[44:45], v[46:47], v[48:49]
	v_add_f32_e32 v46, v52, v53
	v_add_f32_e32 v45, v45, v46
	v_add_f32_e32 v44, v44, v45
	v_lshlrev_b32_e32 v45, 2, v62
	v_xor_b32_e32 v45, 0x80, v45
	v_mov_b32_e32 v45, v44
	s_nop 1
	v_permlane32_swap_b32_e32 v45, v44
	v_lshlrev_b32_e32 v46, 2, v67
	v_xor_b32_e32 v46, 4, v46
	s_cselect_b32 s9, s9, 0
	s_cselect_b32 s8, s0, s8
	s_waitcnt lgkmcnt(0)
	v_add_f32_e32 v44, v44, v45
	v_lshlrev_b32_e32 v45, 2, v63
	v_xor_b32_e32 v45, 64, v45
	v_mov_b32_e32 v45, v44
	s_nop 1
	v_permlane16_swap_b32_e32 v45, v44
	s_cselect_b32 s0, s49, s55
	s_cselect_b32 s10, s48, s54
	s_lshl_b64 s[8:9], s[8:9], 11
	s_add_u32 s8, s10, s8
	s_waitcnt lgkmcnt(0)
	v_add_f32_e32 v44, v44, v45
	v_lshlrev_b32_e32 v45, 2, v64
	v_xor_b32_e32 v45, 32, v45
	s_nop 1
	v_mov_b32_dpp v45, v44 row_ror:8 row_mask:0xf bank_mask:0xf
	s_addc_u32 s9, s0, s9
	v_lshl_add_u64 v[48:49], v[34:35], 1, s[8:9]
	v_readlane_b32 s57, v251, 7
	v_readlane_b32 s58, v251, 8
	s_waitcnt lgkmcnt(0)
	v_add_f32_e32 v44, v44, v45
	v_lshlrev_b32_e32 v45, 2, v65
	v_xor_b32_e32 v45, 16, v45
	s_nop 1
	v_mov_b32_dpp v45, v44 row_shl:4 row_mask:0xf bank_mask:0x5
	v_mov_b32_dpp v45, v44 row_shr:4 row_mask:0xf bank_mask:0xa
	v_readlane_b32 s59, v251, 9
	v_readlane_b32 s60, v251, 10
	v_readlane_b32 s61, v251, 11
	v_readlane_b32 s62, v251, 12
	s_waitcnt lgkmcnt(0)
	v_add_f32_e32 v44, v44, v45
	v_lshlrev_b32_e32 v45, 2, v66
	v_xor_b32_e32 v45, 8, v45
	s_nop 1
	v_mov_b32_dpp v45, v44 quad_perm:[2,3,0,1] row_mask:0xf bank_mask:0xf
	v_readlane_b32 s63, v251, 13
	v_readlane_b32 s64, v251, 14
	v_readlane_b32 s65, v251, 15
	v_readlane_b32 s66, v251, 16
	s_waitcnt lgkmcnt(0)
	v_add_f32_e32 v44, v44, v45
	ds_bpermute_b32 v45, v46, v44
	v_readlane_b32 s67, v251, 17
	v_readlane_b32 s68, v251, 18
	v_readlane_b32 s69, v251, 19
	v_readlane_b32 s56, v251, 38
	s_waitcnt lgkmcnt(0)
	v_add_f32_e32 v44, v44, v45
	v_fmamk_f32 v44, v44, 0x3a800000, v41
	v_mul_f32_e32 v45, 0x4b800000, v44
	v_cmp_gt_f32_e32 vcc, s30, v44
	s_mov_b32 s18, s28
	v_readlane_b32 s57, v251, 39
	v_cndmask_b32_e32 v44, v44, v45, vcc
	v_rsq_f32_e32 v44, v44
	v_readlane_b32 s62, v251, 44
	v_readlane_b32 s63, v251, 45
	v_readlane_b32 s13, v251, 23
	v_mul_f32_e32 v45, 0x45800000, v44
	v_cndmask_b32_e32 v46, v44, v45, vcc
	v_pk_mul_f32 v[14:15], v[14:15], v[46:47] op_sel_hi:[1,0]
	v_pk_mul_f32 v[16:17], v[16:17], v[46:47] op_sel_hi:[1,0]
	s_waitcnt vmcnt(0)
	v_pk_mul_f32 v[14:15], v[36:37], v[14:15]
	v_pk_mul_f32 v[16:17], v[38:39], v[16:17]
	v_cvt_pk_bf16_f32 v14, v14, v15
	v_cvt_pk_bf16_f32 v15, v16, v17
	global_store_dwordx2 v[48:49], v[14:15], off
	global_load_dwordx4 v[14:17], v[42:43], off offset:1024
	v_pk_mul_f32 v[10:11], v[10:11], v[46:47] op_sel_hi:[1,0]
	v_pk_mul_f32 v[12:13], v[12:13], v[46:47] op_sel_hi:[1,0]
	v_pk_mul_f32 v[6:7], v[6:7], v[46:47] op_sel_hi:[1,0]
	v_pk_mul_f32 v[8:9], v[8:9], v[46:47] op_sel_hi:[1,0]
	v_pk_mul_f32 v[50:51], v[2:3], v[46:47] op_sel_hi:[1,0]
	v_pk_mul_f32 v[46:47], v[4:5], v[46:47] op_sel_hi:[1,0]
	v_mov_b64_e32 v[2:3], v[18:19]
	v_mov_b32_e32 v36, v18
	v_mov_b32_e32 v37, v19
	v_mov_b32_e32 v38, v20
	s_andn2_b64 vcc, exec, s[2:3]
	v_mov_b64_e32 v[4:5], v[20:21]
	v_mov_b32_e32 v39, v21
	v_readlane_b32 s14, v251, 24
	v_readlane_b32 s15, v251, 25
	v_readlane_b32 s16, v251, 26
	v_readlane_b32 s17, v251, 27
	v_readlane_b32 s20, v251, 30
	v_readlane_b32 s21, v251, 31
	v_readlane_b32 s22, v251, 32
	v_readlane_b32 s23, v251, 33
	v_readlane_b32 s24, v251, 34
	v_readlane_b32 s25, v251, 35
	v_readlane_b32 s26, v251, 36
	v_readlane_b32 s27, v251, 37
	v_readlane_b32 s58, v251, 40
	v_readlane_b32 s59, v251, 41
	v_readlane_b32 s60, v251, 42
	v_readlane_b32 s61, v251, 43
	v_readlane_b32 s64, v251, 46
	v_readlane_b32 s65, v251, 47
	v_readlane_b32 s66, v251, 48
	v_readlane_b32 s67, v251, 49
	v_readlane_b32 s68, v251, 50
	v_readlane_b32 s69, v251, 51
	v_readlane_b32 s70, v251, 52
	v_readlane_b32 s71, v251, 53
	s_waitcnt vmcnt(0)
	v_pk_mul_f32 v[12:13], v[16:17], v[12:13]
	v_pk_mul_f32 v[10:11], v[14:15], v[10:11]
	v_mov_b32_e32 v14, v22
	v_cvt_pk_bf16_f32 v10, v10, v11
	v_cvt_pk_bf16_f32 v11, v12, v13
	global_store_dwordx2 v[48:49], v[10:11], off offset:512
	global_load_dwordx4 v[10:13], v[42:43], off offset:2048
	v_mov_b32_e32 v15, v23
	v_mov_b32_e32 v16, v24
	v_mov_b32_e32 v17, v25
	s_waitcnt vmcnt(0)
	v_pk_mul_f32 v[8:9], v[12:13], v[8:9]
	v_pk_mul_f32 v[6:7], v[10:11], v[6:7]
	v_mov_b32_e32 v10, v26
	v_cvt_pk_bf16_f32 v6, v6, v7
	v_cvt_pk_bf16_f32 v7, v8, v9
	global_store_dwordx2 v[48:49], v[6:7], off offset:1024
	global_load_dwordx4 v[42:45], v[42:43], off offset:3072
	v_mov_b32_e32 v11, v27
	v_mov_b32_e32 v12, v28
	v_mov_b32_e32 v13, v29
	v_mov_b32_e32 v6, v30
	v_mov_b32_e32 v7, v31
	v_mov_b32_e32 v8, v32
	v_mov_b32_e32 v9, v33
	s_waitcnt vmcnt(0)
	v_pk_mul_f32 v[22:23], v[44:45], v[46:47]
	v_pk_mul_f32 v[24:25], v[42:43], v[50:51]
	s_nop 0
	v_cvt_pk_bf16_f32 v24, v24, v25
	v_cvt_pk_bf16_f32 v25, v22, v23
	global_store_dwordx2 v[48:49], v[24:25], off offset:1536
	s_cbranch_vccz .LBB0_109

; __device__ __forceinline__ void attn_sample_item(const Params& p, int item, const int wv) {
;     ...
;   __syncthreads();
;   float pv[4];
;   {
;     float mx = -1e30f;
; #pragma unroll
;     for (int i = 0; i < 4; ++i) { pv[i] = sc_l[lane + 64 * i]; mx = fmaxf(mx, pv[i]); }
;     mx = wave_max(mx);
;     float sum = 0.f;
; #pragma unroll
;     for (int i = 0; i < 4; ++i) { pv[i] = __expf(pv[i] - mx); sum += pv[i]; }
;     sum = wave_sum(sum);
;     const float inv = 1.f / sum;
; #pragma unroll
;     for (int i = 0; i < 4; ++i) pv[i] *= inv;
;   }
;   __syncthreads();
;   if (wid == 0) {
; #pragma unroll
;     for (int i = 0; i < 4; ++i) sc_l[lane + 64 * i] = pv[i];
;   }
.LBB0_480:
	s_or_b64 exec, exec, s[10:11]
	v_lshl_add_u32 v68, v72, 2, 16
	s_waitcnt lgkmcnt(0)
	s_barrier
	ds_read2st64_b32 v[70:71], v68 offset1:1
	ds_read2st64_b32 v[72:73], v68 offset0:2 offset1:3
	v_mbcnt_lo_u32_b32 v74, -1, 0
	v_mbcnt_hi_u32_b32 v74, -1, v74
	v_mbcnt_lo_u32_b32 v75, -1, 0
	v_mbcnt_hi_u32_b32 v75, -1, v75
	v_readlane_b32 s10, v251, 58
	s_waitcnt lgkmcnt(1)
	v_max3_f32 v69, v70, s17, v71
	v_lshlrev_b32_e32 v74, 2, v74
	s_waitcnt lgkmcnt(0)
	v_max3_f32 v69, v69, v72, v73
	v_xor_b32_e32 v74, 0x80, v74
	ds_bpermute_b32 v74, v74, v69
	v_readlane_b32 s11, v251, 59
	s_and_b64 vcc, exec, s[10:11]
	s_waitcnt lgkmcnt(0)
	v_max_f32_e32 v74, v74, v74
	v_max_f32_e32 v69, v69, v74
	v_lshlrev_b32_e32 v74, 2, v75
	v_xor_b32_e32 v74, 64, v74
	ds_bpermute_b32 v74, v74, v69
	v_mbcnt_lo_u32_b32 v75, -1, 0
	v_mbcnt_hi_u32_b32 v75, -1, v75
	s_waitcnt lgkmcnt(0)
	v_max_f32_e32 v74, v74, v74
	v_lshlrev_b32_e32 v75, 2, v75
	v_max_f32_e32 v69, v69, v74
	v_xor_b32_e32 v74, 32, v75
	s_nop 1
	v_mov_b32_dpp v74, v69 row_ror:8 row_mask:0xf bank_mask:0xf
	v_mbcnt_lo_u32_b32 v75, -1, 0
	v_mbcnt_hi_u32_b32 v75, -1, v75
	s_waitcnt lgkmcnt(0)
	v_max_f32_e32 v74, v74, v74
	v_lshlrev_b32_e32 v75, 2, v75
	v_xor_b32_e32 v75, 16, v75
	v_max_f32_e32 v69, v69, v74
	s_nop 1
	v_mov_b32_dpp v74, v69 row_shl:4 row_mask:0xf bank_mask:0x5
	v_mov_b32_dpp v74, v69 row_shr:4 row_mask:0xf bank_mask:0xa
	v_mbcnt_lo_u32_b32 v75, -1, 0
	v_mbcnt_hi_u32_b32 v75, -1, v75
	s_waitcnt lgkmcnt(0)
	v_max_f32_e32 v74, v74, v74
	v_lshlrev_b32_e32 v75, 2, v75
	v_xor_b32_e32 v75, 8, v75
	v_max_f32_e32 v69, v69, v74
	s_nop 1
	v_mov_b32_dpp v74, v69 quad_perm:[2,3,0,1] row_mask:0xf bank_mask:0xf
	v_mbcnt_lo_u32_b32 v75, -1, 0
	v_mbcnt_hi_u32_b32 v75, -1, v75
	s_waitcnt lgkmcnt(0)
	v_max_f32_e32 v74, v74, v74
	v_lshlrev_b32_e32 v75, 2, v75
	v_xor_b32_e32 v75, 4, v75
	v_max_f32_e32 v69, v69, v74
	s_nop 1
	v_mov_b32_dpp v74, v69 quad_perm:[1,0,3,2] row_mask:0xf bank_mask:0xf
	s_waitcnt lgkmcnt(0)
	v_max_f32_e32 v74, v74, v74
	v_max_f32_e32 v69, v69, v74
	v_sub_f32_e32 v70, v70, v69
	v_sub_f32_e32 v71, v71, v69
	v_sub_f32_e32 v72, v72, v69
	v_sub_f32_e32 v69, v73, v69
	v_mul_f32_e32 v70, 0x3fb8aa3b, v70
	v_mul_f32_e32 v71, 0x3fb8aa3b, v71
	v_mul_f32_e32 v73, 0x3fb8aa3b, v69
	v_exp_f32_e32 v69, v70
	v_mul_f32_e32 v72, 0x3fb8aa3b, v72
	v_exp_f32_e32 v70, v71
	v_exp_f32_e32 v71, v72
	v_exp_f32_e32 v72, v73
	v_add_f32_e32 v73, 0, v69
	v_add_f32_e32 v73, v70, v73
	v_mbcnt_lo_u32_b32 v74, -1, 0
	v_mbcnt_hi_u32_b32 v74, -1, v74
	v_add_f32_e32 v73, v71, v73
	v_lshlrev_b32_e32 v74, 2, v74
	v_add_f32_e32 v73, v72, v73
	v_xor_b32_e32 v74, 0x80, v74
	v_mov_b32_e32 v74, v73
	s_nop 1
	v_permlane32_swap_b32_e32 v74, v73
	v_mbcnt_lo_u32_b32 v75, -1, 0
	v_mbcnt_hi_u32_b32 v75, -1, v75
	s_waitcnt lgkmcnt(0)
	v_add_f32_e32 v73, v73, v74
	v_lshlrev_b32_e32 v74, 2, v75
	v_xor_b32_e32 v74, 64, v74
	v_mov_b32_e32 v74, v73
	s_nop 1
	v_permlane16_swap_b32_e32 v74, v73
	v_mbcnt_lo_u32_b32 v75, -1, 0
	v_mbcnt_hi_u32_b32 v75, -1, v75
	s_waitcnt lgkmcnt(0)
	v_add_f32_e32 v73, v73, v74
	v_lshlrev_b32_e32 v75, 2, v75
	v_xor_b32_e32 v74, 32, v75
	s_nop 1
	v_mov_b32_dpp v74, v73 row_ror:8 row_mask:0xf bank_mask:0xf
	v_mbcnt_lo_u32_b32 v75, -1, 0
	v_mbcnt_hi_u32_b32 v75, -1, v75
	s_waitcnt lgkmcnt(0)
	v_add_f32_e32 v73, v73, v74
	v_lshlrev_b32_e32 v75, 2, v75
	v_xor_b32_e32 v75, 16, v75
	s_nop 1
	v_mov_b32_dpp v74, v73 row_shl:4 row_mask:0xf bank_mask:0x5
	v_mov_b32_dpp v74, v73 row_shr:4 row_mask:0xf bank_mask:0xa
	v_mbcnt_lo_u32_b32 v75, -1, 0
	v_mbcnt_hi_u32_b32 v75, -1, v75
	s_waitcnt lgkmcnt(0)
	v_add_f32_e32 v73, v73, v74
	v_lshlrev_b32_e32 v75, 2, v75
	v_xor_b32_e32 v75, 8, v75
	s_nop 1
	v_mov_b32_dpp v74, v73 quad_perm:[2,3,0,1] row_mask:0xf bank_mask:0xf
	v_mbcnt_lo_u32_b32 v75, -1, 0
	v_mbcnt_hi_u32_b32 v75, -1, v75
	s_waitcnt lgkmcnt(0)
	v_lshlrev_b32_e32 v75, 2, v75
	s_barrier
	v_add_f32_e32 v73, v73, v74
	v_xor_b32_e32 v74, 4, v75
	s_nop 1
	v_mov_b32_dpp v74, v73 quad_perm:[1,0,3,2] row_mask:0xf bank_mask:0xf
	s_waitcnt lgkmcnt(0)
	s_cbranch_vccnz .LBB0_482
	v_add_f32_e32 v73, v73, v74
	v_div_scale_f32 v74, s[10:11], v73, v73, 1.0
	v_rcp_f32_e32 v75, v74
	v_div_scale_f32 v76, vcc, 1.0, v73, 1.0
	v_fma_f32 v77, -v74, v75, 1.0
	v_fmac_f32_e32 v75, v77, v75
	v_mul_f32_e32 v77, v76, v75
	v_fma_f32 v78, -v74, v77, v76
	v_fmac_f32_e32 v77, v78, v75
	v_fma_f32 v74, -v74, v77, v76
	v_div_fmas_f32 v74, v74, v75, v77
	v_div_fixup_f32 v73, v74, v73, 1.0
	v_mul_f32_e32 v70, v70, v73
	v_mul_f32_e32 v69, v69, v73
	v_mul_f32_e32 v72, v72, v73
	v_mul_f32_e32 v71, v71, v73
	ds_write2st64_b32 v68, v69, v70 offset1:1
	ds_write2st64_b32 v68, v71, v72 offset0:2 offset1:3

; __device__ __forceinline__ void attn_sample_item(const Params& p, int item, const int wv) {
;     ...
;   __syncthreads();
;   float pv[4];
;   {
;     float mx = -1e30f;
; #pragma unroll
;     for (int i = 0; i < 4; ++i) { pv[i] = sc_l[lane + 64 * i]; mx = fmaxf(mx, pv[i]); }
;     mx = wave_max(mx);
;     float sum = 0.f;
; #pragma unroll
;     for (int i = 0; i < 4; ++i) { pv[i] = __expf(pv[i] - mx); sum += pv[i]; }
;     sum = wave_sum(sum);
;     const float inv = 1.f / sum;
; #pragma unroll
;     for (int i = 0; i < 4; ++i) pv[i] *= inv;
;   }
;   __syncthreads();
;   if (wid == 0) {
; #pragma unroll
;     for (int i = 0; i < 4; ++i) sc_l[lane + 64 * i] = pv[i];
;   }
.LBB0_506:
	s_or_b64 exec, exec, s[8:9]
	v_lshl_add_u32 v68, v72, 2, 16
	s_waitcnt lgkmcnt(0)
	s_barrier
	ds_read2st64_b32 v[70:71], v68 offset1:1
	ds_read2st64_b32 v[72:73], v68 offset0:2 offset1:3
	v_mbcnt_lo_u32_b32 v74, -1, 0
	v_mbcnt_hi_u32_b32 v74, -1, v74
	v_mbcnt_lo_u32_b32 v75, -1, 0
	v_mbcnt_hi_u32_b32 v75, -1, v75
	v_readlane_b32 s8, v251, 58
	s_waitcnt lgkmcnt(1)
	v_max3_f32 v69, v70, s16, v71
	v_lshlrev_b32_e32 v74, 2, v74
	s_waitcnt lgkmcnt(0)
	v_max3_f32 v69, v69, v72, v73
	v_xor_b32_e32 v74, 0x80, v74
	ds_bpermute_b32 v74, v74, v69
	v_readlane_b32 s9, v251, 59
	s_and_b64 vcc, exec, s[8:9]
	s_waitcnt lgkmcnt(0)
	v_max_f32_e32 v74, v74, v74
	v_max_f32_e32 v69, v69, v74
	v_lshlrev_b32_e32 v74, 2, v75
	v_xor_b32_e32 v74, 64, v74
	ds_bpermute_b32 v74, v74, v69
	v_mbcnt_lo_u32_b32 v75, -1, 0
	v_mbcnt_hi_u32_b32 v75, -1, v75
	s_waitcnt lgkmcnt(0)
	v_max_f32_e32 v74, v74, v74
	v_lshlrev_b32_e32 v75, 2, v75
	v_max_f32_e32 v69, v69, v74
	v_xor_b32_e32 v74, 32, v75
	s_nop 1
	v_mov_b32_dpp v74, v69 row_ror:8 row_mask:0xf bank_mask:0xf
	v_mbcnt_lo_u32_b32 v75, -1, 0
	v_mbcnt_hi_u32_b32 v75, -1, v75
	s_waitcnt lgkmcnt(0)
	v_max_f32_e32 v74, v74, v74
	v_lshlrev_b32_e32 v75, 2, v75
	v_xor_b32_e32 v75, 16, v75
	v_max_f32_e32 v69, v69, v74
	s_nop 1
	v_mov_b32_dpp v74, v69 row_shl:4 row_mask:0xf bank_mask:0x5
	v_mov_b32_dpp v74, v69 row_shr:4 row_mask:0xf bank_mask:0xa
	v_mbcnt_lo_u32_b32 v75, -1, 0
	v_mbcnt_hi_u32_b32 v75, -1, v75
	s_waitcnt lgkmcnt(0)
	v_max_f32_e32 v74, v74, v74
	v_lshlrev_b32_e32 v75, 2, v75
	v_xor_b32_e32 v75, 8, v75
	v_max_f32_e32 v69, v69, v74
	s_nop 1
	v_mov_b32_dpp v74, v69 quad_perm:[2,3,0,1] row_mask:0xf bank_mask:0xf
	v_mbcnt_lo_u32_b32 v75, -1, 0
	v_mbcnt_hi_u32_b32 v75, -1, v75
	s_waitcnt lgkmcnt(0)
	v_max_f32_e32 v74, v74, v74
	v_lshlrev_b32_e32 v75, 2, v75
	v_xor_b32_e32 v75, 4, v75
	v_max_f32_e32 v69, v69, v74
	s_nop 1
	v_mov_b32_dpp v74, v69 quad_perm:[1,0,3,2] row_mask:0xf bank_mask:0xf
	s_waitcnt lgkmcnt(0)
	v_max_f32_e32 v74, v74, v74
	v_max_f32_e32 v69, v69, v74
	v_sub_f32_e32 v70, v70, v69
	v_sub_f32_e32 v71, v71, v69
	v_sub_f32_e32 v72, v72, v69
	v_sub_f32_e32 v69, v73, v69
	v_mul_f32_e32 v70, 0x3fb8aa3b, v70
	v_mul_f32_e32 v71, 0x3fb8aa3b, v71
	v_mul_f32_e32 v73, 0x3fb8aa3b, v69
	v_exp_f32_e32 v69, v70
	v_mul_f32_e32 v72, 0x3fb8aa3b, v72
	v_exp_f32_e32 v70, v71
	v_exp_f32_e32 v71, v72
	v_exp_f32_e32 v72, v73
	v_add_f32_e32 v73, 0, v69
	v_add_f32_e32 v73, v70, v73
	v_mbcnt_lo_u32_b32 v74, -1, 0
	v_mbcnt_hi_u32_b32 v74, -1, v74
	v_add_f32_e32 v73, v71, v73
	v_lshlrev_b32_e32 v74, 2, v74
	v_add_f32_e32 v73, v72, v73
	v_xor_b32_e32 v74, 0x80, v74
	v_mov_b32_e32 v74, v73
	s_nop 1
	v_permlane32_swap_b32_e32 v74, v73
	v_mbcnt_lo_u32_b32 v75, -1, 0
	v_mbcnt_hi_u32_b32 v75, -1, v75
	s_waitcnt lgkmcnt(0)
	v_add_f32_e32 v73, v73, v74
	v_lshlrev_b32_e32 v74, 2, v75
	v_xor_b32_e32 v74, 64, v74
	v_mov_b32_e32 v74, v73
	s_nop 1
	v_permlane16_swap_b32_e32 v74, v73
	v_mbcnt_lo_u32_b32 v75, -1, 0
	v_mbcnt_hi_u32_b32 v75, -1, v75
	s_waitcnt lgkmcnt(0)
	v_add_f32_e32 v73, v73, v74
	v_lshlrev_b32_e32 v75, 2, v75
	v_xor_b32_e32 v74, 32, v75
	s_nop 1
	v_mov_b32_dpp v74, v73 row_ror:8 row_mask:0xf bank_mask:0xf
	v_mbcnt_lo_u32_b32 v75, -1, 0
	v_mbcnt_hi_u32_b32 v75, -1, v75
	s_waitcnt lgkmcnt(0)
	v_add_f32_e32 v73, v73, v74
	v_lshlrev_b32_e32 v75, 2, v75
	v_xor_b32_e32 v75, 16, v75
	s_nop 1
	v_mov_b32_dpp v74, v73 row_shl:4 row_mask:0xf bank_mask:0x5
	v_mov_b32_dpp v74, v73 row_shr:4 row_mask:0xf bank_mask:0xa
	v_mbcnt_lo_u32_b32 v75, -1, 0
	v_mbcnt_hi_u32_b32 v75, -1, v75
	s_waitcnt lgkmcnt(0)
	v_add_f32_e32 v73, v73, v74
	v_lshlrev_b32_e32 v75, 2, v75
	v_xor_b32_e32 v75, 8, v75
	s_nop 1
	v_mov_b32_dpp v74, v73 quad_perm:[2,3,0,1] row_mask:0xf bank_mask:0xf
	v_mbcnt_lo_u32_b32 v75, -1, 0
	v_mbcnt_hi_u32_b32 v75, -1, v75
	s_waitcnt lgkmcnt(0)
	v_lshlrev_b32_e32 v75, 2, v75
	s_barrier
	v_add_f32_e32 v73, v73, v74
	v_xor_b32_e32 v74, 4, v75
	s_nop 1
	v_mov_b32_dpp v74, v73 quad_perm:[1,0,3,2] row_mask:0xf bank_mask:0xf
	s_waitcnt lgkmcnt(0)
	s_cbranch_vccnz .LBB0_508
	v_add_f32_e32 v73, v73, v74
	v_div_scale_f32 v74, s[8:9], v73, v73, 1.0
	v_rcp_f32_e32 v75, v74
	v_div_scale_f32 v76, vcc, 1.0, v73, 1.0
	v_fma_f32 v77, -v74, v75, 1.0
	v_fmac_f32_e32 v75, v77, v75
	v_mul_f32_e32 v77, v76, v75
	v_fma_f32 v78, -v74, v77, v76
	v_fmac_f32_e32 v77, v78, v75
	v_fma_f32 v74, -v74, v77, v76
	v_div_fmas_f32 v74, v74, v75, v77
	v_div_fixup_f32 v73, v74, v73, 1.0
	v_mul_f32_e32 v70, v70, v73
	v_mul_f32_e32 v69, v69, v73
	v_mul_f32_e32 v72, v72, v73
	v_mul_f32_e32 v71, v71, v73
	ds_write2st64_b32 v68, v69, v70 offset1:1
	ds_write2st64_b32 v68, v71, v72 offset0:2 offset1:3

; __device__ __forceinline__ float shfl_xor_f(float v, int mask) { const int l = lane_fresh(); return __int_as_float(__builtin_amdgcn_ds_bpermute((l ^ mask) << 2, __float_as_int(v))); }
; __device__ __forceinline__ float wave_sum(float v) {
; #pragma unroll
;   for (int o = 32; o >= 1; o >>= 1) v += shfl_xor_f(v, o);
;   return v;
; }
; __device__ __forceinline__ float wave_max(float v) {
; #pragma unroll
;   for (int o = 32; o >= 1; o >>= 1) v = fmaxf(v, shfl_xor_f(v, o));
;   return v;
; }
; __device__ __forceinline__ void attn_sample_item(const Params& p, int item, const int wv) {
;     ...
;   float pv[4];
;   {
;     float mx = -1e30f;
; #pragma unroll
;     for (int i = 0; i < 4; ++i) { pv[i] = sc_l[lane + 64 * i]; mx = fmaxf(mx, pv[i]); }
;     mx = wave_max(mx);
;     float sum = 0.f;
; #pragma unroll
;     for (int i = 0; i < 4; ++i) { pv[i] = __expf(pv[i] - mx); sum += pv[i]; }
;     sum = wave_sum(sum);
;     const float inv = 1.f / sum;
; #pragma unroll
;     for (int i = 0; i < 4; ++i) pv[i] *= inv;
;   }
;   __syncthreads();
;   if (wid == 0) {
; #pragma unroll
;     for (int i = 0; i < 4; ++i) sc_l[lane + 64 * i] = pv[i];
;   }
;   __syncthreads();
.LBB0_528:
	s_or_b64 exec, exec, s[8:9]
	v_lshl_add_u32 v67, v72, 2, 16
	s_waitcnt lgkmcnt(0)
	s_barrier
	ds_read2st64_b32 v[68:69], v67 offset1:1
	ds_read2st64_b32 v[70:71], v67 offset0:2 offset1:3
	s_mov_b32 s7, 0xf149f2ca
	v_mbcnt_lo_u32_b32 v73, -1, 0
	v_mbcnt_hi_u32_b32 v73, -1, v73
	v_readlane_b32 s8, v251, 58
	s_waitcnt lgkmcnt(1)
	v_max3_f32 v72, v68, s7, v69
	v_lshlrev_b32_e32 v73, 2, v73
	s_waitcnt lgkmcnt(0)
	v_max3_f32 v72, v72, v70, v71
	v_xor_b32_e32 v73, 0x80, v73
	ds_bpermute_b32 v73, v73, v72
	v_readlane_b32 s9, v251, 59
	s_movk_i32 s7, 0x80
	s_and_b64 vcc, exec, s[8:9]
	s_waitcnt lgkmcnt(0)
	v_max_f32_e32 v73, v73, v73
	v_max_f32_e32 v72, v72, v73
	v_mbcnt_lo_u32_b32 v73, -1, 0
	v_mbcnt_hi_u32_b32 v73, -1, v73
	v_mbcnt_lo_u32_b32 v74, -1, 0
	v_mbcnt_hi_u32_b32 v74, -1, v74
	s_nop 0
	v_lshlrev_b32_e32 v73, 2, v73
	v_xor_b32_e32 v73, 64, v73
	ds_bpermute_b32 v73, v73, v72
	s_waitcnt lgkmcnt(0)
	v_max_f32_e32 v73, v73, v73
	v_max_f32_e32 v72, v72, v73
	v_lshlrev_b32_e32 v73, 2, v74
	v_xor_b32_e32 v73, 32, v73
	s_nop 1
	v_mov_b32_dpp v73, v72 row_ror:8 row_mask:0xf bank_mask:0xf
	v_mbcnt_lo_u32_b32 v74, -1, 0
	v_mbcnt_hi_u32_b32 v74, -1, v74
	s_waitcnt lgkmcnt(0)
	v_max_f32_e32 v73, v73, v73
	v_lshlrev_b32_e32 v74, 2, v74
	v_max_f32_e32 v72, v72, v73
	v_xor_b32_e32 v73, 16, v74
	s_nop 1
	v_mov_b32_dpp v73, v72 row_shl:4 row_mask:0xf bank_mask:0x5
	v_mov_b32_dpp v73, v72 row_shr:4 row_mask:0xf bank_mask:0xa
	v_mbcnt_lo_u32_b32 v74, -1, 0
	v_mbcnt_hi_u32_b32 v74, -1, v74
	s_waitcnt lgkmcnt(0)
	v_max_f32_e32 v73, v73, v73
	v_lshlrev_b32_e32 v74, 2, v74
	v_xor_b32_e32 v74, 8, v74
	v_max_f32_e32 v72, v72, v73
	s_nop 1
	v_mov_b32_dpp v73, v72 quad_perm:[2,3,0,1] row_mask:0xf bank_mask:0xf
	v_mbcnt_lo_u32_b32 v74, -1, 0
	v_mbcnt_hi_u32_b32 v74, -1, v74
	s_waitcnt lgkmcnt(0)
	v_max_f32_e32 v73, v73, v73
	v_lshlrev_b32_e32 v74, 2, v74
	v_xor_b32_e32 v74, 4, v74
	v_max_f32_e32 v72, v72, v73
	s_nop 1
	v_mov_b32_dpp v73, v72 quad_perm:[1,0,3,2] row_mask:0xf bank_mask:0xf
	s_waitcnt lgkmcnt(0)
	v_max_f32_e32 v73, v73, v73
	v_max_f32_e32 v72, v72, v73
	v_sub_f32_e32 v68, v68, v72
	v_sub_f32_e32 v69, v69, v72
	v_mul_f32_e32 v68, 0x3fb8aa3b, v68
	v_sub_f32_e32 v70, v70, v72
	v_mul_f32_e32 v69, 0x3fb8aa3b, v69
	v_exp_f32_e32 v68, v68
	v_mul_f32_e32 v70, 0x3fb8aa3b, v70
	v_exp_f32_e32 v69, v69
	v_sub_f32_e32 v71, v71, v72
	v_exp_f32_e32 v70, v70
	v_mul_f32_e32 v71, 0x3fb8aa3b, v71
	v_exp_f32_e32 v71, v71
	v_add_f32_e32 v72, 0, v68
	v_add_f32_e32 v72, v69, v72
	v_mbcnt_lo_u32_b32 v73, -1, 0
	v_mbcnt_hi_u32_b32 v73, -1, v73
	v_add_f32_e32 v72, v70, v72
	v_lshlrev_b32_e32 v73, 2, v73
	v_add_f32_e32 v72, v71, v72
	v_xor_b32_e32 v73, 0x80, v73
	v_mov_b32_e32 v73, v72
	s_nop 1
	v_permlane32_swap_b32_e32 v73, v72
	s_waitcnt lgkmcnt(0)
	v_add_f32_e32 v72, v72, v73
	v_mbcnt_lo_u32_b32 v73, -1, 0
	v_mbcnt_hi_u32_b32 v73, -1, v73
	v_mbcnt_lo_u32_b32 v74, -1, 0
	v_mbcnt_hi_u32_b32 v74, -1, v74
	s_nop 0
	v_lshlrev_b32_e32 v73, 2, v73
	v_xor_b32_e32 v73, 64, v73
	v_mov_b32_e32 v73, v72
	s_nop 1
	v_permlane16_swap_b32_e32 v73, v72
	s_waitcnt lgkmcnt(0)
	v_add_f32_e32 v72, v72, v73
	v_lshlrev_b32_e32 v73, 2, v74
	v_xor_b32_e32 v73, 32, v73
	s_nop 1
	v_mov_b32_dpp v73, v72 row_ror:8 row_mask:0xf bank_mask:0xf
	v_mbcnt_lo_u32_b32 v74, -1, 0
	v_mbcnt_hi_u32_b32 v74, -1, v74
	s_waitcnt lgkmcnt(0)
	v_add_f32_e32 v72, v72, v73
	v_lshlrev_b32_e32 v74, 2, v74
	v_xor_b32_e32 v73, 16, v74
	s_nop 1
	v_mov_b32_dpp v73, v72 row_shl:4 row_mask:0xf bank_mask:0x5
	v_mov_b32_dpp v73, v72 row_shr:4 row_mask:0xf bank_mask:0xa
	v_mbcnt_lo_u32_b32 v74, -1, 0
	v_mbcnt_hi_u32_b32 v74, -1, v74
	s_waitcnt lgkmcnt(0)
	v_add_f32_e32 v72, v72, v73
	v_lshlrev_b32_e32 v74, 2, v74
	v_xor_b32_e32 v74, 8, v74
	s_nop 1
	v_mov_b32_dpp v73, v72 quad_perm:[2,3,0,1] row_mask:0xf bank_mask:0xf
	v_mbcnt_lo_u32_b32 v74, -1, 0
	v_mbcnt_hi_u32_b32 v74, -1, v74
	s_waitcnt lgkmcnt(0)
	v_lshlrev_b32_e32 v74, 2, v74
	s_barrier
	v_add_f32_e32 v72, v72, v73
	v_xor_b32_e32 v73, 4, v74
	s_nop 1
	v_mov_b32_dpp v73, v72 quad_perm:[1,0,3,2] row_mask:0xf bank_mask:0xf
	s_waitcnt lgkmcnt(0)
	s_cbranch_vccnz .LBB0_530
	v_add_f32_e32 v72, v72, v73
	v_div_scale_f32 v73, s[8:9], v72, v72, 1.0
	v_rcp_f32_e32 v74, v73
	v_div_scale_f32 v75, vcc, 1.0, v72, 1.0
	v_fma_f32 v76, -v73, v74, 1.0
	v_fmac_f32_e32 v74, v76, v74
	v_mul_f32_e32 v76, v75, v74
	v_fma_f32 v77, -v73, v76, v75
	v_fmac_f32_e32 v76, v77, v74
	v_fma_f32 v73, -v73, v76, v75
	v_div_fmas_f32 v73, v73, v74, v76
	v_div_fixup_f32 v72, v73, v72, 1.0
	v_mul_f32_e32 v69, v69, v72
	v_mul_f32_e32 v68, v68, v72
	v_mul_f32_e32 v71, v71, v72
	v_mul_f32_e32 v70, v70, v72
	ds_write2st64_b32 v67, v68, v69 offset1:1
	ds_write2st64_b32 v67, v70, v71 offset0:2 offset1:3

; __device__ __forceinline__ unsigned xb_ld(unsigned* p) { return __hip_atomic_load(p, __ATOMIC_RELAXED, __HIP_MEMORY_SCOPE_AGENT); }
; #define XB_SPIN(cond, bar) do { unsigned _sp = 0; while (cond) { __builtin_amdgcn_s_sleep(1); \
;     if ((++_sp & 255u) == 0u) { if (xb_ld(&(bar)[XB_TMO])) break; if (_sp > XB_SPIN_CAP) { atomicAdd(&(bar)[XB_TMO], 1u); break; } } } } while (0)
; __device__ __forceinline__ void attn_prompt_item(const Params& p, int item, const int wv, unsigned* bar) {
;     ...
;   if (wv == 0) { if (lane == 0) { XB_SPIN(xb_ld(&bar[6144 + (b * 4 + h) * 16]) == 0u, bar); } }
;   __syncthreads();
;   __builtin_amdgcn_fence(__ATOMIC_ACQUIRE, "agent");
; #pragma unroll
;   for (int i = 0; i < 8; ++i) {
;     int idx = i * 512 + tid, mm = idx >> 4, ch = idx & 15;
;     *(u32x4*)(K_l + mm * 136 + ch * 8) = *(const u32x4*)(KP + (size_t)(b * 256 + mm) * 512 + h * 128 + ch * 8);
;   }
; #pragma unroll
;   for (int i = 0; i < 8; ++i) {
;     int idx = i * 512 + tid, d = idx >> 5, ch = idx & 31;
;     *(u32x4*)(VT_l + d * 264 + ch * 8) = *(const u32x4*)(VT + ((size_t)(b * 4 + h) * 128 + d) * 256 + ch * 8);
;   }
;   const int q0 = b * 2048 + qt * 256 + wid * 32;
;   bf16x8 qf[2][4];
; #pragma unroll
;   for (int qb = 0; qb < 2; ++qb)
; #pragma unroll
;     for (int ks = 0; ks < 4; ++ks) qf[qb][ks] = *(const bf16x8*)(Q + (size_t)(q0 + qb * 16 + fr) * 512 + h * 128 + ks * 32 + fq * 8);
.LBB0_535:
	s_or_b64 exec, exec, s[12:13]
	v_add_u32_e32 v6, s82, v161
	s_and_b32 s13, s34, 0xff
	s_lshl_b32 s16, s35, 8
	s_lshl_b32 s17, s10, 7
	s_lshl_b32 s12, s10, 8
	v_ashrrev_i32_e32 v36, 4, v6
	v_add_u32_e32 v28, 0x200, v6
	s_add_u32 s14, s24, s12
	v_lshlrev_b32_e32 v7, 4, v161
	v_add_u32_e32 v2, s16, v36
	v_ashrrev_i32_e32 v38, 4, v28
	s_addc_u32 s15, s25, 0
	v_and_b32_e32 v152, 0xf0, v7
	v_ashrrev_i32_e32 v3, 31, v2
	v_add_u32_e32 v4, s16, v38
	s_waitcnt lgkmcnt(0)
	v_lshl_add_u64 v[0:1], s[14:15], 0, v[152:153]
	v_lshlrev_b64 v[2:3], 10, v[2:3]
	v_ashrrev_i32_e32 v5, 31, v4
	v_add_u32_e32 v29, 0x400, v6
	v_lshl_add_u64 v[2:3], v[0:1], 0, v[2:3]
	v_lshlrev_b64 v[4:5], 10, v[4:5]
	v_ashrrev_i32_e32 v39, 4, v29
	v_add_u32_e32 v30, 0x600, v6
	s_barrier
	s_waitcnt vmcnt(0)
	buffer_inv sc1
	v_lshl_add_u64 v[4:5], v[0:1], 0, v[4:5]
	global_load_dwordx4 v[8:11], v[2:3], off
	global_load_dwordx4 v[12:15], v[4:5], off
	v_add_u32_e32 v2, s16, v39
	v_ashrrev_i32_e32 v84, 4, v30
	v_ashrrev_i32_e32 v3, 31, v2
	v_add_u32_e32 v4, s16, v84
	v_lshlrev_b64 v[2:3], 10, v[2:3]
	v_ashrrev_i32_e32 v5, 31, v4
	v_lshl_add_u64 v[2:3], v[0:1], 0, v[2:3]
	v_lshlrev_b64 v[4:5], 10, v[4:5]
	v_lshl_add_u64 v[4:5], v[0:1], 0, v[4:5]
	global_load_dwordx4 v[16:19], v[2:3], off
	global_load_dwordx4 v[20:23], v[4:5], off
	v_add_u32_e32 v31, 0x800, v6
	v_ashrrev_i32_e32 v85, 4, v31
	v_add_u32_e32 v37, 0xa00, v6
	v_add_u32_e32 v2, s16, v85
	v_ashrrev_i32_e32 v89, 4, v37
	v_ashrrev_i32_e32 v3, 31, v2
	v_add_u32_e32 v4, s16, v89
	v_lshlrev_b64 v[2:3], 10, v[2:3]
	v_ashrrev_i32_e32 v5, 31, v4
	v_add_u32_e32 v48, 0xc00, v6
	v_lshl_add_u64 v[2:3], v[0:1], 0, v[2:3]
	v_lshlrev_b64 v[4:5], 10, v[4:5]
	v_ashrrev_i32_e32 v110, 4, v48
	v_add_u32_e32 v49, 0xe00, v6
	v_lshl_add_u64 v[4:5], v[0:1], 0, v[4:5]
	global_load_dwordx4 v[24:27], v[2:3], off
	global_load_dwordx4 v[32:35], v[4:5], off
	v_add_u32_e32 v2, s16, v110
	v_ashrrev_i32_e32 v111, 4, v49
	v_ashrrev_i32_e32 v3, 31, v2
	v_add_u32_e32 v4, s16, v111
	v_lshlrev_b64 v[2:3], 10, v[2:3]
	v_ashrrev_i32_e32 v5, 31, v4
	s_lshl_b32 s10, s35, 9
	v_ashrrev_i32_e32 v90, 5, v6
	v_lshl_add_u64 v[2:3], v[0:1], 0, v[2:3]
	v_lshlrev_b64 v[4:5], 10, v[4:5]
	s_or_b32 s10, s17, s10
	v_ashrrev_i32_e32 v91, 31, v90
	v_ashrrev_i32_e32 v96, 5, v28
	v_add_u32_e32 v88, 16, v152
	v_lshl_add_u64 v[0:1], v[0:1], 0, v[4:5]
	global_load_dwordx4 v[40:43], v[2:3], off
	global_load_dwordx4 v[44:47], v[0:1], off
	v_and_b32_e32 v152, 0x1f0, v7
	v_lshl_add_u64 v[2:3], s[10:11], 0, v[90:91]
	v_ashrrev_i32_e32 v97, 31, v96
	v_lshl_add_u64 v[0:1], s[8:9], 0, v[152:153]
	v_lshlrev_b64 v[2:3], 9, v[2:3]
	v_lshl_add_u64 v[4:5], v[96:97], 0, s[10:11]
	v_ashrrev_i32_e32 v98, 5, v29
	v_lshl_add_u64 v[2:3], v[0:1], 0, v[2:3]
	v_lshlrev_b64 v[4:5], 9, v[4:5]
	v_ashrrev_i32_e32 v99, 31, v98
	v_ashrrev_i32_e32 v100, 5, v30
	v_lshl_add_u64 v[4:5], v[0:1], 0, v[4:5]
	global_load_dwordx4 v[52:55], v[2:3], off
	global_load_dwordx4 v[56:59], v[4:5], off
	v_lshl_add_u64 v[2:3], v[98:99], 0, s[10:11]
	v_ashrrev_i32_e32 v101, 31, v100
	v_lshlrev_b64 v[2:3], 9, v[2:3]
	v_lshl_add_u64 v[4:5], v[100:101], 0, s[10:11]
	v_ashrrev_i32_e32 v102, 5, v31
	v_lshl_add_u64 v[2:3], v[0:1], 0, v[2:3]
	v_lshlrev_b64 v[4:5], 9, v[4:5]
	v_ashrrev_i32_e32 v103, 31, v102
	v_ashrrev_i32_e32 v104, 5, v37
	v_lshl_add_u64 v[4:5], v[0:1], 0, v[4:5]
	global_load_dwordx4 v[60:63], v[2:3], off
	global_load_dwordx4 v[64:67], v[4:5], off
	v_lshl_add_u64 v[2:3], v[102:103], 0, s[10:11]
	v_ashrrev_i32_e32 v105, 31, v104
	v_lshlrev_b64 v[2:3], 9, v[2:3]
	v_lshl_add_u64 v[4:5], v[104:105], 0, s[10:11]
	v_ashrrev_i32_e32 v106, 5, v48
	v_lshl_add_u64 v[2:3], v[0:1], 0, v[2:3]
	v_lshlrev_b64 v[4:5], 9, v[4:5]
	v_ashrrev_i32_e32 v107, 31, v106
	v_lshl_add_u64 v[4:5], v[0:1], 0, v[4:5]
	global_load_dwordx4 v[68:71], v[2:3], off
	global_load_dwordx4 v[72:75], v[4:5], off
	v_lshl_add_u64 v[2:3], v[106:107], 0, s[10:11]
	v_lshlrev_b64 v[2:3], 9, v[2:3]
	v_ashrrev_i32_e32 v108, 5, v49
	v_lshl_add_u64 v[2:3], v[0:1], 0, v[2:3]
	v_ashrrev_i32_e32 v109, 31, v108
	global_load_dwordx4 v[76:79], v[2:3], off
	v_lshl_add_u64 v[2:3], v[108:109], 0, s[10:11]
	v_lshlrev_b64 v[2:3], 9, v[2:3]
	v_lshl_add_u64 v[0:1], v[0:1], 0, v[2:3]
	s_lshl_b32 s13, s13, 8
	v_and_b32_e32 v163, 15, v161
	global_load_dwordx4 v[80:83], v[0:1], off
	s_lshl_b32 s10, s35, 11
	s_and_b32 s13, s13, 0x700
	v_ashrrev_i32_e32 v162, 4, v161
	v_or_b32_e32 v0, s7, v163
	s_or_b32 s10, s10, s13
	v_add_u32_e32 v4, s10, v0
	s_add_u32 s14, s22, s12
	v_lshlrev_b32_e32 v0, 3, v162
	s_addc_u32 s15, s23, 0
	v_ashrrev_i32_e32 v1, 31, v0
	v_ashrrev_i32_e32 v5, 31, v4
	v_lshl_add_u64 v[6:7], v[0:1], 1, s[14:15]
	v_lshlrev_b64 v[156:157], 10, v[4:5]
	v_or_b32_e32 v4, 16, v4
	v_lshl_add_u64 v[48:49], v[6:7], 0, v[156:157]
	v_ashrrev_i32_e32 v5, 31, v4
	global_load_dwordx4 v[0:3], v[48:49], off
	v_lshlrev_b64 v[154:155], 10, v[4:5]
	v_lshl_add_u64 v[50:51], v[6:7], 0, v[154:155]
	global_load_dwordx4 v[92:95], v[50:51], off
	global_load_dwordx4 v[4:7], v[48:49], off offset:64
	global_load_dwordx4 v[28:31], v[50:51], off offset:64
	v_mad_u64_u32 v[36:37], s[14:15], v36, s28, v[88:89]
	s_waitcnt vmcnt(19)
	ds_write_b128 v36, v[8:11]
	v_mad_u64_u32 v[8:9], s[14:15], v38, s28, v[88:89]
	s_waitcnt vmcnt(18)
	ds_write_b128 v8, v[12:15]
	v_mad_u64_u32 v[8:9], s[14:15], v39, s28, v[88:89]
	global_load_dwordx4 v[36:39], v[50:51], off offset:128
	s_waitcnt vmcnt(18)
	ds_write_b128 v8, v[16:19]
	v_mad_u64_u32 v[8:9], s[14:15], v84, s28, v[88:89]
	global_load_dwordx4 v[16:19], v[48:49], off offset:128
	s_waitcnt vmcnt(18)
; #define MFMA16(a, b, c) __builtin_amdgcn_mfma_f32_16x16x32_bf16((a), (b), (c), 0, 0, 0)
; __device__ __forceinline__ void attn_prompt_item(const Params& p, int item, const int wv, unsigned* bar) {
;     ...
; #pragma unroll
;   for (int i = 0; i < 8; ++i) {
;     int idx = i * 512 + tid, mm = idx >> 4, ch = idx & 15;
;     *(u32x4*)(K_l + mm * 136 + ch * 8) = *(const u32x4*)(KP + (size_t)(b * 256 + mm) * 512 + h * 128 + ch * 8);
;   }
; #pragma unroll
;   for (int i = 0; i < 8; ++i) {
;     int idx = i * 512 + tid, d = idx >> 5, ch = idx & 31;
;     *(u32x4*)(VT_l + d * 264 + ch * 8) = *(const u32x4*)(VT + ((size_t)(b * 4 + h) * 128 + d) * 256 + ch * 8);
;   }
;   const int q0 = b * 2048 + qt * 256 + wid * 32;
;   bf16x8 qf[2][4];
; #pragma unroll
;   for (int qb = 0; qb < 2; ++qb)
; #pragma unroll
;     for (int ks = 0; ks < 4; ++ks) qf[qb][ks] = *(const bf16x8*)(Q + (size_t)(q0 + qb * 16 + fr) * 512 + h * 128 + ks * 32 + fq * 8);
;   __syncthreads();
;   f32x4 s[16][2];
; #pragma unroll
;   for (int mb = 0; mb < 16; ++mb) {
;     s[mb][0] = (f32x4){0.f, 0.f, 0.f, 0.f}; s[mb][1] = (f32x4){0.f, 0.f, 0.f, 0.f};
; #pragma unroll
;     for (int ks = 0; ks < 4; ++ks) {
;       bf16x8 kf = *(const bf16x8*)(K_l + (mb * 16 + fr) * 136 + ks * 32 + fq * 8);
;       s[mb][0] = MFMA16(kf, qf[0][ks], s[mb][0]);
;       s[mb][1] = MFMA16(kf, qf[1][ks], s[mb][1]);
;     }
;   }
	ds_write_b128 v8, v[20:23]
	v_mad_u64_u32 v[8:9], s[14:15], v85, s28, v[88:89]
	global_load_dwordx4 v[84:87], v[48:49], off offset:192
	s_waitcnt vmcnt(18)
	ds_write_b128 v8, v[24:27]
	global_load_dwordx4 v[48:51], v[50:51], off offset:192
	v_mad_u64_u32 v[8:9], s[14:15], v89, s28, v[88:89]
	s_waitcnt vmcnt(18)
	ds_write_b128 v8, v[32:35]
	v_mad_u64_u32 v[8:9], s[14:15], v110, s28, v[88:89]
	s_waitcnt vmcnt(17)
	ds_write_b128 v8, v[40:43]
	v_mad_u64_u32 v[8:9], s[14:15], v111, s28, v[88:89]
	s_waitcnt vmcnt(16)
	ds_write_b128 v8, v[44:47]
	v_add_u32_e32 v8, s29, v152
	v_mad_u64_u32 v[10:11], s[14:15], v90, s30, v[8:9]
	s_waitcnt vmcnt(15)
	ds_write_b128 v10, v[52:55]
	v_mad_u64_u32 v[10:11], s[14:15], v96, s30, v[8:9]
	s_waitcnt vmcnt(14)
	ds_write_b128 v10, v[56:59]
	v_mad_u64_u32 v[10:11], s[14:15], v98, s30, v[8:9]
	s_waitcnt vmcnt(13)
	ds_write_b128 v10, v[60:63]
	v_mad_u64_u32 v[10:11], s[14:15], v100, s30, v[8:9]
	s_waitcnt vmcnt(12)
	ds_write_b128 v10, v[64:67]
	v_mad_u64_u32 v[10:11], s[14:15], v102, s30, v[8:9]
	v_and_b32_e32 v152, -16, v161
	s_add_u32 s12, s26, s12
	s_addc_u32 s13, s27, 0
	s_waitcnt vmcnt(11)
	ds_write_b128 v10, v[68:71]
	v_mad_u64_u32 v[10:11], s[14:15], v104, s30, v[8:9]
	s_waitcnt vmcnt(10)
	ds_write_b128 v10, v[72:75]
	v_mad_u64_u32 v[10:11], s[14:15], v106, s30, v[8:9]
	v_mad_u64_u32 v[8:9], s[14:15], v108, s30, v[8:9]
	s_waitcnt vmcnt(9)
	ds_write_b128 v10, v[76:79]
	s_add_i32 s34, s34, s58
	s_cmp_ge_i32 s34, s5
	s_waitcnt vmcnt(8)
	ds_write_b128 v8, v[80:83]
	v_mul_u32_u24_e32 v8, 0x110, v163
	v_add3_u32 v112, 16, v152, v8
	s_waitcnt lgkmcnt(0)
	s_barrier
	ds_read_b128 v[8:11], v112
	ds_read_b128 v[12:15], v112 offset:64
	s_waitcnt vmcnt(7) lgkmcnt(1)
	v_mfma_f32_16x16x32_bf16 v[20:23], v[8:11], v[0:3], 0
	s_waitcnt vmcnt(6)
	v_mfma_f32_16x16x32_bf16 v[8:11], v[8:11], v[92:95], 0
	s_waitcnt vmcnt(5) lgkmcnt(0)
	v_mfma_f32_16x16x32_bf16 v[20:23], v[12:15], v[4:7], v[20:23]
	s_waitcnt vmcnt(4)
	v_mfma_f32_16x16x32_bf16 v[8:11], v[12:15], v[28:31], v[8:11]
	ds_read_b128 v[12:15], v112 offset:128
	ds_read_b128 v[24:27], v112 offset:192
	s_waitcnt vmcnt(3) lgkmcnt(1)
	v_mfma_f32_16x16x32_bf16 v[8:11], v[12:15], v[36:39], v[8:11]
	s_waitcnt vmcnt(2)
	v_mfma_f32_16x16x32_bf16 v[20:23], v[12:15], v[16:19], v[20:23]
	s_waitcnt vmcnt(0) lgkmcnt(0)
	v_mfma_f32_16x16x32_bf16 v[76:79], v[24:27], v[48:51], v[8:11]
	s_nop 3
	ds_read_b128 v[8:11], v112 offset:4352
	ds_read_b128 v[12:15], v112 offset:4416
	v_mfma_f32_16x16x32_bf16 v[148:151], v[24:27], v[84:87], v[20:23]
	s_waitcnt lgkmcnt(1)
	v_mfma_f32_16x16x32_bf16 v[20:23], v[8:11], v[0:3], 0
	v_mfma_f32_16x16x32_bf16 v[8:11], v[8:11], v[92:95], 0
	s_nop 4
	v_max_f32_e32 v113, v150, v150
	s_waitcnt lgkmcnt(0)
	v_mfma_f32_16x16x32_bf16 v[20:23], v[12:15], v[4:7], v[20:23]
	v_mfma_f32_16x16x32_bf16 v[8:11], v[12:15], v[28:31], v[8:11]
	ds_read_b128 v[12:15], v112 offset:4480
	ds_read_b128 v[24:27], v112 offset:4544
	s_waitcnt lgkmcnt(1)
	v_mfma_f32_16x16x32_bf16 v[8:11], v[12:15], v[36:39], v[8:11]
	v_mfma_f32_16x16x32_bf16 v[20:23], v[12:15], v[16:19], v[20:23]
	s_waitcnt lgkmcnt(0)
	v_mfma_f32_16x16x32_bf16 v[72:75], v[24:27], v[48:51], v[8:11]
	s_nop 4
	ds_read_b128 v[8:11], v112 offset:8704
	ds_read_b128 v[12:15], v112 offset:8768
	v_mfma_f32_16x16x32_bf16 v[144:147], v[24:27], v[84:87], v[20:23]
	s_waitcnt lgkmcnt(1)
	v_mfma_f32_16x16x32_bf16 v[20:23], v[8:11], v[0:3], 0
	v_mfma_f32_16x16x32_bf16 v[8:11], v[8:11], v[92:95], 0
	s_nop 4
	v_max_f32_e32 v114, v146, v146
	s_waitcnt lgkmcnt(0)
	v_mfma_f32_16x16x32_bf16 v[20:23], v[12:15], v[4:7], v[20:23]
	v_mfma_f32_16x16x32_bf16 v[8:11], v[12:15], v[28:31], v[8:11]
	ds_read_b128 v[12:15], v112 offset:8832
	ds_read_b128 v[24:27], v112 offset:8896
	s_waitcnt lgkmcnt(1)
	v_mfma_f32_16x16x32_bf16 v[8:11], v[12:15], v[36:39], v[8:11]
	v_mfma_f32_16x16x32_bf16 v[20:23], v[12:15], v[16:19], v[20:23]
	s_waitcnt lgkmcnt(0)
	v_mfma_f32_16x16x32_bf16 v[68:71], v[24:27], v[48:51], v[8:11]
	s_nop 4
	ds_read_b128 v[8:11], v112 offset:13056
	ds_read_b128 v[12:15], v112 offset:13120
	v_mfma_f32_16x16x32_bf16 v[140:143], v[24:27], v[84:87], v[20:23]
	s_waitcnt lgkmcnt(1)
	v_mfma_f32_16x16x32_bf16 v[20:23], v[8:11], v[0:3], 0
	v_mfma_f32_16x16x32_bf16 v[8:11], v[8:11], v[92:95], 0
	s_waitcnt lgkmcnt(0)
	v_mfma_f32_16x16x32_bf16 v[20:23], v[12:15], v[4:7], v[20:23]
	v_mfma_f32_16x16x32_bf16 v[8:11], v[12:15], v[28:31], v[8:11]
	ds_read_b128 v[12:15], v112 offset:13184
	ds_read_b128 v[24:27], v112 offset:13248
	s_waitcnt lgkmcnt(1)
	v_mfma_f32_16x16x32_bf16 v[8:11], v[12:15], v[36:39], v[8:11]
	v_mfma_f32_16x16x32_bf16 v[20:23], v[12:15], v[16:19], v[20:23]
	s_waitcnt lgkmcnt(0)
	v_mfma_f32_16x16x32_bf16 v[60:63], v[24:27], v[48:51], v[8:11]
	s_nop 4
	ds_read_b128 v[8:11], v112 offset:17408
	ds_read_b128 v[12:15], v112 offset:17472
	v_mfma_f32_16x16x32_bf16 v[136:139], v[24:27], v[84:87], v[20:23]
	s_waitcnt lgkmcnt(1)
	v_mfma_f32_16x16x32_bf16 v[20:23], v[8:11], v[0:3], 0
	v_mfma_f32_16x16x32_bf16 v[8:11], v[8:11], v[92:95], 0
	s_waitcnt lgkmcnt(0)
	v_mfma_f32_16x16x32_bf16 v[20:23], v[12:15], v[4:7], v[20:23]
	v_mfma_f32_16x16x32_bf16 v[8:11], v[12:15], v[28:31], v[8:11]
	ds_read_b128 v[12:15], v112 offset:17536
	ds_read_b128 v[24:27], v112 offset:17600
	s_waitcnt lgkmcnt(1)
	v_mfma_f32_16x16x32_bf16 v[8:11], v[12:15], v[36:39], v[8:11]
	v_mfma_f32_16x16x32_bf16 v[20:23], v[12:15], v[16:19], v[20:23]
	s_waitcnt lgkmcnt(0)
	v_mfma_f32_16x16x32_bf16 v[56:59], v[24:27], v[48:51], v[8:11]
	s_nop 4
	ds_read_b128 v[8:11], v112 offset:21760
	ds_read_b128 v[12:15], v112 offset:21824
	v_mfma_f32_16x16x32_bf16 v[132:135], v[24:27], v[84:87], v[20:23]
	s_waitcnt lgkmcnt(1)
; #define MFMA16(a, b, c) __builtin_amdgcn_mfma_f32_16x16x32_bf16((a), (b), (c), 0, 0, 0)
; __device__ __forceinline__ void attn_prompt_item(const Params& p, int item, const int wv, unsigned* bar) {
;     ...
;   f32x4 s[16][2];
; #pragma unroll
;   for (int mb = 0; mb < 16; ++mb) {
;     s[mb][0] = (f32x4){0.f, 0.f, 0.f, 0.f}; s[mb][1] = (f32x4){0.f, 0.f, 0.f, 0.f};
; #pragma unroll
;     for (int ks = 0; ks < 4; ++ks) {
;       bf16x8 kf = *(const bf16x8*)(K_l + (mb * 16 + fr) * 136 + ks * 32 + fq * 8);
;       s[mb][0] = MFMA16(kf, qf[0][ks], s[mb][0]);
;       s[mb][1] = MFMA16(kf, qf[1][ks], s[mb][1]);
;     }
;   }
;   const float cexp = 0.08838834764831845f * 1.4426950408889634f;
;   float inv[2];
;   bf16x8 pf[2][8];
; #pragma unroll
;   for (int qb = 0; qb < 2; ++qb) {
;     float mx = -1e30f;
; #pragma unroll
;     for (int mb = 0; mb < 16; ++mb) mx = fmaxf(mx, fmaxf(fmaxf(s[mb][qb][0], s[mb][qb][1]), fmaxf(s[mb][qb][2], s[mb][qb][3])));
	v_mfma_f32_16x16x32_bf16 v[20:23], v[8:11], v[0:3], 0
	v_mfma_f32_16x16x32_bf16 v[8:11], v[8:11], v[92:95], 0
	s_waitcnt lgkmcnt(0)
	v_mfma_f32_16x16x32_bf16 v[20:23], v[12:15], v[4:7], v[20:23]
	v_mfma_f32_16x16x32_bf16 v[8:11], v[12:15], v[28:31], v[8:11]
	ds_read_b128 v[12:15], v112 offset:21888
	ds_read_b128 v[24:27], v112 offset:21952
	s_waitcnt lgkmcnt(1)
	v_mfma_f32_16x16x32_bf16 v[8:11], v[12:15], v[36:39], v[8:11]
	v_mfma_f32_16x16x32_bf16 v[20:23], v[12:15], v[16:19], v[20:23]
	s_waitcnt lgkmcnt(0)
	v_mfma_f32_16x16x32_bf16 v[44:47], v[24:27], v[48:51], v[8:11]
	s_nop 4
	ds_read_b128 v[8:11], v112 offset:26112
	ds_read_b128 v[12:15], v112 offset:26176
	v_mfma_f32_16x16x32_bf16 v[128:131], v[24:27], v[84:87], v[20:23]
	s_waitcnt lgkmcnt(1)
	v_mfma_f32_16x16x32_bf16 v[20:23], v[8:11], v[0:3], 0
	v_mfma_f32_16x16x32_bf16 v[8:11], v[8:11], v[92:95], 0
	s_waitcnt lgkmcnt(0)
	v_mfma_f32_16x16x32_bf16 v[20:23], v[12:15], v[4:7], v[20:23]
	v_mfma_f32_16x16x32_bf16 v[8:11], v[12:15], v[28:31], v[8:11]
	ds_read_b128 v[12:15], v112 offset:26240
	ds_read_b128 v[24:27], v112 offset:26304
	s_waitcnt lgkmcnt(1)
	v_mfma_f32_16x16x32_bf16 v[8:11], v[12:15], v[36:39], v[8:11]
	v_mfma_f32_16x16x32_bf16 v[20:23], v[12:15], v[16:19], v[20:23]
	s_waitcnt lgkmcnt(0)
	v_mfma_f32_16x16x32_bf16 v[40:43], v[24:27], v[48:51], v[8:11]
	s_nop 4
	ds_read_b128 v[8:11], v112 offset:30464
	ds_read_b128 v[12:15], v112 offset:30528
	v_mfma_f32_16x16x32_bf16 v[124:127], v[24:27], v[84:87], v[20:23]
	s_waitcnt lgkmcnt(1)
	v_mfma_f32_16x16x32_bf16 v[20:23], v[8:11], v[0:3], 0
	v_mfma_f32_16x16x32_bf16 v[8:11], v[8:11], v[92:95], 0
	s_waitcnt lgkmcnt(0)
	v_mfma_f32_16x16x32_bf16 v[20:23], v[12:15], v[4:7], v[20:23]
	v_mfma_f32_16x16x32_bf16 v[8:11], v[12:15], v[28:31], v[8:11]
	ds_read_b128 v[12:15], v112 offset:30592
	ds_read_b128 v[24:27], v112 offset:30656
	s_waitcnt lgkmcnt(1)
	v_mfma_f32_16x16x32_bf16 v[8:11], v[12:15], v[36:39], v[8:11]
	v_mfma_f32_16x16x32_bf16 v[20:23], v[12:15], v[16:19], v[20:23]
	s_waitcnt lgkmcnt(0)
	v_mfma_f32_16x16x32_bf16 v[32:35], v[24:27], v[48:51], v[8:11]
	s_nop 4
	ds_read_b128 v[8:11], v112 offset:34816
	ds_read_b128 v[12:15], v112 offset:34880
	v_mfma_f32_16x16x32_bf16 v[120:123], v[24:27], v[84:87], v[20:23]
	s_waitcnt lgkmcnt(1)
	v_mfma_f32_16x16x32_bf16 v[20:23], v[8:11], v[0:3], 0
	v_mfma_f32_16x16x32_bf16 v[8:11], v[8:11], v[92:95], 0
	s_waitcnt lgkmcnt(0)
	v_mfma_f32_16x16x32_bf16 v[20:23], v[12:15], v[4:7], v[20:23]
	v_mfma_f32_16x16x32_bf16 v[8:11], v[12:15], v[28:31], v[8:11]
	ds_read_b128 v[12:15], v112 offset:34944
	ds_read_b128 v[24:27], v112 offset:35008
	s_waitcnt lgkmcnt(1)
	v_mfma_f32_16x16x32_bf16 v[20:23], v[12:15], v[16:19], v[20:23]
	v_mfma_f32_16x16x32_bf16 v[8:11], v[12:15], v[36:39], v[8:11]
	s_waitcnt lgkmcnt(0)
	v_mfma_f32_16x16x32_bf16 v[116:119], v[24:27], v[84:87], v[20:23]
	v_mfma_f32_16x16x32_bf16 v[24:27], v[24:27], v[48:51], v[8:11]
	s_nop 4
	ds_read_b128 v[8:11], v112 offset:39168
	ds_read_b128 v[12:15], v112 offset:39232
	s_waitcnt lgkmcnt(1)
	v_mfma_f32_16x16x32_bf16 v[20:23], v[8:11], v[0:3], 0
	v_mfma_f32_16x16x32_bf16 v[8:11], v[8:11], v[92:95], 0
	s_waitcnt lgkmcnt(0)
	v_mfma_f32_16x16x32_bf16 v[20:23], v[12:15], v[4:7], v[20:23]
	v_mfma_f32_16x16x32_bf16 v[8:11], v[12:15], v[28:31], v[8:11]
	ds_read_b128 v[12:15], v112 offset:39296
	ds_read_b128 v[52:55], v112 offset:39360
	s_waitcnt lgkmcnt(1)
	v_mfma_f32_16x16x32_bf16 v[20:23], v[12:15], v[16:19], v[20:23]
	v_mfma_f32_16x16x32_bf16 v[8:11], v[12:15], v[36:39], v[8:11]
	s_waitcnt lgkmcnt(0)
	v_mfma_f32_16x16x32_bf16 v[108:111], v[52:55], v[84:87], v[20:23]
	v_mfma_f32_16x16x32_bf16 v[20:23], v[52:55], v[48:51], v[8:11]
	s_nop 4
	ds_read_b128 v[8:11], v112 offset:43520
	ds_read_b128 v[12:15], v112 offset:43584
	s_waitcnt lgkmcnt(1)
	v_mfma_f32_16x16x32_bf16 v[52:55], v[8:11], v[0:3], 0
	v_mfma_f32_16x16x32_bf16 v[8:11], v[8:11], v[92:95], 0
	s_waitcnt lgkmcnt(0)
	v_mfma_f32_16x16x32_bf16 v[52:55], v[12:15], v[4:7], v[52:55]
	v_mfma_f32_16x16x32_bf16 v[8:11], v[12:15], v[28:31], v[8:11]
	ds_read_b128 v[12:15], v112 offset:43648
	ds_read_b128 v[64:67], v112 offset:43712
	ds_read_b128 v[88:91], v112 offset:47872
	ds_read_b128 v[96:99], v112 offset:47936
	ds_read_b128 v[100:103], v112 offset:48000
	ds_read_b128 v[164:167], v112 offset:48064
	ds_read_b128 v[168:171], v112 offset:52224
	ds_read_b128 v[172:175], v112 offset:52288
	ds_read_b128 v[176:179], v112 offset:52352
	ds_read_b128 v[180:183], v112 offset:52416
	s_waitcnt lgkmcnt(9)
	v_mfma_f32_16x16x32_bf16 v[8:11], v[12:15], v[36:39], v[8:11]
	ds_read_b128 v[184:187], v112 offset:56576
	ds_read_b128 v[188:191], v112 offset:56640
	ds_read_b128 v[192:195], v112 offset:56704
	ds_read_b128 v[196:199], v112 offset:56768
	ds_read_b128 v[200:203], v112 offset:60928
	ds_read_b128 v[204:207], v112 offset:60992
	ds_read_b128 v[208:211], v112 offset:61056
	ds_read_b128 v[212:215], v112 offset:61120
	v_mfma_f32_16x16x32_bf16 v[52:55], v[12:15], v[16:19], v[52:55]
	s_waitcnt lgkmcnt(14)
	v_mfma_f32_16x16x32_bf16 v[12:15], v[64:67], v[48:51], v[8:11]
	v_mfma_f32_16x16x32_bf16 v[8:11], v[88:91], v[0:3], 0
	v_mfma_f32_16x16x32_bf16 v[88:91], v[88:91], v[92:95], 0
	v_mfma_f32_16x16x32_bf16 v[8:11], v[96:99], v[4:7], v[8:11]
	v_mfma_f32_16x16x32_bf16 v[88:91], v[96:99], v[28:31], v[88:91]
	v_max_f32_e32 v97, v143, v143
	v_max_f32_e32 v98, v142, v142
	v_max_f32_e32 v97, v98, v97
	v_mfma_f32_16x16x32_bf16 v[104:107], v[64:67], v[84:87], v[52:55]
	ds_read_b128 v[216:219], v112 offset:65280
	ds_read_b128 v[80:83], v112 offset:65344
	ds_read_b128 v[64:67], v112 offset:65408
	ds_read_b128 v[52:55], v112 offset:65472
	v_max_f32_e32 v112, v151, v151
	v_max_f32_e32 v112, v113, v112
	s_waitcnt lgkmcnt(14)
; __device__ __forceinline__ float shfl_xor_f(float v, int mask) { const int l = lane_fresh(); return __int_as_float(__builtin_amdgcn_ds_bpermute((l ^ mask) << 2, __float_as_int(v))); }
; #define MFMA16(a, b, c) __builtin_amdgcn_mfma_f32_16x16x32_bf16((a), (b), (c), 0, 0, 0)
; __device__ __forceinline__ void attn_prompt_item(const Params& p, int item, const int wv, unsigned* bar) {
;     ...
;   f32x4 s[16][2];
; #pragma unroll
;   for (int mb = 0; mb < 16; ++mb) {
;     s[mb][0] = (f32x4){0.f, 0.f, 0.f, 0.f}; s[mb][1] = (f32x4){0.f, 0.f, 0.f, 0.f};
; #pragma unroll
;     for (int ks = 0; ks < 4; ++ks) {
;       bf16x8 kf = *(const bf16x8*)(K_l + (mb * 16 + fr) * 136 + ks * 32 + fq * 8);
;       s[mb][0] = MFMA16(kf, qf[0][ks], s[mb][0]);
;       s[mb][1] = MFMA16(kf, qf[1][ks], s[mb][1]);
;     }
;   }
;   const float cexp = 0.08838834764831845f * 1.4426950408889634f;
;   float inv[2];
;   bf16x8 pf[2][8];
; #pragma unroll
;   for (int qb = 0; qb < 2; ++qb) {
;     float mx = -1e30f;
; #pragma unroll
;     for (int mb = 0; mb < 16; ++mb) mx = fmaxf(mx, fmaxf(fmaxf(s[mb][qb][0], s[mb][qb][1]), fmaxf(s[mb][qb][2], s[mb][qb][3])));
;     mx = fmaxf(mx, shfl_xor_f(mx, 16)); mx = fmaxf(mx, shfl_xor_f(mx, 32));
	v_mfma_f32_16x16x32_bf16 v[8:11], v[100:103], v[16:19], v[8:11]
	v_max_f32_e32 v113, v147, v147
	v_max_f32_e32 v96, v114, v113
	v_max3_f32 v112, v148, v149, v112
	v_mfma_f32_16x16x32_bf16 v[88:91], v[100:103], v[36:39], v[88:91]
	v_max3_f32 v96, v144, v145, v96
	v_max_f32_e32 v98, v139, v139
	v_max_f32_e32 v99, v138, v138
	v_max3_f32 v96, v112, s31, v96
	v_mfma_f32_16x16x32_bf16 v[112:115], v[164:167], v[84:87], v[8:11]
	v_max3_f32 v97, v140, v141, v97
	s_nop 1
	v_max_f32_e32 v8, v99, v98
	v_max3_f32 v8, v136, v137, v8
	v_max3_f32 v96, v96, v97, v8
	v_mfma_f32_16x16x32_bf16 v[8:11], v[164:167], v[48:51], v[88:91]
	v_max_f32_e32 v98, v131, v131
	v_max_f32_e32 v99, v130, v130
	v_max_f32_e32 v98, v99, v98
	v_max_f32_e32 v88, v135, v135
	v_max_f32_e32 v89, v134, v134
	v_max_f32_e32 v97, v89, v88
	v_mfma_f32_16x16x32_bf16 v[88:91], v[168:171], v[0:3], 0
	v_max3_f32 v97, v132, v133, v97
	v_max3_f32 v98, v128, v129, v98
	v_max3_f32 v96, v96, v97, v98
	v_mfma_f32_16x16x32_bf16 v[88:91], v[172:175], v[4:7], v[88:91]
	v_max_f32_e32 v97, v127, v127
	v_max_f32_e32 v98, v126, v126
	v_max_f32_e32 v97, v98, v97
	s_waitcnt lgkmcnt(13)
	v_mfma_f32_16x16x32_bf16 v[88:91], v[176:179], v[16:19], v[88:91]
	v_max_f32_e32 v98, v123, v123
	v_max_f32_e32 v99, v122, v122
	v_max_f32_e32 v98, v99, v98
	s_waitcnt lgkmcnt(12)
	v_mfma_f32_16x16x32_bf16 v[100:103], v[180:183], v[84:87], v[88:91]
	v_max3_f32 v97, v124, v125, v97
	v_max3_f32 v98, v120, v121, v98
	v_max3_f32 v164, v96, v97, v98
	s_waitcnt lgkmcnt(11)
	v_mfma_f32_16x16x32_bf16 v[88:91], v[184:187], v[0:3], 0
	v_max_f32_e32 v96, v119, v119
	v_max_f32_e32 v97, v118, v118
	v_max_f32_e32 v96, v97, v96
	s_waitcnt lgkmcnt(10)
	v_mfma_f32_16x16x32_bf16 v[88:91], v[188:191], v[4:7], v[88:91]
	v_max_f32_e32 v166, v111, v111
	v_max_f32_e32 v167, v110, v110
	v_max3_f32 v165, v116, v117, v96
	s_waitcnt lgkmcnt(9)
	v_mfma_f32_16x16x32_bf16 v[88:91], v[192:195], v[16:19], v[88:91]
	s_waitcnt lgkmcnt(8)
	v_mfma_f32_16x16x32_bf16 v[96:99], v[196:199], v[84:87], v[88:91]
	s_nop 5
	v_max_f32_e32 v88, v167, v166
	v_max3_f32 v88, v108, v109, v88
	v_max3_f32 v164, v164, v165, v88
	s_waitcnt lgkmcnt(7)
	v_mfma_f32_16x16x32_bf16 v[88:91], v[200:203], v[0:3], 0
	v_max_f32_e32 v165, v107, v107
	v_max_f32_e32 v166, v106, v106
	v_max_f32_e32 v165, v166, v165
	s_waitcnt lgkmcnt(3)
	v_mfma_f32_16x16x32_bf16 v[0:3], v[216:219], v[0:3], 0
	v_max_f32_e32 v166, v115, v115
	v_max_f32_e32 v167, v114, v114
	v_max_f32_e32 v166, v167, v166
	v_mfma_f32_16x16x32_bf16 v[88:91], v[204:207], v[4:7], v[88:91]
	v_max3_f32 v165, v104, v105, v165
	v_max3_f32 v166, v112, v113, v166
	v_max3_f32 v164, v164, v165, v166
	s_waitcnt lgkmcnt(2)
	v_mfma_f32_16x16x32_bf16 v[0:3], v[80:83], v[4:7], v[0:3]
	v_max_f32_e32 v165, v103, v103
	v_max_f32_e32 v166, v102, v102
	v_max_f32_e32 v165, v166, v165
	v_mfma_f32_16x16x32_bf16 v[88:91], v[208:211], v[16:19], v[88:91]
	v_max_f32_e32 v166, v99, v99
	v_max_f32_e32 v167, v98, v98
	v_max_f32_e32 v4, v167, v166
	s_waitcnt lgkmcnt(1)
	v_mfma_f32_16x16x32_bf16 v[0:3], v[64:67], v[16:19], v[0:3]
	v_max3_f32 v165, v100, v101, v165
	v_max3_f32 v4, v96, v97, v4
	v_max3_f32 v4, v164, v165, v4
	v_mfma_f32_16x16x32_bf16 v[88:91], v[212:215], v[84:87], v[88:91]
	s_waitcnt lgkmcnt(0)
	v_mfma_f32_16x16x32_bf16 v[84:87], v[52:55], v[84:87], v[0:3]
	v_mfma_f32_16x16x32_bf16 v[0:3], v[168:171], v[92:95], 0
	s_nop 4
	v_max_f32_e32 v5, v91, v91
	v_max_f32_e32 v6, v90, v90
	v_max_f32_e32 v5, v6, v5
	v_max_f32_e32 v6, v87, v87
	v_max_f32_e32 v7, v86, v86
	v_max_f32_e32 v6, v7, v6
	v_max3_f32 v5, v88, v89, v5
	v_max3_f32 v6, v84, v85, v6
	v_mfma_f32_16x16x32_bf16 v[0:3], v[172:175], v[28:31], v[0:3]
	v_max3_f32 v4, v4, v5, v6
	v_mbcnt_lo_u32_b32 v5, -1, 0
	v_mbcnt_hi_u32_b32 v5, -1, v5
	s_nop 0
	v_lshlrev_b32_e32 v5, 2, v5
	v_xor_b32_e32 v5, 64, v5
	v_mfma_f32_16x16x32_bf16 v[0:3], v[176:179], v[36:39], v[0:3]
	ds_bpermute_b32 v5, v5, v4
	s_waitcnt lgkmcnt(0)
	v_max_f32_e32 v5, v5, v5
	v_mfma_f32_16x16x32_bf16 v[16:19], v[180:183], v[48:51], v[0:3]
	v_mbcnt_lo_u32_b32 v0, -1, 0
	v_mbcnt_hi_u32_b32 v0, -1, v0
	v_max_f32_e32 v4, v4, v5
	s_nop 2
	v_lshlrev_b32_e32 v0, 2, v0
	v_xor_b32_e32 v5, 0x80, v0
	ds_bpermute_b32 v5, v5, v4
	v_mfma_f32_16x16x32_bf16 v[0:3], v[184:187], v[92:95], 0
	s_waitcnt lgkmcnt(0)
; __device__ __forceinline__ float shfl_xor_f(float v, int mask) { const int l = lane_fresh(); return __int_as_float(__builtin_amdgcn_ds_bpermute((l ^ mask) << 2, __float_as_int(v))); }
; __device__ __forceinline__ void attn_prompt_item(const Params& p, int item, const int wv, unsigned* bar) {
;     ...
;     float sum = 0.f;
; #pragma unroll
;     for (int mb = 0; mb < 16; ++mb)
; #pragma unroll
;       for (int e = 0; e < 4; ++e) { float pv = exp2f((s[mb][qb][e] - mx) * cexp); s[mb][qb][e] = pv; sum += pv; }
;     sum += shfl_xor_f(sum, 16); sum += shfl_xor_f(sum, 32);
	v_max_f32_e32 v5, v5, v5
	v_max_f32_e32 v164, v4, v5
	v_sub_f32_e32 v4, v148, v164
	v_mul_f32_e32 v5, 0x3e0293ee, v4
	v_cmp_gt_f32_e32 vcc, s33, v5
	v_sub_f32_e32 v149, v149, v164
	v_mul_f32_e32 v166, 0x3e0293ee, v149
	v_cndmask_b32_e32 v5, 0, v159, vcc
	v_fmac_f32_e32 v5, 0x3e0293ee, v4
	v_exp_f32_e32 v148, v5
	v_cndmask_b32_e32 v165, 0, v160, vcc
	v_cmp_gt_f32_e32 vcc, s33, v166
	v_sub_f32_e32 v150, v150, v164
	v_ldexp_f32 v148, v148, v165
	v_cndmask_b32_e32 v166, 0, v159, vcc
	v_fmac_f32_e32 v166, 0x3e0293ee, v149
	v_exp_f32_e32 v149, v166
	v_mul_f32_e32 v166, 0x3e0293ee, v150
	v_cndmask_b32_e32 v165, 0, v160, vcc
	v_cmp_gt_f32_e32 vcc, s33, v166
	v_sub_f32_e32 v151, v151, v164
	v_mul_f32_e32 v167, 0x3e0293ee, v151
	v_cndmask_b32_e32 v166, 0, v159, vcc
	v_fmac_f32_e32 v166, 0x3e0293ee, v150
	v_exp_f32_e32 v150, v166
	v_cndmask_b32_e32 v166, 0, v160, vcc
	v_cmp_gt_f32_e32 vcc, s33, v167
	v_sub_f32_e32 v144, v144, v164
	v_ldexp_f32 v150, v150, v166
	v_cndmask_b32_e32 v167, 0, v159, vcc
	v_fmac_f32_e32 v167, 0x3e0293ee, v151
	v_exp_f32_e32 v151, v167
	v_cndmask_b32_e32 v166, 0, v160, vcc
	v_sub_f32_e32 v145, v145, v164
	v_mul_f32_e32 v167, 0x3e0293ee, v145
	v_ldexp_f32 v151, v151, v166
	v_mul_f32_e32 v166, 0x3e0293ee, v144
	v_cmp_gt_f32_e32 vcc, s33, v166
	v_sub_f32_e32 v146, v146, v164
	v_sub_f32_e32 v147, v147, v164
	v_cndmask_b32_e32 v166, 0, v159, vcc
	v_fmac_f32_e32 v166, 0x3e0293ee, v144
	v_exp_f32_e32 v144, v166
	v_cndmask_b32_e32 v166, 0, v160, vcc
	v_cmp_gt_f32_e32 vcc, s33, v167
	v_sub_f32_e32 v140, v140, v164
	v_ldexp_f32 v144, v144, v166
	v_cndmask_b32_e32 v167, 0, v159, vcc
	v_fmac_f32_e32 v167, 0x3e0293ee, v145
	v_exp_f32_e32 v145, v167
	v_cndmask_b32_e32 v166, 0, v160, vcc
	v_mul_f32_e32 v167, 0x3e0293ee, v147
	v_sub_f32_e32 v141, v141, v164
	v_ldexp_f32 v145, v145, v166
	v_mul_f32_e32 v166, 0x3e0293ee, v146
	v_cmp_gt_f32_e32 vcc, s33, v166
	v_sub_f32_e32 v142, v142, v164
	v_sub_f32_e32 v143, v143, v164
	v_cndmask_b32_e32 v166, 0, v159, vcc
	v_fmac_f32_e32 v166, 0x3e0293ee, v146
	v_exp_f32_e32 v146, v166
	v_cndmask_b32_e32 v166, 0, v160, vcc
	v_cmp_gt_f32_e32 vcc, s33, v167
	v_sub_f32_e32 v136, v136, v164
	v_ldexp_f32 v146, v146, v166
	v_cndmask_b32_e32 v167, 0, v159, vcc
	v_fmac_f32_e32 v167, 0x3e0293ee, v147
	v_exp_f32_e32 v147, v167
	v_cndmask_b32_e32 v166, 0, v160, vcc
	v_mul_f32_e32 v167, 0x3e0293ee, v141
	v_sub_f32_e32 v137, v137, v164
	v_ldexp_f32 v147, v147, v166
	v_mul_f32_e32 v166, 0x3e0293ee, v140
	v_cmp_gt_f32_e32 vcc, s33, v166
	v_sub_f32_e32 v138, v138, v164
	v_sub_f32_e32 v139, v139, v164
	v_cndmask_b32_e32 v166, 0, v159, vcc
	v_fmac_f32_e32 v166, 0x3e0293ee, v140
	v_exp_f32_e32 v140, v166
	v_cndmask_b32_e32 v166, 0, v160, vcc
	v_cmp_gt_f32_e32 vcc, s33, v167
	v_sub_f32_e32 v132, v132, v164
	v_ldexp_f32 v140, v140, v166
	v_cndmask_b32_e32 v167, 0, v159, vcc
	v_fmac_f32_e32 v167, 0x3e0293ee, v141
	v_exp_f32_e32 v141, v167
	v_cndmask_b32_e32 v166, 0, v160, vcc
	v_mul_f32_e32 v167, 0x3e0293ee, v143
	v_sub_f32_e32 v133, v133, v164
	v_ldexp_f32 v141, v141, v166
	v_mul_f32_e32 v166, 0x3e0293ee, v142
	v_cmp_gt_f32_e32 vcc, s33, v166
	v_sub_f32_e32 v134, v134, v164
	v_sub_f32_e32 v135, v135, v164
	v_cndmask_b32_e32 v166, 0, v159, vcc
	v_fmac_f32_e32 v166, 0x3e0293ee, v142
	v_exp_f32_e32 v142, v166
	v_cndmask_b32_e32 v166, 0, v160, vcc
	v_cmp_gt_f32_e32 vcc, s33, v167
	v_sub_f32_e32 v128, v128, v164
	v_ldexp_f32 v142, v142, v166
	v_cndmask_b32_e32 v167, 0, v159, vcc
	v_fmac_f32_e32 v167, 0x3e0293ee, v143
	v_exp_f32_e32 v143, v167
	v_cndmask_b32_e32 v166, 0, v160, vcc
	v_mul_f32_e32 v167, 0x3e0293ee, v137
	v_sub_f32_e32 v129, v129, v164
	v_ldexp_f32 v143, v143, v166
	v_mul_f32_e32 v166, 0x3e0293ee, v136
	v_cmp_gt_f32_e32 vcc, s33, v166
	v_sub_f32_e32 v130, v130, v164
	v_sub_f32_e32 v131, v131, v164
	v_cndmask_b32_e32 v166, 0, v159, vcc
	v_fmac_f32_e32 v166, 0x3e0293ee, v136
	v_exp_f32_e32 v136, v166
	v_cndmask_b32_e32 v166, 0, v160, vcc
	v_cmp_gt_f32_e32 vcc, s33, v167
	v_sub_f32_e32 v124, v124, v164
	v_ldexp_f32 v136, v136, v166
	v_cndmask_b32_e32 v167, 0, v159, vcc
	v_fmac_f32_e32 v167, 0x3e0293ee, v137
	v_exp_f32_e32 v137, v167
	v_cndmask_b32_e32 v166, 0, v160, vcc
	v_mul_f32_e32 v167, 0x3e0293ee, v139
	v_sub_f32_e32 v125, v125, v164
	v_ldexp_f32 v137, v137, v166
	v_mul_f32_e32 v166, 0x3e0293ee, v138
	v_cmp_gt_f32_e32 vcc, s33, v166
	v_sub_f32_e32 v126, v126, v164
	v_sub_f32_e32 v127, v127, v164
	v_cndmask_b32_e32 v166, 0, v159, vcc
	v_fmac_f32_e32 v166, 0x3e0293ee, v138
	v_exp_f32_e32 v138, v166
	v_cndmask_b32_e32 v166, 0, v160, vcc
	v_cmp_gt_f32_e32 vcc, s33, v167
	v_sub_f32_e32 v120, v120, v164
	v_ldexp_f32 v138, v138, v166
	v_cndmask_b32_e32 v167, 0, v159, vcc
	v_fmac_f32_e32 v167, 0x3e0293ee, v139
	v_exp_f32_e32 v139, v167
	v_cndmask_b32_e32 v166, 0, v160, vcc
	v_mul_f32_e32 v167, 0x3e0293ee, v133
	v_sub_f32_e32 v121, v121, v164
	v_ldexp_f32 v139, v139, v166
	v_mul_f32_e32 v166, 0x3e0293ee, v132
	v_cmp_gt_f32_e32 vcc, s33, v166
	v_sub_f32_e32 v122, v122, v164
	v_sub_f32_e32 v123, v123, v164
	v_cndmask_b32_e32 v166, 0, v159, vcc
	v_fmac_f32_e32 v166, 0x3e0293ee, v132
	v_exp_f32_e32 v132, v166
	v_cndmask_b32_e32 v166, 0, v160, vcc
	v_cmp_gt_f32_e32 vcc, s33, v167
	v_sub_f32_e32 v116, v116, v164
	v_ldexp_f32 v132, v132, v166
	v_cndmask_b32_e32 v167, 0, v159, vcc
	v_fmac_f32_e32 v167, 0x3e0293ee, v133
	v_exp_f32_e32 v133, v167
	v_cndmask_b32_e32 v166, 0, v160, vcc
	v_mul_f32_e32 v167, 0x3e0293ee, v135
	v_sub_f32_e32 v117, v117, v164
	v_ldexp_f32 v133, v133, v166
	v_mul_f32_e32 v166, 0x3e0293ee, v134
	v_cmp_gt_f32_e32 vcc, s33, v166
	v_sub_f32_e32 v118, v118, v164
	v_sub_f32_e32 v119, v119, v164
; __device__ __forceinline__ float shfl_xor_f(float v, int mask) { const int l = lane_fresh(); return __int_as_float(__builtin_amdgcn_ds_bpermute((l ^ mask) << 2, __float_as_int(v))); }
; __device__ __forceinline__ void attn_prompt_item(const Params& p, int item, const int wv, unsigned* bar) {
;     ...
;     float sum = 0.f;
; #pragma unroll
;     for (int mb = 0; mb < 16; ++mb)
; #pragma unroll
;       for (int e = 0; e < 4; ++e) { float pv = exp2f((s[mb][qb][e] - mx) * cexp); s[mb][qb][e] = pv; sum += pv; }
;     sum += shfl_xor_f(sum, 16); sum += shfl_xor_f(sum, 32);
	v_cndmask_b32_e32 v166, 0, v159, vcc
	v_fmac_f32_e32 v166, 0x3e0293ee, v134
	v_exp_f32_e32 v134, v166
	v_cndmask_b32_e32 v166, 0, v160, vcc
	v_cmp_gt_f32_e32 vcc, s33, v167
	v_sub_f32_e32 v108, v108, v164
	v_ldexp_f32 v134, v134, v166
	v_cndmask_b32_e32 v167, 0, v159, vcc
	v_fmac_f32_e32 v167, 0x3e0293ee, v135
	v_exp_f32_e32 v135, v167
	v_cndmask_b32_e32 v166, 0, v160, vcc
	v_mul_f32_e32 v167, 0x3e0293ee, v129
	v_sub_f32_e32 v109, v109, v164
	v_ldexp_f32 v135, v135, v166
	v_mul_f32_e32 v166, 0x3e0293ee, v128
	v_cmp_gt_f32_e32 vcc, s33, v166
	v_sub_f32_e32 v110, v110, v164
	v_sub_f32_e32 v111, v111, v164
	v_cndmask_b32_e32 v166, 0, v159, vcc
	v_fmac_f32_e32 v166, 0x3e0293ee, v128
	v_exp_f32_e32 v128, v166
	v_cndmask_b32_e32 v166, 0, v160, vcc
	v_cmp_gt_f32_e32 vcc, s33, v167
	v_sub_f32_e32 v104, v104, v164
	v_ldexp_f32 v128, v128, v166
	v_cndmask_b32_e32 v167, 0, v159, vcc
	v_fmac_f32_e32 v167, 0x3e0293ee, v129
	v_exp_f32_e32 v129, v167
	v_cndmask_b32_e32 v166, 0, v160, vcc
	v_mul_f32_e32 v167, 0x3e0293ee, v131
	v_sub_f32_e32 v105, v105, v164
	v_ldexp_f32 v129, v129, v166
	v_mul_f32_e32 v166, 0x3e0293ee, v130
	v_cmp_gt_f32_e32 vcc, s33, v166
	v_sub_f32_e32 v106, v106, v164
	v_sub_f32_e32 v107, v107, v164
	v_cndmask_b32_e32 v166, 0, v159, vcc
	v_fmac_f32_e32 v166, 0x3e0293ee, v130
	v_exp_f32_e32 v130, v166
	v_cndmask_b32_e32 v166, 0, v160, vcc
	v_cmp_gt_f32_e32 vcc, s33, v167
	v_sub_f32_e32 v112, v112, v164
	v_ldexp_f32 v130, v130, v166
	v_cndmask_b32_e32 v167, 0, v159, vcc
	v_fmac_f32_e32 v167, 0x3e0293ee, v131
	v_exp_f32_e32 v131, v167
	v_cndmask_b32_e32 v166, 0, v160, vcc
	v_mul_f32_e32 v167, 0x3e0293ee, v125
	v_ldexp_f32 v149, v149, v165
	v_ldexp_f32 v131, v131, v166
	v_mul_f32_e32 v166, 0x3e0293ee, v124
	v_cmp_gt_f32_e32 vcc, s33, v166
	v_sub_f32_e32 v113, v113, v164
	v_add_f32_e32 v165, v148, v149
	v_cndmask_b32_e32 v166, 0, v159, vcc
	v_fmac_f32_e32 v166, 0x3e0293ee, v124
	v_exp_f32_e32 v124, v166
	v_cndmask_b32_e32 v166, 0, v160, vcc
	v_cmp_gt_f32_e32 vcc, s33, v167
	v_add_f32_e32 v165, v150, v165
	v_ldexp_f32 v124, v124, v166
	v_cndmask_b32_e32 v167, 0, v159, vcc
	v_fmac_f32_e32 v167, 0x3e0293ee, v125
	v_exp_f32_e32 v125, v167
	v_cndmask_b32_e32 v166, 0, v160, vcc
	v_mul_f32_e32 v167, 0x3e0293ee, v127
	v_add_f32_e32 v165, v151, v165
	v_ldexp_f32 v125, v125, v166
	v_mul_f32_e32 v166, 0x3e0293ee, v126
	v_cmp_gt_f32_e32 vcc, s33, v166
	v_add_f32_e32 v165, v144, v165
	v_add_f32_e32 v165, v145, v165
	v_cndmask_b32_e32 v166, 0, v159, vcc
	v_fmac_f32_e32 v166, 0x3e0293ee, v126
	v_exp_f32_e32 v126, v166
	v_cndmask_b32_e32 v166, 0, v160, vcc
	v_cmp_gt_f32_e32 vcc, s33, v167
	v_add_f32_e32 v165, v146, v165
	v_ldexp_f32 v126, v126, v166
	v_cndmask_b32_e32 v167, 0, v159, vcc
	v_fmac_f32_e32 v167, 0x3e0293ee, v127
	v_exp_f32_e32 v127, v167
	v_cndmask_b32_e32 v166, 0, v160, vcc
	v_mul_f32_e32 v167, 0x3e0293ee, v121
	v_add_f32_e32 v165, v147, v165
	v_ldexp_f32 v127, v127, v166
	v_mul_f32_e32 v166, 0x3e0293ee, v120
	v_cmp_gt_f32_e32 vcc, s33, v166
	v_add_f32_e32 v165, v140, v165
	v_sub_f32_e32 v114, v114, v164
	v_cndmask_b32_e32 v166, 0, v159, vcc
	v_fmac_f32_e32 v166, 0x3e0293ee, v120
	v_exp_f32_e32 v120, v166
	v_cndmask_b32_e32 v166, 0, v160, vcc
	v_cmp_gt_f32_e32 vcc, s33, v167
	v_add_f32_e32 v165, v141, v165
	v_ldexp_f32 v120, v120, v166
	v_cndmask_b32_e32 v167, 0, v159, vcc
	v_fmac_f32_e32 v167, 0x3e0293ee, v121
	v_exp_f32_e32 v121, v167
	v_cndmask_b32_e32 v166, 0, v160, vcc
	v_mul_f32_e32 v167, 0x3e0293ee, v123
	v_add_f32_e32 v165, v142, v165
	v_ldexp_f32 v121, v121, v166
	v_mul_f32_e32 v166, 0x3e0293ee, v122
	v_cmp_gt_f32_e32 vcc, s33, v166
	v_add_f32_e32 v165, v143, v165
	v_sub_f32_e32 v115, v115, v164
	v_cndmask_b32_e32 v166, 0, v159, vcc
	v_fmac_f32_e32 v166, 0x3e0293ee, v122
	v_exp_f32_e32 v122, v166
	v_cndmask_b32_e32 v166, 0, v160, vcc
	v_cmp_gt_f32_e32 vcc, s33, v167
	v_add_f32_e32 v165, v136, v165
	v_ldexp_f32 v122, v122, v166
	v_cndmask_b32_e32 v167, 0, v159, vcc
	v_fmac_f32_e32 v167, 0x3e0293ee, v123
	v_exp_f32_e32 v123, v167
	v_cndmask_b32_e32 v166, 0, v160, vcc
	v_mul_f32_e32 v167, 0x3e0293ee, v117
	v_add_f32_e32 v165, v137, v165
	v_ldexp_f32 v123, v123, v166
	v_mul_f32_e32 v166, 0x3e0293ee, v116
	v_cmp_gt_f32_e32 vcc, s33, v166
	v_add_f32_e32 v165, v138, v165
	v_add_f32_e32 v165, v139, v165
	v_cndmask_b32_e32 v166, 0, v159, vcc
	v_fmac_f32_e32 v166, 0x3e0293ee, v116
	v_exp_f32_e32 v116, v166
	v_cndmask_b32_e32 v166, 0, v160, vcc
	v_cmp_gt_f32_e32 vcc, s33, v167
	v_add_f32_e32 v165, v132, v165
	v_ldexp_f32 v116, v116, v166
	v_cndmask_b32_e32 v167, 0, v159, vcc
	v_fmac_f32_e32 v167, 0x3e0293ee, v117
	v_exp_f32_e32 v117, v167
	v_cndmask_b32_e32 v166, 0, v160, vcc
	v_mul_f32_e32 v167, 0x3e0293ee, v119
	v_add_f32_e32 v165, v133, v165
	v_ldexp_f32 v117, v117, v166
	v_mul_f32_e32 v166, 0x3e0293ee, v118
	v_cmp_gt_f32_e32 vcc, s33, v166
	v_add_f32_e32 v165, v134, v165
	v_add_f32_e32 v165, v135, v165
	v_cndmask_b32_e32 v166, 0, v159, vcc
	v_fmac_f32_e32 v166, 0x3e0293ee, v118
	v_exp_f32_e32 v118, v166
	v_cndmask_b32_e32 v166, 0, v160, vcc
	v_cmp_gt_f32_e32 vcc, s33, v167
	v_sub_f32_e32 v100, v100, v164
	v_ldexp_f32 v118, v118, v166
	v_cndmask_b32_e32 v167, 0, v159, vcc
	v_fmac_f32_e32 v167, 0x3e0293ee, v119
	v_exp_f32_e32 v119, v167
	v_cndmask_b32_e32 v166, 0, v160, vcc
	v_mul_f32_e32 v167, 0x3e0293ee, v109
	v_add_f32_e32 v165, v128, v165
	v_ldexp_f32 v119, v119, v166
	v_mul_f32_e32 v166, 0x3e0293ee, v108
	v_cmp_gt_f32_e32 vcc, s33, v166
	v_add_f32_e32 v165, v129, v165
	v_add_f32_e32 v165, v130, v165
	v_cndmask_b32_e32 v166, 0, v159, vcc
	v_fmac_f32_e32 v166, 0x3e0293ee, v108
	v_exp_f32_e32 v108, v166
	v_cndmask_b32_e32 v166, 0, v160, vcc
; __device__ __forceinline__ float shfl_xor_f(float v, int mask) { const int l = lane_fresh(); return __int_as_float(__builtin_amdgcn_ds_bpermute((l ^ mask) << 2, __float_as_int(v))); }
; __device__ __forceinline__ void attn_prompt_item(const Params& p, int item, const int wv, unsigned* bar) {
;     ...
;     float sum = 0.f;
; #pragma unroll
;     for (int mb = 0; mb < 16; ++mb)
; #pragma unroll
;       for (int e = 0; e < 4; ++e) { float pv = exp2f((s[mb][qb][e] - mx) * cexp); s[mb][qb][e] = pv; sum += pv; }
;     sum += shfl_xor_f(sum, 16); sum += shfl_xor_f(sum, 32);
	v_cmp_gt_f32_e32 vcc, s33, v167
	v_sub_f32_e32 v101, v101, v164
	v_ldexp_f32 v108, v108, v166
	v_cndmask_b32_e32 v167, 0, v159, vcc
	v_fmac_f32_e32 v167, 0x3e0293ee, v109
	v_exp_f32_e32 v109, v167
	v_cndmask_b32_e32 v166, 0, v160, vcc
	v_mul_f32_e32 v167, 0x3e0293ee, v111
	v_add_f32_e32 v165, v131, v165
	v_ldexp_f32 v109, v109, v166
	v_mul_f32_e32 v166, 0x3e0293ee, v110
	v_cmp_gt_f32_e32 vcc, s33, v166
	v_add_f32_e32 v165, v124, v165
	v_add_f32_e32 v165, v125, v165
	v_cndmask_b32_e32 v166, 0, v159, vcc
	v_fmac_f32_e32 v166, 0x3e0293ee, v110
	v_exp_f32_e32 v110, v166
	v_cndmask_b32_e32 v166, 0, v160, vcc
	v_cmp_gt_f32_e32 vcc, s33, v167
	v_add_f32_e32 v165, v126, v165
	v_ldexp_f32 v110, v110, v166
	v_cndmask_b32_e32 v167, 0, v159, vcc
	v_fmac_f32_e32 v167, 0x3e0293ee, v111
	v_exp_f32_e32 v111, v167
	v_cndmask_b32_e32 v166, 0, v160, vcc
	v_mul_f32_e32 v167, 0x3e0293ee, v105
	v_add_f32_e32 v165, v127, v165
	v_ldexp_f32 v111, v111, v166
	v_mul_f32_e32 v166, 0x3e0293ee, v104
	v_cmp_gt_f32_e32 vcc, s33, v166
	v_add_f32_e32 v165, v120, v165
	v_add_f32_e32 v165, v121, v165
	v_cndmask_b32_e32 v166, 0, v159, vcc
	v_fmac_f32_e32 v166, 0x3e0293ee, v104
	v_exp_f32_e32 v104, v166
	v_cndmask_b32_e32 v166, 0, v160, vcc
	v_cmp_gt_f32_e32 vcc, s33, v167
	v_add_f32_e32 v165, v122, v165
	v_ldexp_f32 v104, v104, v166
	v_cndmask_b32_e32 v167, 0, v159, vcc
	v_fmac_f32_e32 v167, 0x3e0293ee, v105
	v_exp_f32_e32 v105, v167
	v_cndmask_b32_e32 v166, 0, v160, vcc
	v_mul_f32_e32 v167, 0x3e0293ee, v107
	v_sub_f32_e32 v102, v102, v164
	v_ldexp_f32 v105, v105, v166
	v_mul_f32_e32 v166, 0x3e0293ee, v106
	v_cmp_gt_f32_e32 vcc, s33, v166
	v_add_f32_e32 v165, v123, v165
	v_add_f32_e32 v165, v116, v165
	v_cndmask_b32_e32 v166, 0, v159, vcc
	v_fmac_f32_e32 v166, 0x3e0293ee, v106
	v_exp_f32_e32 v106, v166
	v_cndmask_b32_e32 v166, 0, v160, vcc
	v_cmp_gt_f32_e32 vcc, s33, v167
	v_add_f32_e32 v165, v117, v165
	v_ldexp_f32 v106, v106, v166
	v_cndmask_b32_e32 v167, 0, v159, vcc
	v_fmac_f32_e32 v167, 0x3e0293ee, v107
	v_exp_f32_e32 v107, v167
	v_cndmask_b32_e32 v166, 0, v160, vcc
	v_mul_f32_e32 v167, 0x3e0293ee, v113
	v_sub_f32_e32 v103, v103, v164
	v_ldexp_f32 v107, v107, v166
	v_mul_f32_e32 v166, 0x3e0293ee, v112
	v_cmp_gt_f32_e32 vcc, s33, v166
	v_add_f32_e32 v165, v118, v165
	v_add_f32_e32 v165, v119, v165
	v_cndmask_b32_e32 v166, 0, v159, vcc
	v_fmac_f32_e32 v166, 0x3e0293ee, v112
	v_exp_f32_e32 v112, v166
	v_cndmask_b32_e32 v166, 0, v160, vcc
	v_cmp_gt_f32_e32 vcc, s33, v167
	v_add_f32_e32 v165, v108, v165
	v_ldexp_f32 v112, v112, v166
	v_cndmask_b32_e32 v167, 0, v159, vcc
	v_fmac_f32_e32 v167, 0x3e0293ee, v113
	v_exp_f32_e32 v113, v167
	v_cndmask_b32_e32 v166, 0, v160, vcc
	v_mul_f32_e32 v167, 0x3e0293ee, v115
	v_add_f32_e32 v165, v109, v165
	v_ldexp_f32 v113, v113, v166
	v_mul_f32_e32 v166, 0x3e0293ee, v114
	v_cmp_gt_f32_e32 vcc, s33, v166
	v_add_f32_e32 v165, v110, v165
	v_add_f32_e32 v165, v111, v165
	v_cndmask_b32_e32 v166, 0, v159, vcc
	v_fmac_f32_e32 v166, 0x3e0293ee, v114
	v_exp_f32_e32 v114, v166
	v_cndmask_b32_e32 v166, 0, v160, vcc
	v_cmp_gt_f32_e32 vcc, s33, v167
	v_add_f32_e32 v165, v104, v165
	v_ldexp_f32 v114, v114, v166
	v_cndmask_b32_e32 v167, 0, v159, vcc
	v_fmac_f32_e32 v167, 0x3e0293ee, v115
	v_exp_f32_e32 v115, v167
	v_cndmask_b32_e32 v166, 0, v160, vcc
	v_mul_f32_e32 v167, 0x3e0293ee, v101
	v_add_f32_e32 v165, v105, v165
	v_ldexp_f32 v115, v115, v166
	v_mul_f32_e32 v166, 0x3e0293ee, v100
	v_cmp_gt_f32_e32 vcc, s33, v166
	v_sub_f32_e32 v96, v96, v164
	v_add_f32_e32 v165, v106, v165
	v_cndmask_b32_e32 v166, 0, v159, vcc
	v_fmac_f32_e32 v166, 0x3e0293ee, v100
	v_exp_f32_e32 v100, v166
	v_cndmask_b32_e32 v166, 0, v160, vcc
	v_cmp_gt_f32_e32 vcc, s33, v167
	v_add_f32_e32 v165, v107, v165
	v_ldexp_f32 v100, v100, v166
	v_cndmask_b32_e32 v167, 0, v159, vcc
	v_fmac_f32_e32 v167, 0x3e0293ee, v101
	v_exp_f32_e32 v101, v167
	v_cndmask_b32_e32 v166, 0, v160, vcc
	v_mul_f32_e32 v167, 0x3e0293ee, v103
	v_add_f32_e32 v165, v112, v165
	v_ldexp_f32 v101, v101, v166
	v_mul_f32_e32 v166, 0x3e0293ee, v102
	v_cmp_gt_f32_e32 vcc, s33, v166
	v_sub_f32_e32 v97, v97, v164
	v_add_f32_e32 v165, v113, v165
	v_cndmask_b32_e32 v166, 0, v159, vcc
	v_fmac_f32_e32 v166, 0x3e0293ee, v102
	v_exp_f32_e32 v102, v166
	v_cndmask_b32_e32 v166, 0, v160, vcc
	v_cmp_gt_f32_e32 vcc, s33, v167
	v_add_f32_e32 v165, v114, v165
	v_ldexp_f32 v102, v102, v166
	v_cndmask_b32_e32 v167, 0, v159, vcc
	v_fmac_f32_e32 v167, 0x3e0293ee, v103
	v_exp_f32_e32 v103, v167
	v_cndmask_b32_e32 v166, 0, v160, vcc
	v_mul_f32_e32 v167, 0x3e0293ee, v97
	v_add_f32_e32 v165, v115, v165
	v_ldexp_f32 v103, v103, v166
	v_mul_f32_e32 v166, 0x3e0293ee, v96
	v_cmp_gt_f32_e32 vcc, s33, v166
	v_add_f32_e32 v165, v100, v165
	v_add_f32_e32 v165, v101, v165
	v_cndmask_b32_e32 v166, 0, v159, vcc
	v_fmac_f32_e32 v166, 0x3e0293ee, v96
	v_exp_f32_e32 v96, v166
	v_cndmask_b32_e32 v166, 0, v160, vcc
	v_cmp_gt_f32_e32 vcc, s33, v167
	v_add_f32_e32 v165, v102, v165
	v_add_f32_e32 v165, v103, v165
	v_cndmask_b32_e32 v167, 0, v159, vcc
	v_fmac_f32_e32 v167, 0x3e0293ee, v97
	v_exp_f32_e32 v97, v167
	v_ldexp_f32 v166, v96, v166
	v_add_f32_e32 v96, v166, v165
	v_cndmask_b32_e32 v165, 0, v160, vcc
	v_ldexp_f32 v165, v97, v165
	v_sub_f32_e32 v97, v98, v164
	v_mul_f32_e32 v98, 0x3e0293ee, v97
	v_cmp_gt_f32_e32 vcc, s33, v98
	v_sub_f32_e32 v99, v99, v164
	v_mul_f32_e32 v167, 0x3e0293ee, v99
	v_cndmask_b32_e32 v98, 0, v159, vcc
	v_fmac_f32_e32 v98, 0x3e0293ee, v97
	v_exp_f32_e32 v97, v98
	v_cndmask_b32_e32 v98, 0, v160, vcc
	v_cmp_gt_f32_e32 vcc, s33, v167
	v_sub_f32_e32 v88, v88, v164
	v_sub_f32_e32 v89, v89, v164
	v_cndmask_b32_e32 v167, 0, v159, vcc
; __device__ __forceinline__ u32x2 pack4(f32x4 v) { u32x2 r; r.x = cvt_pk(v[0], v[1]); r.y = cvt_pk(v[2], v[3]); return r; }
; __device__ __forceinline__ float shfl_xor_f(float v, int mask) { const int l = lane_fresh(); return __int_as_float(__builtin_amdgcn_ds_bpermute((l ^ mask) << 2, __float_as_int(v))); }
; __device__ __forceinline__ void attn_prompt_item(const Params& p, int item, const int wv, unsigned* bar) {
;     ...
;     float mx = -1e30f;
; #pragma unroll
;     for (int mb = 0; mb < 16; ++mb) mx = fmaxf(mx, fmaxf(fmaxf(s[mb][qb][0], s[mb][qb][1]), fmaxf(s[mb][qb][2], s[mb][qb][3])));
;     mx = fmaxf(mx, shfl_xor_f(mx, 16)); mx = fmaxf(mx, shfl_xor_f(mx, 32));
;     float sum = 0.f;
; #pragma unroll
;     for (int mb = 0; mb < 16; ++mb)
; #pragma unroll
;       for (int e = 0; e < 4; ++e) { float pv = exp2f((s[mb][qb][e] - mx) * cexp); s[mb][qb][e] = pv; sum += pv; }
;     sum += shfl_xor_f(sum, 16); sum += shfl_xor_f(sum, 32);
;     inv[qb] = 1.f / sum;
; #pragma unroll
;     for (int st = 0; st < 8; ++st) {
;       u32x2 lo = pack4(s[2 * st][qb]), hi = pack4(s[2 * st + 1][qb]);
;       u32x4 w = {lo.x, lo.y, hi.x, hi.y};
;       pf[qb][st] = __builtin_bit_cast(bf16x8, w);
;     }
;   }
	v_fmac_f32_e32 v167, 0x3e0293ee, v99
	v_exp_f32_e32 v99, v167
	v_ldexp_f32 v167, v97, v98
	v_cndmask_b32_e32 v97, 0, v160, vcc
	v_mul_f32_e32 v98, 0x3e0293ee, v89
	v_ldexp_f32 v99, v99, v97
	v_mul_f32_e32 v97, 0x3e0293ee, v88
	v_cmp_gt_f32_e32 vcc, s33, v97
	v_add_f32_e32 v96, v165, v96
	v_add_f32_e32 v96, v167, v96
	v_cndmask_b32_e32 v97, 0, v159, vcc
	v_fmac_f32_e32 v97, 0x3e0293ee, v88
	v_exp_f32_e32 v88, v97
	v_cndmask_b32_e32 v97, 0, v160, vcc
	v_cmp_gt_f32_e32 vcc, s33, v98
	v_add_f32_e32 v96, v99, v96
	v_ldexp_f32 v168, v88, v97
	v_cndmask_b32_e32 v98, 0, v159, vcc
	v_fmac_f32_e32 v98, 0x3e0293ee, v89
	v_exp_f32_e32 v89, v98
	v_add_f32_e32 v88, v168, v96
	v_cndmask_b32_e32 v96, 0, v160, vcc
	v_sub_f32_e32 v91, v91, v164
	v_ldexp_f32 v169, v89, v96
	v_sub_f32_e32 v89, v90, v164
	v_mul_f32_e32 v90, 0x3e0293ee, v89
	v_cmp_gt_f32_e32 vcc, s33, v90
	v_mul_f32_e32 v96, 0x3e0293ee, v91
	v_sub_f32_e32 v84, v84, v164
	v_cndmask_b32_e32 v90, 0, v159, vcc
	v_fmac_f32_e32 v90, 0x3e0293ee, v89
	v_exp_f32_e32 v89, v90
	v_cndmask_b32_e32 v90, 0, v160, vcc
	v_cmp_gt_f32_e32 vcc, s33, v96
	v_sub_f32_e32 v85, v85, v164
	v_ldexp_f32 v170, v89, v90
	v_cndmask_b32_e32 v96, 0, v159, vcc
	v_fmac_f32_e32 v96, 0x3e0293ee, v91
	v_exp_f32_e32 v91, v96
	v_cndmask_b32_e32 v89, 0, v160, vcc
	v_mul_f32_e32 v90, 0x3e0293ee, v85
	v_add_f32_e32 v88, v169, v88
	v_ldexp_f32 v171, v91, v89
	v_mul_f32_e32 v89, 0x3e0293ee, v84
	v_cmp_gt_f32_e32 vcc, s33, v89
	v_add_f32_e32 v88, v170, v88
	v_add_f32_e32 v88, v171, v88
	v_cndmask_b32_e32 v89, 0, v159, vcc
	v_fmac_f32_e32 v89, 0x3e0293ee, v84
	v_exp_f32_e32 v84, v89
	v_cndmask_b32_e32 v89, 0, v160, vcc
	v_cmp_gt_f32_e32 vcc, s33, v90
	v_sub_f32_e32 v87, v87, v164
	v_ldexp_f32 v172, v84, v89
	v_cndmask_b32_e32 v90, 0, v159, vcc
	v_fmac_f32_e32 v90, 0x3e0293ee, v85
	v_exp_f32_e32 v85, v90
	v_add_f32_e32 v84, v172, v88
	v_cndmask_b32_e32 v88, 0, v160, vcc
	v_mfma_f32_16x16x32_bf16 v[0:3], v[188:191], v[28:31], v[0:3]
	v_ldexp_f32 v173, v85, v88
	v_sub_f32_e32 v85, v86, v164
	v_mul_f32_e32 v86, 0x3e0293ee, v85
	v_cmp_gt_f32_e32 vcc, s33, v86
	v_mul_f32_e32 v88, 0x3e0293ee, v87
	v_mfma_f32_16x16x32_bf16 v[0:3], v[192:195], v[36:39], v[0:3]
	v_cndmask_b32_e32 v86, 0, v159, vcc
	v_fmac_f32_e32 v86, 0x3e0293ee, v85
	v_exp_f32_e32 v85, v86
	v_cndmask_b32_e32 v86, 0, v160, vcc
	v_cmp_gt_f32_e32 vcc, s33, v88
	v_add_f32_e32 v84, v173, v84
	v_ldexp_f32 v164, v85, v86
	v_cndmask_b32_e32 v88, 0, v159, vcc
	v_fmac_f32_e32 v88, 0x3e0293ee, v87
	v_exp_f32_e32 v87, v88
	v_cndmask_b32_e32 v85, 0, v160, vcc
	v_add_f32_e32 v84, v164, v84
	v_mfma_f32_16x16x32_bf16 v[4:7], v[196:199], v[48:51], v[0:3]
	v_ldexp_f32 v174, v87, v85
	v_mbcnt_lo_u32_b32 v85, -1, 0
	v_mbcnt_hi_u32_b32 v85, -1, v85
	v_add_f32_e32 v84, v174, v84
	v_lshlrev_b32_e32 v85, 2, v85
	v_mfma_f32_16x16x32_bf16 v[0:3], v[200:203], v[92:95], 0
	v_xor_b32_e32 v85, 64, v85
	ds_bpermute_b32 v85, v85, v84
	v_cvt_pk_bf16_f32 v89, v142, v143
	v_mfma_f32_16x16x32_bf16 v[92:95], v[216:219], v[92:95], 0
	v_cvt_pk_bf16_f32 v90, v136, v137
	v_cvt_pk_bf16_f32 v87, v130, v131
	v_cvt_pk_bf16_f32 v88, v140, v141
	v_mfma_f32_16x16x32_bf16 v[0:3], v[204:207], v[28:31], v[0:3]
	v_cvt_pk_bf16_f32 v91, v138, v139
	v_cvt_pk_bf16_f32 v86, v128, v129
	v_mfma_f32_16x16x32_bf16 v[28:31], v[80:83], v[28:31], v[92:95]
	v_mbcnt_lo_u32_b32 v81, -1, 0
	v_mbcnt_hi_u32_b32 v81, -1, v81
	s_waitcnt lgkmcnt(0)
	v_add_f32_e32 v80, v84, v85
	v_lshlrev_b32_e32 v81, 2, v81
	v_xor_b32_e32 v81, 0x80, v81
	ds_bpermute_b32 v81, v81, v80
	v_mfma_f32_16x16x32_bf16 v[0:3], v[208:211], v[36:39], v[0:3]
	v_cvt_pk_bf16_f32 v93, v150, v151
	v_cvt_pk_bf16_f32 v92, v148, v149
	v_cvt_pk_bf16_f32 v94, v144, v145
	s_waitcnt lgkmcnt(0)
	v_add_f32_e32 v96, v80, v81
	v_div_scale_f32 v98, s[14:15], v96, v96, 1.0
	v_rcp_f32_e32 v97, v98
	v_mfma_f32_16x16x32_bf16 v[28:31], v[64:67], v[36:39], v[28:31]
	v_max_f32_e32 v37, v78, v78
	v_max_f32_e32 v38, v74, v74
	v_fma_f32 v36, -v98, v97, 1.0
	v_fmac_f32_e32 v97, v36, v97
	v_max_f32_e32 v36, v79, v79
	v_max_f32_e32 v36, v37, v36
	v_max_f32_e32 v37, v75, v75
	v_max_f32_e32 v37, v38, v37
	v_max3_f32 v36, v76, v77, v36
	v_max3_f32 v37, v72, v73, v37
	v_max3_f32 v36, v36, s31, v37
	v_max_f32_e32 v37, v71, v71
	v_max_f32_e32 v38, v70, v70
	v_max_f32_e32 v37, v38, v37
	v_max_f32_e32 v38, v63, v63
	v_max_f32_e32 v39, v62, v62
	v_max_f32_e32 v38, v39, v38
	v_max3_f32 v37, v68, v69, v37
	v_max3_f32 v38, v60, v61, v38
	v_max3_f32 v36, v36, v37, v38
	v_max_f32_e32 v37, v59, v59
	v_max_f32_e32 v38, v58, v58
	v_max_f32_e32 v37, v38, v37
	v_max_f32_e32 v38, v47, v47
	v_max_f32_e32 v39, v46, v46
	v_max_f32_e32 v38, v39, v38
	v_max3_f32 v37, v56, v57, v37
	v_max3_f32 v38, v44, v45, v38
	v_max3_f32 v36, v36, v37, v38
	v_max_f32_e32 v37, v43, v43
	v_max_f32_e32 v38, v42, v42
	v_max_f32_e32 v37, v38, v37
	v_max_f32_e32 v38, v35, v35
	v_max_f32_e32 v39, v34, v34
	v_max_f32_e32 v38, v39, v38
	v_max3_f32 v37, v40, v41, v37
	v_max3_f32 v38, v32, v33, v38
	v_max3_f32 v36, v36, v37, v38
	v_max_f32_e32 v37, v27, v27
	v_max_f32_e32 v38, v26, v26
	v_max_f32_e32 v37, v38, v37
	v_max_f32_e32 v38, v23, v23
	v_max_f32_e32 v39, v22, v22
	v_max_f32_e32 v38, v39, v38
	v_max3_f32 v37, v24, v25, v37
	v_max3_f32 v38, v20, v21, v38
	v_max3_f32 v36, v36, v37, v38
	v_max_f32_e32 v37, v15, v15
	v_max_f32_e32 v38, v14, v14
	v_max_f32_e32 v37, v38, v37
	v_max_f32_e32 v38, v11, v11
	v_max_f32_e32 v39, v10, v10
	v_max_f32_e32 v38, v39, v38
	v_max3_f32 v37, v12, v13, v37
	v_max3_f32 v38, v8, v9, v38
	v_mfma_f32_16x16x32_bf16 v[0:3], v[212:215], v[48:51], v[0:3]
	v_max3_f32 v36, v36, v37, v38
	v_max_f32_e32 v37, v19, v19
	v_max_f32_e32 v38, v18, v18
	v_mfma_f32_16x16x32_bf16 v[28:31], v[52:55], v[48:51], v[28:31]
	v_max_f32_e32 v37, v38, v37
	v_max_f32_e32 v38, v7, v7
	v_max_f32_e32 v39, v6, v6
	v_max_f32_e32 v38, v39, v38
	v_max3_f32 v37, v16, v17, v37
	v_max3_f32 v38, v4, v5, v38
	v_max3_f32 v36, v36, v37, v38
	v_max_f32_e32 v37, v3, v3
	v_max_f32_e32 v38, v2, v2
	v_max_f32_e32 v37, v38, v37
	v_max_f32_e32 v38, v31, v31
	v_max_f32_e32 v39, v30, v30
	v_max_f32_e32 v38, v39, v38
	v_max3_f32 v37, v0, v1, v37
	v_max3_f32 v38, v28, v29, v38
	v_max3_f32 v36, v36, v37, v38
	v_mbcnt_lo_u32_b32 v37, -1, 0
	v_mbcnt_hi_u32_b32 v37, -1, v37
	v_cvt_pk_bf16_f32 v55, v167, v99
	v_lshlrev_b32_e32 v37, 2, v37
	v_xor_b32_e32 v37, 64, v37
	ds_bpermute_b32 v37, v37, v36
	v_cvt_pk_bf16_f32 v52, v100, v101
	v_cvt_pk_bf16_f32 v53, v102, v103
	v_cvt_pk_bf16_f32 v49, v106, v107
	v_cvt_pk_bf16_f32 v66, v108, v109
	s_waitcnt lgkmcnt(0)
; __device__ __forceinline__ float shfl_xor_f(float v, int mask) { const int l = lane_fresh(); return __int_as_float(__builtin_amdgcn_ds_bpermute((l ^ mask) << 2, __float_as_int(v))); }
; __device__ __forceinline__ void attn_prompt_item(const Params& p, int item, const int wv, unsigned* bar) {
;     ...
;     float mx = -1e30f;
; #pragma unroll
;     for (int mb = 0; mb < 16; ++mb) mx = fmaxf(mx, fmaxf(fmaxf(s[mb][qb][0], s[mb][qb][1]), fmaxf(s[mb][qb][2], s[mb][qb][3])));
;     mx = fmaxf(mx, shfl_xor_f(mx, 16)); mx = fmaxf(mx, shfl_xor_f(mx, 32));
;     float sum = 0.f;
; #pragma unroll
;     for (int mb = 0; mb < 16; ++mb)
; #pragma unroll
;       for (int e = 0; e < 4; ++e) { float pv = exp2f((s[mb][qb][e] - mx) * cexp); s[mb][qb][e] = pv; sum += pv; }
;     sum += shfl_xor_f(sum, 16); sum += shfl_xor_f(sum, 32);
;     inv[qb] = 1.f / sum;
	v_max_f32_e32 v37, v37, v37
	v_max_f32_e32 v38, v36, v37
	v_mbcnt_lo_u32_b32 v36, -1, 0
	v_mbcnt_hi_u32_b32 v36, -1, v36
	v_cvt_pk_bf16_f32 v48, v104, v105
	v_lshlrev_b32_e32 v36, 2, v36
	v_xor_b32_e32 v36, 0x80, v36
	ds_bpermute_b32 v39, v36, v38
	v_cvt_pk_bf16_f32 v95, v146, v147
	v_cvt_pk_bf16_f32 v84, v132, v133
	v_cvt_pk_bf16_f32 v85, v134, v135
	v_cvt_pk_bf16_f32 v80, v124, v125
	s_waitcnt lgkmcnt(0)
	v_max_f32_e32 v39, v39, v39
	v_max_f32_e32 v99, v38, v39
	v_sub_f32_e32 v38, v76, v99
	v_mul_f32_e32 v39, 0x3e0293ee, v38
	v_cmp_gt_f32_e32 vcc, s33, v39
	v_sub_f32_e32 v78, v78, v99
	v_mul_f32_e32 v101, 0x3e0293ee, v78
	v_cndmask_b32_e32 v39, 0, v159, vcc
	v_fmac_f32_e32 v39, 0x3e0293ee, v38
	v_exp_f32_e32 v76, v39
	v_cndmask_b32_e32 v100, 0, v160, vcc
	v_sub_f32_e32 v79, v79, v99
	v_sub_f32_e32 v72, v72, v99
	v_ldexp_f32 v100, v76, v100
	v_sub_f32_e32 v76, v77, v99
	v_mul_f32_e32 v77, 0x3e0293ee, v76
	v_cmp_gt_f32_e32 vcc, s33, v77
	v_mul_f32_e32 v102, 0x3e0293ee, v72
	v_sub_f32_e32 v73, v73, v99
	v_cndmask_b32_e32 v77, 0, v159, vcc
	v_fmac_f32_e32 v77, 0x3e0293ee, v76
	v_exp_f32_e32 v76, v77
	v_cndmask_b32_e32 v77, 0, v160, vcc
	v_cmp_gt_f32_e32 vcc, s33, v101
	v_sub_f32_e32 v74, v74, v99
	v_sub_f32_e32 v75, v75, v99
	v_cndmask_b32_e32 v101, 0, v159, vcc
	v_fmac_f32_e32 v101, 0x3e0293ee, v78
	v_exp_f32_e32 v101, v101
	v_ldexp_f32 v78, v76, v77
	v_cndmask_b32_e32 v76, 0, v160, vcc
	v_add_f32_e32 v77, v100, v78
	v_ldexp_f32 v76, v101, v76
	v_mul_f32_e32 v101, 0x3e0293ee, v79
	v_cmp_gt_f32_e32 vcc, s33, v101
	v_add_f32_e32 v77, v76, v77
	v_sub_f32_e32 v68, v68, v99
	v_cndmask_b32_e32 v101, 0, v159, vcc
	v_fmac_f32_e32 v101, 0x3e0293ee, v79
	v_exp_f32_e32 v79, v101
	v_cndmask_b32_e32 v101, 0, v160, vcc
	v_cmp_gt_f32_e32 vcc, s33, v102
	v_sub_f32_e32 v69, v69, v99
	v_sub_f32_e32 v70, v70, v99
	v_cndmask_b32_e32 v102, 0, v159, vcc
	v_fmac_f32_e32 v102, 0x3e0293ee, v72
	v_exp_f32_e32 v102, v102
	v_ldexp_f32 v72, v79, v101
	v_mul_f32_e32 v101, 0x3e0293ee, v73
	v_add_f32_e32 v79, v72, v77
	v_cndmask_b32_e32 v77, 0, v160, vcc
	v_cmp_gt_f32_e32 vcc, s33, v101
	v_ldexp_f32 v77, v102, v77
	v_mul_f32_e32 v102, 0x3e0293ee, v74
	v_cndmask_b32_e32 v101, 0, v159, vcc
	v_fmac_f32_e32 v101, 0x3e0293ee, v73
	v_exp_f32_e32 v73, v101
	v_cndmask_b32_e32 v101, 0, v160, vcc
	v_cmp_gt_f32_e32 vcc, s33, v102
	v_add_f32_e32 v79, v77, v79
	v_sub_f32_e32 v71, v71, v99
	v_cndmask_b32_e32 v102, 0, v159, vcc
	v_fmac_f32_e32 v102, 0x3e0293ee, v74
	v_exp_f32_e32 v102, v102
	v_ldexp_f32 v74, v73, v101
	v_mul_f32_e32 v101, 0x3e0293ee, v75
	v_add_f32_e32 v73, v74, v79
	v_cndmask_b32_e32 v79, 0, v160, vcc
	v_cmp_gt_f32_e32 vcc, s33, v101
	v_ldexp_f32 v79, v102, v79
	v_mul_f32_e32 v102, 0x3e0293ee, v68
	v_cndmask_b32_e32 v101, 0, v159, vcc
	v_fmac_f32_e32 v101, 0x3e0293ee, v75
	v_exp_f32_e32 v75, v101
	v_cndmask_b32_e32 v101, 0, v160, vcc
	v_cmp_gt_f32_e32 vcc, s33, v102
	v_sub_f32_e32 v60, v60, v99
	v_ldexp_f32 v75, v75, v101
	v_cndmask_b32_e32 v102, 0, v159, vcc
	v_fmac_f32_e32 v102, 0x3e0293ee, v68
	v_exp_f32_e32 v68, v102
	v_cndmask_b32_e32 v101, 0, v160, vcc
	v_mul_f32_e32 v102, 0x3e0293ee, v70
	v_add_f32_e32 v73, v79, v73
	v_ldexp_f32 v68, v68, v101
	v_mul_f32_e32 v101, 0x3e0293ee, v69
	v_cmp_gt_f32_e32 vcc, s33, v101
	v_add_f32_e32 v73, v75, v73
	v_add_f32_e32 v73, v68, v73
	v_cndmask_b32_e32 v101, 0, v159, vcc
	v_fmac_f32_e32 v101, 0x3e0293ee, v69
	v_exp_f32_e32 v69, v101
	v_cndmask_b32_e32 v101, 0, v160, vcc
	v_cmp_gt_f32_e32 vcc, s33, v102
	v_sub_f32_e32 v61, v61, v99
	v_ldexp_f32 v69, v69, v101
	v_cndmask_b32_e32 v102, 0, v159, vcc
	v_fmac_f32_e32 v102, 0x3e0293ee, v70
	v_exp_f32_e32 v70, v102
	v_cndmask_b32_e32 v101, 0, v160, vcc
	v_mul_f32_e32 v102, 0x3e0293ee, v60
	v_add_f32_e32 v73, v69, v73
	v_ldexp_f32 v70, v70, v101
	v_mul_f32_e32 v101, 0x3e0293ee, v71
	v_cmp_gt_f32_e32 vcc, s33, v101
	v_add_f32_e32 v73, v70, v73
	v_sub_f32_e32 v62, v62, v99
	v_cndmask_b32_e32 v101, 0, v159, vcc
	v_fmac_f32_e32 v101, 0x3e0293ee, v71
	v_exp_f32_e32 v71, v101
	v_cndmask_b32_e32 v101, 0, v160, vcc
	v_cmp_gt_f32_e32 vcc, s33, v102
	v_sub_f32_e32 v63, v63, v99
	v_ldexp_f32 v71, v71, v101
	v_cndmask_b32_e32 v102, 0, v159, vcc
	v_fmac_f32_e32 v102, 0x3e0293ee, v60
	v_exp_f32_e32 v60, v102
	v_add_f32_e32 v101, v71, v73
	v_cndmask_b32_e32 v73, 0, v160, vcc
	v_mul_f32_e32 v102, 0x3e0293ee, v62
	v_ldexp_f32 v73, v60, v73
	v_add_f32_e32 v60, v73, v101
	v_mul_f32_e32 v101, 0x3e0293ee, v61
	v_cmp_gt_f32_e32 vcc, s33, v101
	v_sub_f32_e32 v56, v56, v99
	v_sub_f32_e32 v57, v57, v99
	v_cndmask_b32_e32 v101, 0, v159, vcc
	v_fmac_f32_e32 v101, 0x3e0293ee, v61
	v_exp_f32_e32 v61, v101
	v_cndmask_b32_e32 v101, 0, v160, vcc
	v_cmp_gt_f32_e32 vcc, s33, v102
	v_sub_f32_e32 v58, v58, v99
	v_ldexp_f32 v61, v61, v101
	v_cndmask_b32_e32 v102, 0, v159, vcc
	v_fmac_f32_e32 v102, 0x3e0293ee, v62
	v_exp_f32_e32 v62, v102
	v_cndmask_b32_e32 v101, 0, v160, vcc
	v_mul_f32_e32 v102, 0x3e0293ee, v56
	v_add_f32_e32 v60, v61, v60
	v_ldexp_f32 v62, v62, v101
	v_mul_f32_e32 v101, 0x3e0293ee, v63
	v_cmp_gt_f32_e32 vcc, s33, v101
	v_add_f32_e32 v60, v62, v60
	v_sub_f32_e32 v59, v59, v99
	v_cndmask_b32_e32 v101, 0, v159, vcc
	v_fmac_f32_e32 v101, 0x3e0293ee, v63
	v_exp_f32_e32 v63, v101
	v_cndmask_b32_e32 v101, 0, v160, vcc
	v_cmp_gt_f32_e32 vcc, s33, v102
	v_sub_f32_e32 v44, v44, v99
	v_ldexp_f32 v63, v63, v101
	v_cndmask_b32_e32 v102, 0, v159, vcc
	v_fmac_f32_e32 v102, 0x3e0293ee, v56
	v_exp_f32_e32 v56, v102
	v_add_f32_e32 v101, v63, v60
	v_cndmask_b32_e32 v60, 0, v160, vcc
	v_mul_f32_e32 v102, 0x3e0293ee, v58
	v_ldexp_f32 v60, v56, v60
	v_add_f32_e32 v56, v60, v101
	v_mul_f32_e32 v101, 0x3e0293ee, v57
; __device__ __forceinline__ u32x2 pack4(f32x4 v) { u32x2 r; r.x = cvt_pk(v[0], v[1]); r.y = cvt_pk(v[2], v[3]); return r; }
; __device__ __forceinline__ float shfl_xor_f(float v, int mask) { const int l = lane_fresh(); return __int_as_float(__builtin_amdgcn_ds_bpermute((l ^ mask) << 2, __float_as_int(v))); }
; __device__ __forceinline__ void attn_prompt_item(const Params& p, int item, const int wv, unsigned* bar) {
;     ...
;     for (int mb = 0; mb < 16; ++mb)
; #pragma unroll
;       for (int e = 0; e < 4; ++e) { float pv = exp2f((s[mb][qb][e] - mx) * cexp); s[mb][qb][e] = pv; sum += pv; }
;     sum += shfl_xor_f(sum, 16); sum += shfl_xor_f(sum, 32);
;     inv[qb] = 1.f / sum;
; #pragma unroll
;     for (int st = 0; st < 8; ++st) {
;       u32x2 lo = pack4(s[2 * st][qb]), hi = pack4(s[2 * st + 1][qb]);
;       u32x4 w = {lo.x, lo.y, hi.x, hi.y};
;       pf[qb][st] = __builtin_bit_cast(bf16x8, w);
;     }
	v_cmp_gt_f32_e32 vcc, s33, v101
	v_sub_f32_e32 v45, v45, v99
	v_sub_f32_e32 v46, v46, v99
	v_cndmask_b32_e32 v101, 0, v159, vcc
	v_fmac_f32_e32 v101, 0x3e0293ee, v57
	v_exp_f32_e32 v57, v101
	v_cndmask_b32_e32 v101, 0, v160, vcc
	v_cmp_gt_f32_e32 vcc, s33, v102
	v_sub_f32_e32 v47, v47, v99
	v_sub_f32_e32 v40, v40, v99
	v_cndmask_b32_e32 v102, 0, v159, vcc
	v_fmac_f32_e32 v102, 0x3e0293ee, v58
	v_exp_f32_e32 v102, v102
	v_ldexp_f32 v58, v57, v101
	v_mul_f32_e32 v101, 0x3e0293ee, v59
	v_add_f32_e32 v57, v58, v56
	v_cndmask_b32_e32 v56, 0, v160, vcc
	v_cmp_gt_f32_e32 vcc, s33, v101
	v_ldexp_f32 v56, v102, v56
	v_mul_f32_e32 v102, 0x3e0293ee, v44
	v_cndmask_b32_e32 v101, 0, v159, vcc
	v_fmac_f32_e32 v101, 0x3e0293ee, v59
	v_exp_f32_e32 v59, v101
	v_cndmask_b32_e32 v101, 0, v160, vcc
	v_cmp_gt_f32_e32 vcc, s33, v102
	v_add_f32_e32 v57, v56, v57
	v_sub_f32_e32 v41, v41, v99
	v_cndmask_b32_e32 v102, 0, v159, vcc
	v_fmac_f32_e32 v102, 0x3e0293ee, v44
	v_exp_f32_e32 v102, v102
	v_ldexp_f32 v44, v59, v101
	v_mul_f32_e32 v101, 0x3e0293ee, v45
	v_add_f32_e32 v59, v44, v57
	v_cndmask_b32_e32 v57, 0, v160, vcc
	v_cmp_gt_f32_e32 vcc, s33, v101
	v_ldexp_f32 v57, v102, v57
	v_mul_f32_e32 v102, 0x3e0293ee, v46
	v_cndmask_b32_e32 v101, 0, v159, vcc
	v_fmac_f32_e32 v101, 0x3e0293ee, v45
	v_exp_f32_e32 v45, v101
	v_cndmask_b32_e32 v101, 0, v160, vcc
	v_cmp_gt_f32_e32 vcc, s33, v102
	v_add_f32_e32 v59, v57, v59
	v_ldexp_f32 v45, v45, v101
	v_cndmask_b32_e32 v102, 0, v159, vcc
	v_fmac_f32_e32 v102, 0x3e0293ee, v46
	v_exp_f32_e32 v46, v102
	v_cndmask_b32_e32 v101, 0, v160, vcc
	v_add_f32_e32 v59, v45, v59
	v_mul_f32_e32 v102, 0x3e0293ee, v40
	v_ldexp_f32 v46, v46, v101
	v_add_f32_e32 v101, v46, v59
	v_mul_f32_e32 v59, 0x3e0293ee, v47
	v_cmp_gt_f32_e32 vcc, s33, v59
	v_sub_f32_e32 v42, v42, v99
	v_sub_f32_e32 v43, v43, v99
	v_cndmask_b32_e32 v59, 0, v159, vcc
	v_fmac_f32_e32 v59, 0x3e0293ee, v47
	v_exp_f32_e32 v47, v59
	v_cndmask_b32_e32 v59, 0, v160, vcc
	v_cmp_gt_f32_e32 vcc, s33, v102
	v_sub_f32_e32 v32, v32, v99
	v_ldexp_f32 v59, v47, v59
	v_cndmask_b32_e32 v102, 0, v159, vcc
	v_fmac_f32_e32 v102, 0x3e0293ee, v40
	v_exp_f32_e32 v40, v102
	v_add_f32_e32 v47, v59, v101
	v_cndmask_b32_e32 v101, 0, v160, vcc
	v_mul_f32_e32 v102, 0x3e0293ee, v42
	v_ldexp_f32 v40, v40, v101
	v_mul_f32_e32 v101, 0x3e0293ee, v41
	v_cmp_gt_f32_e32 vcc, s33, v101
	v_sub_f32_e32 v33, v33, v99
	v_sub_f32_e32 v34, v34, v99
	v_cndmask_b32_e32 v101, 0, v159, vcc
	v_fmac_f32_e32 v101, 0x3e0293ee, v41
	v_exp_f32_e32 v41, v101
	v_cndmask_b32_e32 v101, 0, v160, vcc
	v_cmp_gt_f32_e32 vcc, s33, v102
	v_add_f32_e32 v47, v40, v47
	v_ldexp_f32 v41, v41, v101
	v_cndmask_b32_e32 v102, 0, v159, vcc
	v_fmac_f32_e32 v102, 0x3e0293ee, v42
	v_exp_f32_e32 v42, v102
	v_cndmask_b32_e32 v101, 0, v160, vcc
	v_mul_f32_e32 v102, 0x3e0293ee, v32
	v_add_f32_e32 v47, v41, v47
	v_ldexp_f32 v42, v42, v101
	v_mul_f32_e32 v101, 0x3e0293ee, v43
	v_cmp_gt_f32_e32 vcc, s33, v101
	v_add_f32_e32 v47, v42, v47
	v_sub_f32_e32 v35, v35, v99
	v_cndmask_b32_e32 v101, 0, v159, vcc
	v_fmac_f32_e32 v101, 0x3e0293ee, v43
	v_exp_f32_e32 v43, v101
	v_cndmask_b32_e32 v101, 0, v160, vcc
	v_cmp_gt_f32_e32 vcc, s33, v102
	v_sub_f32_e32 v24, v24, v99
	v_sub_f32_e32 v25, v25, v99
	v_cndmask_b32_e32 v102, 0, v159, vcc
	v_fmac_f32_e32 v102, 0x3e0293ee, v32
	v_exp_f32_e32 v102, v102
	v_ldexp_f32 v32, v43, v101
	v_mul_f32_e32 v101, 0x3e0293ee, v33
	v_cndmask_b32_e32 v43, 0, v160, vcc
	v_cmp_gt_f32_e32 vcc, s33, v101
	v_ldexp_f32 v43, v102, v43
	v_mul_f32_e32 v102, 0x3e0293ee, v34
	v_cndmask_b32_e32 v101, 0, v159, vcc
	v_fmac_f32_e32 v101, 0x3e0293ee, v33
	v_exp_f32_e32 v33, v101
	v_cndmask_b32_e32 v101, 0, v160, vcc
	v_cmp_gt_f32_e32 vcc, s33, v102
	v_add_f32_e32 v47, v32, v47
	v_add_f32_e32 v47, v43, v47
	v_cndmask_b32_e32 v102, 0, v159, vcc
	v_fmac_f32_e32 v102, 0x3e0293ee, v34
	v_exp_f32_e32 v102, v102
	v_ldexp_f32 v34, v33, v101
	v_mul_f32_e32 v101, 0x3e0293ee, v35
	v_add_f32_e32 v33, v34, v47
	v_cndmask_b32_e32 v47, 0, v160, vcc
	v_cmp_gt_f32_e32 vcc, s33, v101
	v_ldexp_f32 v47, v102, v47
	v_mul_f32_e32 v102, 0x3e0293ee, v24
	v_cndmask_b32_e32 v101, 0, v159, vcc
	v_fmac_f32_e32 v101, 0x3e0293ee, v35
	v_exp_f32_e32 v35, v101
	v_cndmask_b32_e32 v101, 0, v160, vcc
	v_cmp_gt_f32_e32 vcc, s33, v102
	v_add_f32_e32 v33, v47, v33
	v_ldexp_f32 v35, v35, v101
	v_cndmask_b32_e32 v102, 0, v159, vcc
	v_fmac_f32_e32 v102, 0x3e0293ee, v24
	v_exp_f32_e32 v24, v102
	v_add_f32_e32 v106, v35, v33
	v_cndmask_b32_e32 v33, 0, v160, vcc
	v_sub_f32_e32 v26, v26, v99
	v_ldexp_f32 v24, v24, v33
	v_mul_f32_e32 v33, 0x3e0293ee, v25
	v_cmp_gt_f32_e32 vcc, s33, v33
	v_add_f32_e32 v106, v24, v106
	v_sub_f32_e32 v27, v27, v99
	v_cndmask_b32_e32 v33, 0, v159, vcc
	v_fmac_f32_e32 v33, 0x3e0293ee, v25
	v_exp_f32_e32 v107, v33
	v_cndmask_b32_e32 v108, 0, v160, vcc
	v_sub_f32_e32 v20, v20, v99
	v_sub_f32_e32 v21, v21, v99
	v_ldexp_f32 v150, v107, v108
	v_cvt_pk_bf16_f32 v107, v76, v72
	v_mul_f32_e32 v72, 0x3e0293ee, v26
	v_cmp_gt_f32_e32 vcc, s33, v72
	v_add_f32_e32 v142, v150, v106
	v_cvt_pk_bf16_f32 v106, v100, v78
	v_cndmask_b32_e32 v72, 0, v159, vcc
	v_fmac_f32_e32 v72, 0x3e0293ee, v26
	v_mul_f32_e32 v78, 0x3e0293ee, v27
	v_exp_f32_e32 v26, v72
	v_cndmask_b32_e32 v72, 0, v160, vcc
	v_cmp_gt_f32_e32 vcc, s33, v78
	v_mul_u32_u24_e32 v101, 0x210, v163
	v_ldexp_f32 v26, v26, v72
	v_cndmask_b32_e32 v78, 0, v159, vcc
	v_fmac_f32_e32 v78, 0x3e0293ee, v27
	v_exp_f32_e32 v27, v78
	v_cndmask_b32_e32 v78, 0, v160, vcc
	v_add_f32_e32 v72, v26, v142
	v_add3_u32 v101, s29, v152, v101
	v_ldexp_f32 v27, v27, v78
	v_mul_f32_e32 v78, 0x3e0293ee, v20
	v_cmp_gt_f32_e32 vcc, s33, v78
; __device__ __forceinline__ u32x2 pack4(f32x4 v) { u32x2 r; r.x = cvt_pk(v[0], v[1]); r.y = cvt_pk(v[2], v[3]); return r; }
; __device__ __forceinline__ float shfl_xor_f(float v, int mask) { const int l = lane_fresh(); return __int_as_float(__builtin_amdgcn_ds_bpermute((l ^ mask) << 2, __float_as_int(v))); }
; #define MFMA16(a, b, c) __builtin_amdgcn_mfma_f32_16x16x32_bf16((a), (b), (c), 0, 0, 0)
; __device__ __forceinline__ void attn_prompt_item(const Params& p, int item, const int wv, unsigned* bar) {
;     ...
;     for (int mb = 0; mb < 16; ++mb)
; #pragma unroll
;       for (int e = 0; e < 4; ++e) { float pv = exp2f((s[mb][qb][e] - mx) * cexp); s[mb][qb][e] = pv; sum += pv; }
;     sum += shfl_xor_f(sum, 16); sum += shfl_xor_f(sum, 32);
;     inv[qb] = 1.f / sum;
; #pragma unroll
;     for (int st = 0; st < 8; ++st) {
;       u32x2 lo = pack4(s[2 * st][qb]), hi = pack4(s[2 * st + 1][qb]);
;       u32x4 w = {lo.x, lo.y, hi.x, hi.y};
;       pf[qb][st] = __builtin_bit_cast(bf16x8, w);
;     }
;   }
;   f32x4 o[8][2];
; #pragma unroll
;   for (int db = 0; db < 8; ++db) { o[db][0] = (f32x4){0.f, 0.f, 0.f, 0.f}; o[db][1] = (f32x4){0.f, 0.f, 0.f, 0.f}; }
; #pragma unroll
;   for (int st = 0; st < 8; ++st)
; #pragma unroll
;     for (int db = 0; db < 8; ++db) {
;       bf16x8 vf = *(const bf16x8*)(VT_l + (db * 16 + fr) * 264 + st * 32 + fq * 8);
;       o[db][0] = MFMA16(vf, pf[0][st], o[db][0]);
;       o[db][1] = MFMA16(vf, pf[1][st], o[db][1]);
;     }
	v_add_f32_e32 v72, v27, v72
	v_mbcnt_lo_u32_b32 v33, -1, 0
	v_mbcnt_hi_u32_b32 v33, -1, v33
	v_mbcnt_lo_u32_b32 v25, -1, 0
	v_mbcnt_hi_u32_b32 v25, -1, v25
	ds_read_b128 v[102:105], v101
	v_cndmask_b32_e32 v78, 0, v159, vcc
	v_fmac_f32_e32 v78, 0x3e0293ee, v20
	v_exp_f32_e32 v20, v78
	v_cndmask_b32_e32 v78, 0, v160, vcc
	v_cvt_pk_bf16_f32 v68, v68, v69
	v_cvt_pk_bf16_f32 v69, v70, v71
	v_ldexp_f32 v100, v20, v78
	v_add_f32_e32 v20, v100, v72
	v_mul_f32_e32 v72, 0x3e0293ee, v21
	v_cmp_gt_f32_e32 vcc, s33, v72
	v_cvt_pk_bf16_f32 v71, v62, v63
	v_sub_f32_e32 v62, v23, v99
	v_cndmask_b32_e32 v72, 0, v159, vcc
	v_fmac_f32_e32 v72, 0x3e0293ee, v21
	v_exp_f32_e32 v21, v72
	v_cndmask_b32_e32 v78, 0, v160, vcc
	v_mul_f32_e32 v63, 0x3e0293ee, v62
	v_cvt_pk_bf16_f32 v70, v73, v61
	v_ldexp_f32 v151, v21, v78
	v_sub_f32_e32 v21, v22, v99
	v_mul_f32_e32 v22, 0x3e0293ee, v21
	v_cmp_gt_f32_e32 vcc, s33, v22
	v_add_f32_e32 v61, v151, v20
	v_cvt_pk_bf16_f32 v108, v77, v74
	v_cndmask_b32_e32 v22, 0, v159, vcc
	v_cndmask_b32_e32 v20, 0, v160, vcc
	v_cmp_gt_f32_e32 vcc, s33, v63
	v_cvt_pk_bf16_f32 v109, v79, v75
	v_sub_f32_e32 v12, v12, v99
	v_cndmask_b32_e32 v63, 0, v159, vcc
	v_fmac_f32_e32 v63, 0x3e0293ee, v62
	v_exp_f32_e32 v62, v63
	v_cndmask_b32_e32 v63, 0, v160, vcc
	v_cvt_pk_bf16_f32 v82, v120, v121
	v_cvt_pk_bf16_f32 v83, v122, v123
	v_cvt_pk_bf16_f32 v64, v116, v117
	v_cvt_pk_bf16_f32 v65, v118, v119
	v_cvt_pk_bf16_f32 v67, v110, v111
	v_cvt_pk_bf16_f32 v50, v112, v113
	v_cvt_pk_bf16_f32 v51, v114, v115
	v_cvt_pk_bf16_f32 v54, v166, v165
	v_cvt_pk_bf16_f32 v36, v168, v169
	v_cvt_pk_bf16_f32 v37, v170, v171
	v_cvt_pk_bf16_f32 v38, v172, v173
	v_cvt_pk_bf16_f32 v39, v164, v174
	ds_read_b128 v[110:113], v101 offset:8448
	ds_read_b128 v[114:117], v101 offset:64
	s_waitcnt lgkmcnt(2)
	v_mfma_f32_16x16x32_bf16 v[118:121], v[102:105], v[92:95], 0
	v_ldexp_f32 v163, v62, v63
	v_mul_f32_e32 v62, 0x3e0293ee, v12
	v_cmp_gt_f32_e32 vcc, s33, v62
	v_mfma_f32_16x16x32_bf16 v[74:77], v[102:105], v[106:109], 0
	ds_read_b128 v[102:105], v101 offset:16896
	ds_read_b128 v[122:125], v101 offset:8512
	ds_read_b128 v[130:133], v101 offset:25344
	ds_read_b128 v[134:137], v101 offset:16960
	ds_read_b128 v[142:145], v101 offset:25408
	ds_read_b128 v[164:167], v101 offset:33792
	ds_read_b128 v[168:171], v101 offset:42240
	ds_read_b128 v[172:175], v101 offset:33856
	v_cndmask_b32_e32 v62, 0, v159, vcc
	ds_read_b128 v[180:183], v101 offset:50688
	ds_read_b128 v[184:187], v101 offset:42304
	v_fmac_f32_e32 v22, 0x3e0293ee, v21
	v_fmac_f32_e32 v62, 0x3e0293ee, v12
	s_waitcnt lgkmcnt(9)
	v_mfma_f32_16x16x32_bf16 v[138:141], v[102:105], v[92:95], 0
	v_exp_f32_e32 v21, v22
	v_exp_f32_e32 v12, v62
	v_cndmask_b32_e32 v62, 0, v160, vcc
	v_mfma_f32_16x16x32_bf16 v[102:105], v[102:105], v[106:109], 0
	v_ldexp_f32 v152, v21, v20
	v_add_f32_e32 v61, v152, v61
	v_add_f32_e32 v61, v163, v61
	s_waitcnt lgkmcnt(3)
	v_mfma_f32_16x16x32_bf16 v[188:191], v[168:171], v[92:95], 0
	ds_read_b128 v[192:195], v101 offset:59136
	ds_read_b128 v[196:199], v101 offset:50752
	ds_read_b128 v[204:207], v101 offset:59200
	v_cvt_pk_bf16_f32 v63, v46, v59
	v_mfma_f32_16x16x32_bf16 v[118:121], v[114:117], v[88:91], v[118:121]
	v_cvt_pk_bf16_f32 v81, v126, v127
	v_sub_f32_e32 v8, v8, v99
	v_cvt_pk_bf16_f32 v60, v60, v58
	v_mfma_f32_16x16x32_bf16 v[72:75], v[114:117], v[68:71], v[74:77]
	v_sub_f32_e32 v9, v9, v99
	v_cvt_pk_bf16_f32 v40, v40, v41
	v_cvt_pk_bf16_f32 v41, v42, v32
	v_mfma_f32_16x16x32_bf16 v[114:117], v[134:137], v[88:91], v[138:141]
	v_cvt_pk_bf16_f32 v42, v43, v34
	v_cvt_pk_bf16_f32 v43, v47, v35
	v_sub_f32_e32 v35, v11, v99
	v_mfma_f32_16x16x32_bf16 v[20:23], v[134:137], v[68:71], v[102:105]
	v_sub_f32_e32 v16, v16, v99
	v_sub_f32_e32 v4, v4, v99
	v_sub_f32_e32 v5, v5, v99
	s_waitcnt lgkmcnt(3)
	v_mfma_f32_16x16x32_bf16 v[134:137], v[184:187], v[88:91], v[188:191]
	v_sub_f32_e32 v0, v0, v99
	v_sub_f32_e32 v2, v2, v99
	v_sub_f32_e32 v30, v30, v99
	v_ldexp_f32 v188, v12, v62
	v_sub_f32_e32 v12, v13, v99
	v_mul_f32_e32 v13, 0x3e0293ee, v12
	v_cmp_gt_f32_e32 vcc, s33, v13
	v_mfma_f32_16x16x32_bf16 v[168:171], v[168:171], v[106:109], 0
	v_cvt_pk_bf16_f32 v62, v57, v45
	v_cndmask_b32_e32 v13, 0, v159, vcc
	v_fmac_f32_e32 v13, 0x3e0293ee, v12
	v_exp_f32_e32 v12, v13
	v_add_f32_e32 v13, v188, v61
	v_cndmask_b32_e32 v61, 0, v160, vcc
	v_mfma_f32_16x16x32_bf16 v[138:141], v[184:187], v[68:71], v[168:171]
	v_ldexp_f32 v184, v12, v61
	v_add_f32_e32 v12, v184, v13
	v_sub_f32_e32 v13, v14, v99
	v_mul_f32_e32 v14, 0x3e0293ee, v13
	v_cmp_gt_f32_e32 vcc, s33, v14
	v_sub_f32_e32 v45, v15, v99
	v_mul_f32_e32 v46, 0x3e0293ee, v45
	v_cndmask_b32_e32 v14, 0, v159, vcc
	v_fmac_f32_e32 v14, 0x3e0293ee, v13
	v_exp_f32_e32 v13, v14
	v_cndmask_b32_e32 v14, 0, v160, vcc
	v_cmp_gt_f32_e32 vcc, s33, v46
	v_mfma_f32_16x16x32_bf16 v[126:129], v[110:113], v[92:95], 0
	v_cvt_pk_bf16_f32 v61, v56, v44
	v_cndmask_b32_e32 v46, 0, v159, vcc
	v_fmac_f32_e32 v46, 0x3e0293ee, v45
	v_mfma_f32_16x16x32_bf16 v[110:113], v[110:113], v[106:109], 0
	v_exp_f32_e32 v45, v46
	v_cndmask_b32_e32 v46, 0, v160, vcc
	v_ldexp_f32 v185, v13, v14
	v_mfma_f32_16x16x32_bf16 v[146:149], v[130:133], v[92:95], 0
	v_ldexp_f32 v186, v45, v46
	v_mul_f32_e32 v45, 0x3e0293ee, v8
	v_cmp_gt_f32_e32 vcc, s33, v45
	v_mfma_f32_16x16x32_bf16 v[130:133], v[130:133], v[106:109], 0
	v_add_f32_e32 v44, v185, v12
	v_cndmask_b32_e32 v45, 0, v159, vcc
	v_fmac_f32_e32 v45, 0x3e0293ee, v8
	v_mfma_f32_16x16x32_bf16 v[176:179], v[164:167], v[92:95], 0
	v_exp_f32_e32 v8, v45
	v_cndmask_b32_e32 v45, 0, v160, vcc
	v_add_f32_e32 v44, v186, v44
	v_mfma_f32_16x16x32_bf16 v[200:203], v[180:183], v[92:95], 0
	v_ldexp_f32 v187, v8, v45
	v_add_f32_e32 v8, v187, v44
	v_mul_f32_e32 v44, 0x3e0293ee, v9
	s_waitcnt lgkmcnt(2)
; #define MFMA16(a, b, c) __builtin_amdgcn_mfma_f32_16x16x32_bf16((a), (b), (c), 0, 0, 0)
; __device__ __forceinline__ void attn_prompt_item(const Params& p, int item, const int wv, unsigned* bar) {
;     ...
;   f32x4 o[8][2];
; #pragma unroll
;   for (int db = 0; db < 8; ++db) { o[db][0] = (f32x4){0.f, 0.f, 0.f, 0.f}; o[db][1] = (f32x4){0.f, 0.f, 0.f, 0.f}; }
; #pragma unroll
;   for (int st = 0; st < 8; ++st)
; #pragma unroll
;     for (int db = 0; db < 8; ++db) {
;       bf16x8 vf = *(const bf16x8*)(VT_l + (db * 16 + fr) * 264 + st * 32 + fq * 8);
;       o[db][0] = MFMA16(vf, pf[0][st], o[db][0]);
;       o[db][1] = MFMA16(vf, pf[1][st], o[db][1]);
;     }
	v_mfma_f32_16x16x32_bf16 v[92:95], v[192:195], v[92:95], 0
	v_cmp_gt_f32_e32 vcc, s33, v44
	v_sub_f32_e32 v31, v31, v99
	v_mfma_f32_16x16x32_bf16 v[76:79], v[122:125], v[88:91], v[126:129]
	v_cndmask_b32_e32 v44, 0, v159, vcc
	v_fmac_f32_e32 v44, 0x3e0293ee, v9
	v_exp_f32_e32 v9, v44
	v_mfma_f32_16x16x32_bf16 v[110:113], v[122:125], v[68:71], v[110:113]
	v_cndmask_b32_e32 v44, 0, v160, vcc
	v_ldexp_f32 v189, v9, v44
	v_mfma_f32_16x16x32_bf16 v[102:105], v[142:145], v[88:91], v[146:149]
	v_sub_f32_e32 v9, v10, v99
	v_mul_f32_e32 v10, 0x3e0293ee, v9
	v_cmp_gt_f32_e32 vcc, s33, v10
	v_mfma_f32_16x16x32_bf16 v[122:125], v[142:145], v[68:71], v[130:133]
	v_add_f32_e32 v32, v189, v8
	v_cndmask_b32_e32 v10, 0, v159, vcc
	v_fmac_f32_e32 v10, 0x3e0293ee, v9
	v_mfma_f32_16x16x32_bf16 v[126:129], v[172:175], v[88:91], v[176:179]
	v_exp_f32_e32 v9, v10
	v_cndmask_b32_e32 v8, 0, v160, vcc
	v_ldexp_f32 v34, v9, v8
	s_waitcnt lgkmcnt(1)
	v_mfma_f32_16x16x32_bf16 v[142:145], v[196:199], v[88:91], v[200:203]
	v_add_f32_e32 v32, v34, v32
	s_waitcnt lgkmcnt(0)
	v_mfma_f32_16x16x32_bf16 v[88:91], v[204:207], v[88:91], v[92:95]
	s_nop 2
	ds_read_b128 v[92:95], v101 offset:128
	v_mfma_f32_16x16x32_bf16 v[164:167], v[164:167], v[106:109], 0
	v_mfma_f32_16x16x32_bf16 v[180:183], v[180:183], v[106:109], 0
	v_mfma_f32_16x16x32_bf16 v[106:109], v[192:195], v[106:109], 0
	v_mfma_f32_16x16x32_bf16 v[130:133], v[172:175], v[68:71], v[164:167]
	v_mfma_f32_16x16x32_bf16 v[146:149], v[196:199], v[68:71], v[180:183]
	v_mfma_f32_16x16x32_bf16 v[68:71], v[204:207], v[68:71], v[106:109]
	s_nop 4
	ds_read_b128 v[106:109], v101 offset:8576
	ds_read_b128 v[164:167], v101 offset:192
	s_waitcnt lgkmcnt(2)
	v_mfma_f32_16x16x32_bf16 v[118:121], v[92:95], v[84:87], v[118:121]
	v_mfma_f32_16x16x32_bf16 v[56:59], v[92:95], v[60:63], v[72:75]
	s_nop 2
	ds_read_b128 v[72:75], v101 offset:17024
	ds_read_b128 v[92:95], v101 offset:8640
	s_waitcnt lgkmcnt(3)
	v_mfma_f32_16x16x32_bf16 v[76:79], v[106:109], v[84:87], v[76:79]
	v_mfma_f32_16x16x32_bf16 v[12:15], v[106:109], v[60:63], v[110:113]
	ds_read_b128 v[106:109], v101 offset:25472
	s_nop 1
	ds_read_b128 v[110:113], v101 offset:17088
	s_waitcnt lgkmcnt(3)
	v_mfma_f32_16x16x32_bf16 v[114:117], v[72:75], v[84:87], v[114:117]
	v_mfma_f32_16x16x32_bf16 v[20:23], v[72:75], v[60:63], v[20:23]
	ds_read_b128 v[72:75], v101 offset:33920
	ds_read_b128 v[168:171], v101 offset:25536
	ds_read_b128 v[172:175], v101 offset:42368
	s_waitcnt lgkmcnt(4)
	v_mfma_f32_16x16x32_bf16 v[102:105], v[106:109], v[84:87], v[102:105]
	v_mfma_f32_16x16x32_bf16 v[106:109], v[106:109], v[60:63], v[122:125]
	s_nop 2
	ds_read_b128 v[122:125], v101 offset:33984
	s_waitcnt lgkmcnt(3)
	v_mfma_f32_16x16x32_bf16 v[126:129], v[72:75], v[84:87], v[126:129]
	v_mfma_f32_16x16x32_bf16 v[72:75], v[72:75], v[60:63], v[130:133]
	s_nop 2
	ds_read_b128 v[130:133], v101 offset:50816
	ds_read_b128 v[176:179], v101 offset:42432
	s_waitcnt lgkmcnt(3)
	v_mfma_f32_16x16x32_bf16 v[134:137], v[172:175], v[84:87], v[134:137]
	v_mfma_f32_16x16x32_bf16 v[138:141], v[172:175], v[60:63], v[138:141]
	ds_read_b128 v[172:175], v101 offset:59264
	ds_read_b128 v[180:183], v101 offset:50880
	v_mfma_f32_16x16x32_bf16 v[44:47], v[164:167], v[40:43], v[56:59]
	v_mfma_f32_16x16x32_bf16 v[56:59], v[92:95], v[80:83], v[76:79]
	s_nop 2
	v_mul_f32_e32 v76, 0x3e0293ee, v35
	v_cmp_gt_f32_e32 vcc, s33, v76
	s_waitcnt lgkmcnt(3)
	v_mfma_f32_16x16x32_bf16 v[142:145], v[130:133], v[84:87], v[142:145]
	v_cndmask_b32_e32 v76, 0, v159, vcc
	v_fmac_f32_e32 v76, 0x3e0293ee, v35
	s_waitcnt lgkmcnt(1)
	v_mfma_f32_16x16x32_bf16 v[84:87], v[172:175], v[84:87], v[88:91]
	v_exp_f32_e32 v35, v76
	v_cndmask_b32_e32 v76, 0, v160, vcc
	v_ldexp_f32 v35, v35, v76
	v_mul_f32_e32 v88, 0x3e0293ee, v16
	v_cmp_gt_f32_e32 vcc, s33, v88
	v_mfma_f32_16x16x32_bf16 v[8:11], v[92:95], v[40:43], v[12:15]
	v_add_f32_e32 v32, v35, v32
	v_cndmask_b32_e32 v92, 0, v159, vcc
	v_fmac_f32_e32 v92, 0x3e0293ee, v16
	v_exp_f32_e32 v16, v92
	v_mfma_f32_16x16x32_bf16 v[76:79], v[168:171], v[80:83], v[102:105]
	s_nop 2
	v_cndmask_b32_e32 v102, 0, v160, vcc
	v_mfma_f32_16x16x32_bf16 v[130:133], v[130:133], v[60:63], v[146:149]
	v_mfma_f32_16x16x32_bf16 v[60:63], v[172:175], v[60:63], v[68:71]
	s_nop 1
	ds_read_b128 v[146:149], v101 offset:59328
	v_mfma_f32_16x16x32_bf16 v[68:71], v[164:167], v[80:83], v[118:121]
	v_ldexp_f32 v164, v16, v102
	v_sub_f32_e32 v16, v17, v99
	v_mul_f32_e32 v17, 0x3e0293ee, v16
	v_cmp_gt_f32_e32 vcc, s33, v17
	v_mfma_f32_16x16x32_bf16 v[92:95], v[122:125], v[80:83], v[126:129]
	ds_read_b128 v[118:121], v101 offset:256
	v_cndmask_b32_e32 v17, 0, v159, vcc
	v_fmac_f32_e32 v17, 0x3e0293ee, v16
	v_exp_f32_e32 v16, v17
	v_add_f32_e32 v17, v164, v32
	v_cndmask_b32_e32 v32, 0, v160, vcc
	v_sub_f32_e32 v126, v19, v99
	v_ldexp_f32 v32, v16, v32
	v_add_f32_e32 v16, v32, v17
	v_sub_f32_e32 v17, v18, v99
	v_mul_f32_e32 v18, 0x3e0293ee, v17
	v_cmp_gt_f32_e32 vcc, s33, v18
	v_mfma_f32_16x16x32_bf16 v[12:15], v[110:113], v[80:83], v[114:117]
	s_nop 0
	v_cndmask_b32_e32 v18, 0, v159, vcc
	v_fmac_f32_e32 v18, 0x3e0293ee, v17
	v_exp_f32_e32 v17, v18
	v_cndmask_b32_e32 v18, 0, v160, vcc
	v_mfma_f32_16x16x32_bf16 v[20:23], v[110:113], v[40:43], v[20:23]
	v_ldexp_f32 v165, v17, v18
	v_mfma_f32_16x16x32_bf16 v[88:91], v[168:171], v[40:43], v[106:109]
	v_mfma_f32_16x16x32_bf16 v[72:75], v[122:125], v[40:43], v[72:75]
	v_mfma_f32_16x16x32_bf16 v[106:109], v[176:179], v[40:43], v[138:141]
	s_waitcnt lgkmcnt(2)
	v_mfma_f32_16x16x32_bf16 v[114:117], v[180:183], v[40:43], v[130:133]
	s_nop 2
	v_add_f32_e32 v130, v165, v16
	s_waitcnt lgkmcnt(1)
; __device__ __forceinline__ u32x2 pack4(f32x4 v) { u32x2 r; r.x = cvt_pk(v[0], v[1]); r.y = cvt_pk(v[2], v[3]); return r; }
; __device__ __forceinline__ float shfl_xor_f(float v, int mask) { const int l = lane_fresh(); return __int_as_float(__builtin_amdgcn_ds_bpermute((l ^ mask) << 2, __float_as_int(v))); }
; #define MFMA16(a, b, c) __builtin_amdgcn_mfma_f32_16x16x32_bf16((a), (b), (c), 0, 0, 0)
; __device__ __forceinline__ void attn_prompt_item(const Params& p, int item, const int wv, unsigned* bar) {
;     ...
;       for (int e = 0; e < 4; ++e) { float pv = exp2f((s[mb][qb][e] - mx) * cexp); s[mb][qb][e] = pv; sum += pv; }
;     sum += shfl_xor_f(sum, 16); sum += shfl_xor_f(sum, 32);
;     inv[qb] = 1.f / sum;
; #pragma unroll
;     for (int st = 0; st < 8; ++st) {
;       u32x2 lo = pack4(s[2 * st][qb]), hi = pack4(s[2 * st + 1][qb]);
;       u32x4 w = {lo.x, lo.y, hi.x, hi.y};
;       pf[qb][st] = __builtin_bit_cast(bf16x8, w);
;     }
;   }
;   f32x4 o[8][2];
; #pragma unroll
;   for (int db = 0; db < 8; ++db) { o[db][0] = (f32x4){0.f, 0.f, 0.f, 0.f}; o[db][1] = (f32x4){0.f, 0.f, 0.f, 0.f}; }
; #pragma unroll
;   for (int st = 0; st < 8; ++st)
; #pragma unroll
;     for (int db = 0; db < 8; ++db) {
;       bf16x8 vf = *(const bf16x8*)(VT_l + (db * 16 + fr) * 264 + st * 32 + fq * 8);
;       o[db][0] = MFMA16(vf, pf[0][st], o[db][0]);
;       o[db][1] = MFMA16(vf, pf[1][st], o[db][1]);
;     }
	v_mfma_f32_16x16x32_bf16 v[16:19], v[146:149], v[40:43], v[60:63]
	v_cvt_pk_bf16_f32 v40, v24, v150
	v_mul_f32_e32 v24, 0x3e0293ee, v126
	v_cmp_gt_f32_e32 vcc, s33, v24
	v_cvt_pk_bf16_f32 v41, v26, v27
	v_mfma_f32_16x16x32_bf16 v[102:105], v[176:179], v[80:83], v[134:137]
	v_cndmask_b32_e32 v24, 0, v159, vcc
	v_fmac_f32_e32 v24, 0x3e0293ee, v126
	v_exp_f32_e32 v24, v24
	v_cndmask_b32_e32 v26, 0, v160, vcc
	v_mfma_f32_16x16x32_bf16 v[110:113], v[180:183], v[80:83], v[142:145]
	v_mul_f32_e32 v27, 0x3e0293ee, v5
	v_ldexp_f32 v24, v24, v26
	v_mul_f32_e32 v26, 0x3e0293ee, v4
	v_cmp_gt_f32_e32 vcc, s33, v26
	v_mfma_f32_16x16x32_bf16 v[80:83], v[146:149], v[80:83], v[84:87]
	ds_read_b128 v[60:63], v101 offset:8704
	s_nop 1
	ds_read_b128 v[84:87], v101 offset:320
	v_cndmask_b32_e32 v26, 0, v159, vcc
	v_fmac_f32_e32 v26, 0x3e0293ee, v4
	v_exp_f32_e32 v4, v26
	v_cndmask_b32_e32 v26, 0, v160, vcc
	v_cmp_gt_f32_e32 vcc, s33, v27
	v_cvt_pk_bf16_f32 v42, v100, v151
	v_cvt_pk_bf16_f32 v43, v152, v163
	v_cndmask_b32_e32 v27, 0, v159, vcc
	s_waitcnt lgkmcnt(2)
	v_mfma_f32_16x16x32_bf16 v[68:71], v[118:121], v[64:67], v[68:71]
	v_fmac_f32_e32 v27, 0x3e0293ee, v5
	v_exp_f32_e32 v5, v27
	v_add_f32_e32 v100, v24, v130
	v_mfma_f32_16x16x32_bf16 v[44:47], v[118:121], v[40:43], v[44:47]
	ds_read_b128 v[118:121], v101 offset:17152
	ds_read_b128 v[122:125], v101 offset:8768
	v_ldexp_f32 v146, v4, v26
	v_cndmask_b32_e32 v4, 0, v160, vcc
	s_waitcnt lgkmcnt(3)
	v_mfma_f32_16x16x32_bf16 v[56:59], v[60:63], v[64:67], v[56:59]
	v_ldexp_f32 v147, v5, v4
	v_sub_f32_e32 v4, v6, v99
	v_mul_f32_e32 v5, 0x3e0293ee, v4
	v_mfma_f32_16x16x32_bf16 v[8:11], v[60:63], v[40:43], v[8:11]
	ds_read_b128 v[60:63], v101 offset:25600
	ds_read_b128 v[126:129], v101 offset:17216
	v_cmp_gt_f32_e32 vcc, s33, v5
	v_sub_f32_e32 v26, v7, v99
	s_waitcnt lgkmcnt(3)
	v_mfma_f32_16x16x32_bf16 v[12:15], v[118:121], v[64:67], v[12:15]
	v_cndmask_b32_e32 v5, 0, v159, vcc
	v_fmac_f32_e32 v5, 0x3e0293ee, v4
	v_mul_f32_e32 v27, 0x3e0293ee, v26
	v_mfma_f32_16x16x32_bf16 v[20:23], v[118:121], v[40:43], v[20:23]
	ds_read_b128 v[118:121], v101 offset:34048
	ds_read_b128 v[130:133], v101 offset:25664
	v_exp_f32_e32 v4, v5
	v_cndmask_b32_e32 v5, 0, v160, vcc
	s_waitcnt lgkmcnt(3)
	v_mfma_f32_16x16x32_bf16 v[76:79], v[60:63], v[64:67], v[76:79]
	v_cmp_gt_f32_e32 vcc, s33, v27
	v_mfma_f32_16x16x32_bf16 v[60:63], v[60:63], v[40:43], v[88:91]
	s_nop 2
	ds_read_b128 v[88:91], v101 offset:42496
	ds_read_b128 v[134:137], v101 offset:34112
	v_cndmask_b32_e32 v27, 0, v159, vcc
	v_fmac_f32_e32 v27, 0x3e0293ee, v26
	s_waitcnt lgkmcnt(3)
	v_mfma_f32_16x16x32_bf16 v[92:95], v[118:121], v[64:67], v[92:95]
	v_exp_f32_e32 v26, v27
	v_cndmask_b32_e32 v27, 0, v160, vcc
	v_mfma_f32_16x16x32_bf16 v[72:75], v[118:121], v[40:43], v[72:75]
	ds_read_b128 v[118:121], v101 offset:50944
	ds_read_b128 v[138:141], v101 offset:42560
	s_waitcnt lgkmcnt(3)
	v_mfma_f32_16x16x32_bf16 v[102:105], v[88:91], v[64:67], v[102:105]
	v_mfma_f32_16x16x32_bf16 v[88:91], v[88:91], v[40:43], v[106:109]
	s_nop 2
	ds_read_b128 v[106:109], v101 offset:59392
	ds_read_b128 v[142:145], v101 offset:51008
	s_waitcnt lgkmcnt(3)
	v_mfma_f32_16x16x32_bf16 v[114:117], v[118:121], v[40:43], v[114:117]
	s_waitcnt lgkmcnt(1)
	v_mfma_f32_16x16x32_bf16 v[16:19], v[106:109], v[40:43], v[16:19]
	v_cvt_pk_bf16_f32 v43, v34, v35
	v_mul_f32_e32 v35, 0x3e0293ee, v0
	v_cmp_gt_f32_e32 vcc, s33, v35
	v_cvt_pk_bf16_f32 v40, v188, v184
	v_cvt_pk_bf16_f32 v41, v185, v186
	v_cndmask_b32_e32 v35, 0, v159, vcc
	v_fmac_f32_e32 v35, 0x3e0293ee, v0
	v_exp_f32_e32 v0, v35
	v_cvt_pk_bf16_f32 v42, v187, v189
	v_ldexp_f32 v35, v26, v27
	v_cndmask_b32_e32 v26, 0, v160, vcc
	v_mfma_f32_16x16x32_bf16 v[12:15], v[126:129], v[48:51], v[12:15]
	v_ldexp_f32 v34, v4, v5
	v_mfma_f32_16x16x32_bf16 v[20:23], v[126:129], v[40:43], v[20:23]
	v_ldexp_f32 v126, v0, v26
	v_sub_f32_e32 v0, v1, v99
	v_mul_f32_e32 v1, 0x3e0293ee, v0
	v_cmp_gt_f32_e32 vcc, s33, v1
	v_mul_f32_e32 v26, 0x3e0293ee, v2
	v_mfma_f32_16x16x32_bf16 v[110:113], v[118:121], v[64:67], v[110:113]
	v_cndmask_b32_e32 v1, 0, v159, vcc
	v_fmac_f32_e32 v1, 0x3e0293ee, v0
	v_exp_f32_e32 v0, v1
	v_cndmask_b32_e32 v1, 0, v160, vcc
	v_cmp_gt_f32_e32 vcc, s33, v26
	ds_read_b128 v[118:121], v101 offset:59456
	v_ldexp_f32 v127, v0, v1
	v_cndmask_b32_e32 v26, 0, v159, vcc
	v_fmac_f32_e32 v26, 0x3e0293ee, v2
	v_exp_f32_e32 v2, v26
	v_sub_f32_e32 v26, v3, v99
	v_mul_f32_e32 v27, 0x3e0293ee, v26
	v_cndmask_b32_e32 v0, 0, v160, vcc
	v_cmp_gt_f32_e32 vcc, s33, v27
	v_mfma_f32_16x16x32_bf16 v[4:7], v[122:125], v[48:51], v[56:59]
	v_ldexp_f32 v128, v2, v0
	v_cndmask_b32_e32 v27, 0, v159, vcc
	v_fmac_f32_e32 v27, 0x3e0293ee, v26
	v_mfma_f32_16x16x32_bf16 v[56:59], v[130:133], v[48:51], v[76:79]
	v_exp_f32_e32 v26, v27
	v_cndmask_b32_e32 v27, 0, v160, vcc
	v_ldexp_f32 v129, v26, v27
	v_mfma_f32_16x16x32_bf16 v[76:79], v[134:137], v[48:51], v[92:95]
	v_sub_f32_e32 v26, v28, v99
	s_nop 1
	ds_read_b128 v[92:95], v101 offset:384
	v_mfma_f32_16x16x32_bf16 v[64:67], v[106:109], v[64:67], v[80:83]
	v_mfma_f32_16x16x32_bf16 v[68:71], v[84:87], v[48:51], v[68:71]
	v_mfma_f32_16x16x32_bf16 v[44:47], v[84:87], v[40:43], v[44:47]
	v_mfma_f32_16x16x32_bf16 v[8:11], v[122:125], v[40:43], v[8:11]
	v_mul_f32_e32 v122, 0x3e0293ee, v30
	v_mfma_f32_16x16x32_bf16 v[60:63], v[130:133], v[40:43], v[60:63]
	v_mfma_f32_16x16x32_bf16 v[72:75], v[134:137], v[40:43], v[72:75]
	v_mfma_f32_16x16x32_bf16 v[80:83], v[138:141], v[48:51], v[102:105]
	v_mfma_f32_16x16x32_bf16 v[84:87], v[138:141], v[40:43], v[88:91]
	s_waitcnt lgkmcnt(2)
; __device__ __forceinline__ u32x2 pack4(f32x4 v) { u32x2 r; r.x = cvt_pk(v[0], v[1]); r.y = cvt_pk(v[2], v[3]); return r; }
; __device__ __forceinline__ float shfl_xor_f(float v, int mask) { const int l = lane_fresh(); return __int_as_float(__builtin_amdgcn_ds_bpermute((l ^ mask) << 2, __float_as_int(v))); }
; #define MFMA16(a, b, c) __builtin_amdgcn_mfma_f32_16x16x32_bf16((a), (b), (c), 0, 0, 0)
; __device__ __forceinline__ void attn_prompt_item(const Params& p, int item, const int wv, unsigned* bar) {
;     ...
;       for (int e = 0; e < 4; ++e) { float pv = exp2f((s[mb][qb][e] - mx) * cexp); s[mb][qb][e] = pv; sum += pv; }
;     sum += shfl_xor_f(sum, 16); sum += shfl_xor_f(sum, 32);
;     inv[qb] = 1.f / sum;
; #pragma unroll
;     for (int st = 0; st < 8; ++st) {
;       u32x2 lo = pack4(s[2 * st][qb]), hi = pack4(s[2 * st + 1][qb]);
;       u32x4 w = {lo.x, lo.y, hi.x, hi.y};
;       pf[qb][st] = __builtin_bit_cast(bf16x8, w);
;     }
;   }
;   f32x4 o[8][2];
; #pragma unroll
;   for (int db = 0; db < 8; ++db) { o[db][0] = (f32x4){0.f, 0.f, 0.f, 0.f}; o[db][1] = (f32x4){0.f, 0.f, 0.f, 0.f}; }
; #pragma unroll
;   for (int st = 0; st < 8; ++st)
; #pragma unroll
;     for (int db = 0; db < 8; ++db) {
;       bf16x8 vf = *(const bf16x8*)(VT_l + (db * 16 + fr) * 264 + st * 32 + fq * 8);
;       o[db][0] = MFMA16(vf, pf[0][st], o[db][0]);
;       o[db][1] = MFMA16(vf, pf[1][st], o[db][1]);
;     }
	v_mfma_f32_16x16x32_bf16 v[0:3], v[142:145], v[48:51], v[110:113]
	v_mfma_f32_16x16x32_bf16 v[88:91], v[142:145], v[40:43], v[114:117]
	s_waitcnt lgkmcnt(1)
	v_mfma_f32_16x16x32_bf16 v[48:51], v[118:121], v[48:51], v[64:67]
	s_nop 2
	ds_read_b128 v[64:67], v101 offset:8832
	ds_read_b128 v[102:105], v101 offset:448
	v_mfma_f32_16x16x32_bf16 v[16:19], v[118:121], v[40:43], v[16:19]
	v_cvt_pk_bf16_f32 v41, v165, v24
	v_mul_f32_e32 v24, 0x3e0293ee, v26
	v_cmp_gt_f32_e32 vcc, s33, v24
	v_cvt_pk_bf16_f32 v40, v164, v32
	v_cvt_pk_bf16_f32 v42, v146, v147
	v_cndmask_b32_e32 v24, 0, v159, vcc
	v_cvt_pk_bf16_f32 v43, v34, v35
	v_fmac_f32_e32 v24, 0x3e0293ee, v26
	v_sub_f32_e32 v32, v29, v99
	s_waitcnt lgkmcnt(2)
	v_mfma_f32_16x16x32_bf16 v[68:71], v[92:95], v[52:55], v[68:71]
	v_exp_f32_e32 v24, v24
	v_mul_f32_e32 v114, 0x3e0293ee, v32
	v_cndmask_b32_e32 v26, 0, v160, vcc
	v_mfma_f32_16x16x32_bf16 v[44:47], v[92:95], v[40:43], v[44:47]
	ds_read_b128 v[92:95], v101 offset:17280
	ds_read_b128 v[106:109], v101 offset:8896
	v_cmp_gt_f32_e32 vcc, s33, v114
	v_ldexp_f32 v24, v24, v26
	s_waitcnt lgkmcnt(3)
	v_mfma_f32_16x16x32_bf16 v[4:7], v[64:67], v[52:55], v[4:7]
	v_cndmask_b32_e32 v114, 0, v159, vcc
	v_fmac_f32_e32 v114, 0x3e0293ee, v32
	v_exp_f32_e32 v32, v114
	v_mfma_f32_16x16x32_bf16 v[8:11], v[64:67], v[40:43], v[8:11]
	ds_read_b128 v[64:67], v101 offset:25728
	ds_read_b128 v[110:113], v101 offset:17344
	v_cndmask_b32_e32 v118, 0, v160, vcc
	v_cmp_gt_f32_e32 vcc, s33, v122
	s_waitcnt lgkmcnt(3)
	v_mfma_f32_16x16x32_bf16 v[12:15], v[92:95], v[52:55], v[12:15]
	v_ldexp_f32 v32, v32, v118
	v_cndmask_b32_e32 v122, 0, v159, vcc
	v_fmac_f32_e32 v122, 0x3e0293ee, v30
	v_mfma_f32_16x16x32_bf16 v[20:23], v[92:95], v[40:43], v[20:23]
	ds_read_b128 v[26:29], v101 offset:34176
	ds_read_b128 v[92:95], v101 offset:25792
	v_exp_f32_e32 v30, v122
	v_mul_f32_e32 v99, 0x3e0293ee, v31
	s_waitcnt lgkmcnt(3)
	v_mfma_f32_16x16x32_bf16 v[56:59], v[64:67], v[52:55], v[56:59]
	v_cndmask_b32_e32 v130, 0, v160, vcc
	v_cmp_gt_f32_e32 vcc, s33, v99
	v_ldexp_f32 v30, v30, v130
	v_mfma_f32_16x16x32_bf16 v[60:63], v[64:67], v[40:43], v[60:63]
	ds_read_b128 v[64:67], v101 offset:42624
	ds_read_b128 v[114:117], v101 offset:34240
	v_cndmask_b32_e32 v99, 0, v159, vcc
	v_fmac_f32_e32 v99, 0x3e0293ee, v31
	s_waitcnt lgkmcnt(3)
	v_mfma_f32_16x16x32_bf16 v[76:79], v[26:29], v[52:55], v[76:79]
	v_exp_f32_e32 v31, v99
	v_mfma_f32_16x16x32_bf16 v[26:29], v[26:29], v[40:43], v[72:75]
	s_nop 2
	ds_read_b128 v[72:75], v101 offset:51072
	ds_read_b128 v[118:121], v101 offset:42688
	s_waitcnt lgkmcnt(3)
	v_mfma_f32_16x16x32_bf16 v[80:83], v[64:67], v[52:55], v[80:83]
	v_mfma_f32_16x16x32_bf16 v[64:67], v[64:67], v[40:43], v[84:87]
	s_nop 2
	ds_read_b128 v[84:87], v101 offset:59520
	ds_read_b128 v[122:125], v101 offset:51136
	s_waitcnt lgkmcnt(3)
	v_mfma_f32_16x16x32_bf16 v[0:3], v[72:75], v[52:55], v[0:3]
	s_waitcnt lgkmcnt(1)
	v_mfma_f32_16x16x32_bf16 v[48:51], v[84:87], v[52:55], v[48:51]
	v_mfma_f32_16x16x32_bf16 v[52:55], v[102:105], v[36:39], v[68:71]
	s_nop 2
	v_add_f32_e32 v68, v146, v100
	v_add_f32_e32 v68, v147, v68
	v_add_f32_e32 v34, v34, v68
	v_add_f32_e32 v34, v35, v34
	v_add_f32_e32 v34, v126, v34
	v_add_f32_e32 v34, v127, v34
	v_add_f32_e32 v34, v128, v34
	v_add_f32_e32 v34, v129, v34
	v_mfma_f32_16x16x32_bf16 v[72:75], v[72:75], v[40:43], v[88:91]
	v_mfma_f32_16x16x32_bf16 v[16:19], v[84:87], v[40:43], v[16:19]
	v_cndmask_b32_e32 v40, 0, v160, vcc
	v_cvt_pk_bf16_f32 v42, v24, v32
	v_add_f32_e32 v24, v24, v34
	v_ldexp_f32 v31, v31, v40
	v_add_f32_e32 v24, v32, v24
	v_cvt_pk_bf16_f32 v43, v30, v31
	v_add_f32_e32 v24, v30, v24
	v_lshlrev_b32_e32 v30, 2, v33
	v_add_f32_e32 v24, v31, v24
	v_xor_b32_e32 v30, 64, v30
	v_mov_b32_e32 v34, v24
	s_nop 1
	v_permlane16_swap_b32_e32 v34, v24
	v_div_scale_f32 v35, vcc, 1.0, v96, 1.0
	v_mul_f32_e32 v84, v35, v97
	v_cvt_pk_bf16_f32 v40, v126, v127
	s_waitcnt lgkmcnt(0)
	v_add_f32_e32 v34, v24, v34
	v_lshlrev_b32_e32 v24, 2, v25
	v_xor_b32_e32 v24, 0x80, v24
	v_mov_b32_e32 v68, v34
	s_nop 1
	v_permlane32_swap_b32_e32 v68, v34
	v_cvt_pk_bf16_f32 v41, v128, v129
	v_fma_f32 v24, -v98, v84, v35
	v_fmac_f32_e32 v84, v24, v97
	v_mfma_f32_16x16x32_bf16 v[24:27], v[114:117], v[40:43], v[26:29]
	ds_read_b128 v[88:91], v101 offset:59584
	v_fma_f32 v35, -v98, v84, v35
	s_waitcnt lgkmcnt(1)
	v_add_f32_e32 v29, v34, v68
	v_div_scale_f32 v34, s[14:15], v29, v29, 1.0
	v_mfma_f32_16x16x32_bf16 v[30:33], v[92:95], v[36:39], v[56:59]
	v_div_fmas_f32 v28, v35, v97, v84
	v_div_fixup_f32 v28, v28, v96, 1.0
	v_mfma_f32_16x16x32_bf16 v[56:59], v[92:95], v[40:43], v[60:63]
	v_mfma_f32_16x16x32_bf16 v[60:63], v[114:117], v[36:39], v[76:79]
	s_nop 2
	v_rcp_f32_e32 v76, v34
	v_mfma_f32_16x16x32_bf16 v[4:7], v[106:109], v[36:39], v[4:7]
	v_fma_f32 v35, -v34, v76, 1.0
	v_fmac_f32_e32 v76, v35, v76
	v_div_scale_f32 v35, vcc, 1.0, v29, 1.0
	v_mul_f32_e32 v77, v35, v76
	v_fma_f32 v78, -v34, v77, v35
	v_fmac_f32_e32 v77, v78, v76
	v_fma_f32 v78, -v34, v77, v35
	v_mfma_f32_16x16x32_bf16 v[12:15], v[110:113], v[36:39], v[12:15]
	v_mfma_f32_16x16x32_bf16 v[68:71], v[118:121], v[36:39], v[80:83]
	v_mfma_f32_16x16x32_bf16 v[0:3], v[122:125], v[36:39], v[0:3]
	s_waitcnt lgkmcnt(0)
; __device__ __forceinline__ u32x2 pack4(f32x4 v) { u32x2 r; r.x = cvt_pk(v[0], v[1]); r.y = cvt_pk(v[2], v[3]); return r; }
; __device__ __forceinline__ void store_pair16(u16* rowp32, u32x2 a, u32x2 b, int fq) {
;   auto rx = __builtin_amdgcn_permlane16_swap(a.x, b.x, false, false);
;   auto ry = __builtin_amdgcn_permlane16_swap(a.y, b.y, false, false);
;   u32x4 w = {rx[0], ry[0], rx[1], ry[1]};
;   *(u32x4*)(rowp32 + ((fq & 1) * 16 + (fq >> 1) * 8)) = w;
; }
; __device__ __forceinline__ void attn_prompt_item(const Params& p, int item, const int wv, unsigned* bar) {
;     ...
; #pragma unroll
;   for (int qb = 0; qb < 2; ++qb)
; #pragma unroll
;     for (int dp = 0; dp < 4; ++dp)
;       store_pair16((u16*)(ws + OFF_XA) + (size_t)(q0 + qb * 16 + fr) * 512 + h * 128 + dp * 32, pack4(o[2 * dp][qb] * inv[qb]), pack4(o[2 * dp + 1][qb] * inv[qb]), fq);
	v_mfma_f32_16x16x32_bf16 v[34:37], v[88:91], v[36:39], v[48:51]
	v_div_fmas_f32 v38, v78, v76, v77
	s_nop 1
	v_div_fixup_f32 v48, v38, v29, 1.0
	v_lshlrev_b32_e32 v38, 2, v162
	v_and_b32_e32 v29, 16, v161
	v_and_b32_e32 v38, -8, v38
	v_add_u32_e32 v38, v38, v29
	v_ashrrev_i32_e32 v39, 31, v38
	v_mfma_f32_16x16x32_bf16 v[44:47], v[102:105], v[40:43], v[44:47]
	v_mul_f32_e64 v6, v28, v6
	v_mul_f32_e64 v7, v28, v7
	v_pk_mul_f32 v[4:5], v[28:29], v[4:5] op_sel_hi:[0,1]
	v_pk_mul_f32 v[2:3], v[28:29], v[2:3] op_sel_hi:[0,1]
	v_mfma_f32_16x16x32_bf16 v[8:11], v[106:109], v[40:43], v[8:11]
	v_mul_f32_e64 v0, v28, v0
	v_mul_f32_e64 v1, v28, v1
	v_cvt_pk_bf16_f32 v0, v0, v1
	v_cvt_pk_bf16_f32 v1, v2, v3
	v_mfma_f32_16x16x32_bf16 v[20:23], v[110:113], v[40:43], v[20:23]
	v_mul_f32_e64 v2, v28, v34
	v_mul_f32_e64 v3, v28, v35
	v_cvt_pk_bf16_f32 v2, v2, v3
	s_nop 1
	v_permlane16_swap_b32_e32 v0, v2
	v_mfma_f32_16x16x32_bf16 v[64:67], v[118:121], v[40:43], v[64:67]
	v_mfma_f32_16x16x32_bf16 v[72:75], v[122:125], v[40:43], v[72:75]
	v_mfma_f32_16x16x32_bf16 v[16:19], v[88:91], v[40:43], v[16:19]
	v_lshl_add_u64 v[42:43], v[38:39], 1, s[12:13]
	v_pk_mul_f32 v[40:41], v[28:29], v[54:55] op_sel_hi:[0,1]
	v_pk_mul_f32 v[38:39], v[28:29], v[52:53] op_sel_hi:[0,1]
	v_cvt_pk_bf16_f32 v38, v38, v39
	v_cvt_pk_bf16_f32 v39, v40, v41
	v_cvt_pk_bf16_f32 v40, v4, v5
	v_cvt_pk_bf16_f32 v41, v6, v7
	v_pk_mul_f32 v[6:7], v[28:29], v[14:15] op_sel_hi:[0,1]
	v_pk_mul_f32 v[4:5], v[28:29], v[12:13] op_sel_hi:[0,1]
	v_cvt_pk_bf16_f32 v4, v4, v5
	v_cvt_pk_bf16_f32 v5, v6, v7
	v_pk_mul_f32 v[12:13], v[28:29], v[32:33] op_sel_hi:[0,1]
	v_pk_mul_f32 v[6:7], v[28:29], v[30:31] op_sel_hi:[0,1]
	v_cvt_pk_bf16_f32 v6, v6, v7
	v_cvt_pk_bf16_f32 v7, v12, v13
	v_lshl_add_u64 v[50:51], v[42:43], 0, v[156:157]
	v_permlane16_swap_b32_e32 v4, v6
	v_permlane16_swap_b32_e32 v5, v7
	global_store_dwordx4 v[50:51], v[4:7], off offset:64
	v_pk_mul_f32 v[12:13], v[28:29], v[70:71] op_sel_hi:[0,1]
	v_permlane16_swap_b32_e32 v38, v40
	v_pk_mul_f32 v[6:7], v[28:29], v[62:63] op_sel_hi:[0,1]
	v_pk_mul_f32 v[4:5], v[28:29], v[60:61] op_sel_hi:[0,1]
	v_cvt_pk_bf16_f32 v4, v4, v5
	v_cvt_pk_bf16_f32 v5, v6, v7
	v_pk_mul_f32 v[6:7], v[28:29], v[68:69] op_sel_hi:[0,1]
	v_cvt_pk_bf16_f32 v6, v6, v7
	v_cvt_pk_bf16_f32 v7, v12, v13
	s_nop 0
	v_permlane16_swap_b32_e32 v4, v6
	v_permlane16_swap_b32_e32 v5, v7
	global_store_dwordx4 v[50:51], v[4:7], off offset:128
	v_permlane16_swap_b32_e32 v39, v41
	s_nop 0
	v_pk_mul_f32 v[4:5], v[28:29], v[36:37] op_sel_hi:[0,1]
	v_cvt_pk_bf16_f32 v3, v4, v5
	s_nop 1
	v_permlane16_swap_b32_e32 v1, v3
	global_store_dwordx4 v[50:51], v[0:3], off offset:192
	v_pk_mul_f32 v[6:7], v[48:49], v[10:11] op_sel_hi:[0,1]
	v_lshl_add_u64 v[4:5], v[42:43], 0, v[154:155]
	v_pk_mul_f32 v[2:3], v[48:49], v[46:47] op_sel_hi:[0,1]
	v_pk_mul_f32 v[0:1], v[48:49], v[44:45] op_sel_hi:[0,1]
	v_cvt_pk_bf16_f32 v0, v0, v1
	v_cvt_pk_bf16_f32 v1, v2, v3
	v_pk_mul_f32 v[2:3], v[48:49], v[8:9] op_sel_hi:[0,1]
	v_cvt_pk_bf16_f32 v2, v2, v3
	v_cvt_pk_bf16_f32 v3, v6, v7
	s_nop 0
	v_permlane16_swap_b32_e32 v0, v2
	v_permlane16_swap_b32_e32 v1, v3
	global_store_dwordx4 v[4:5], v[0:3], off
	v_pk_mul_f32 v[6:7], v[48:49], v[58:59] op_sel_hi:[0,1]
	global_store_dwordx4 v[50:51], v[38:41], off
	v_pk_mul_f32 v[2:3], v[48:49], v[22:23] op_sel_hi:[0,1]
	v_pk_mul_f32 v[0:1], v[48:49], v[20:21] op_sel_hi:[0,1]
	v_cvt_pk_bf16_f32 v0, v0, v1
	v_cvt_pk_bf16_f32 v1, v2, v3
	v_pk_mul_f32 v[2:3], v[48:49], v[56:57] op_sel_hi:[0,1]
	v_cvt_pk_bf16_f32 v2, v2, v3
	v_cvt_pk_bf16_f32 v3, v6, v7
	s_nop 0
	v_permlane16_swap_b32_e32 v0, v2
	v_permlane16_swap_b32_e32 v1, v3
	global_store_dwordx4 v[4:5], v[0:3], off offset:64
	v_pk_mul_f32 v[6:7], v[48:49], v[66:67] op_sel_hi:[0,1]
	s_nop 0
	v_pk_mul_f32 v[2:3], v[48:49], v[26:27] op_sel_hi:[0,1]
	v_pk_mul_f32 v[0:1], v[48:49], v[24:25] op_sel_hi:[0,1]
	v_cvt_pk_bf16_f32 v0, v0, v1
	v_cvt_pk_bf16_f32 v1, v2, v3
	v_pk_mul_f32 v[2:3], v[48:49], v[64:65] op_sel_hi:[0,1]
	v_cvt_pk_bf16_f32 v2, v2, v3
	v_cvt_pk_bf16_f32 v3, v6, v7
	s_nop 0
	v_permlane16_swap_b32_e32 v0, v2
	v_permlane16_swap_b32_e32 v1, v3
	global_store_dwordx4 v[4:5], v[0:3], off offset:128
	v_pk_mul_f32 v[6:7], v[48:49], v[18:19] op_sel_hi:[0,1]
	s_nop 0
	v_pk_mul_f32 v[2:3], v[48:49], v[74:75] op_sel_hi:[0,1]
	v_pk_mul_f32 v[0:1], v[48:49], v[72:73] op_sel_hi:[0,1]
	v_cvt_pk_bf16_f32 v0, v0, v1
	v_cvt_pk_bf16_f32 v1, v2, v3
	v_pk_mul_f32 v[2:3], v[48:49], v[16:17] op_sel_hi:[0,1]
	v_cvt_pk_bf16_f32 v2, v2, v3
	v_cvt_pk_bf16_f32 v3, v6, v7
	s_nop 0
	v_permlane16_swap_b32_e32 v0, v2
	v_permlane16_swap_b32_e32 v1, v3
	global_store_dwordx4 v[4:5], v[0:3], off offset:192
	s_cbranch_scc1 .LBB0_549

; __device__ __forceinline__ u32x2 pack4(f32x4 v) { u32x2 r; r.x = cvt_pk(v[0], v[1]); r.y = cvt_pk(v[2], v[3]); return r; }
; __device__ __forceinline__ int lane_fresh() { int l; asm volatile("v_mbcnt_lo_u32_b32 %0, -1, 0\n\tv_mbcnt_hi_u32_b32 %0, -1, %0" : "=v"(l)); return l; }
; __device__ __forceinline__ float shfl_xor_f(float v, int mask) { const int l = lane_fresh(); return __int_as_float(__builtin_amdgcn_ds_bpermute((l ^ mask) << 2, __float_as_int(v))); }
; __device__ __forceinline__ void store_pair16(u16* rowp32, u32x2 a, u32x2 b, int fq) {
;   auto rx = __builtin_amdgcn_permlane16_swap(a.x, b.x, false, false);
;   auto ry = __builtin_amdgcn_permlane16_swap(a.y, b.y, false, false);
;   u32x4 w = {rx[0], ry[0], rx[1], ry[1]};
;   *(u32x4*)(rowp32 + ((fq & 1) * 16 + (fq >> 1) * 8)) = w;
; }
; __device__ __forceinline__ void phaseE(const Params& p, const int wv, const int rep) {
;     ...
;     const int lane_e = lane_fresh(), fr = lane_e & 15, fq = lane_e >> 4; (void)fr; (void)fq;
; #pragma unroll
;     for (int ai = 0; ai < 2; ++ai)
; #pragma unroll
;       for (int m = 0; m < 4; ++m) {
;         const int row = brow + ai * 128 + wr * 64 + m * 16 + fr;
;         float ss = 0.f;
; #pragma unroll
;         for (int bj = 0; bj < 2; ++bj)
;           {
;             const int cb = bcol + bj * 128 + wc * 32;
;             f32x4 v0 = acc[ai][bj][m][0] + *(const f32x4*)(p.in[0] + (size_t)row * 1024 + cb + fq * 4);
;             f32x4 v1 = acc[ai][bj][m][1] + *(const f32x4*)(p.in[0] + (size_t)row * 1024 + cb + 16 + fq * 4);
;             store_pair16(H2B + (size_t)row * 1024 + cb, pack4(v0), pack4(v1), fq);
;             ss += v0[0] * v0[0] + v0[1] * v0[1] + v0[2] * v0[2] + v0[3] * v0[3] + v1[0] * v1[0] + v1[1] * v1[1] + v1[2] * v1[2] + v1[3] * v1[3];
;           }
;         ss += shfl_xor_f(ss, 16); ss += shfl_xor_f(ss, 32);
;         if (fq == 0) PS[(size_t)row * 16 + pn * 4 + wc] = ss;
.LBB0_983:
	s_lshl_b32 s30, s10, 8
	s_add_i32 s71, s71, s59
	v_mbcnt_lo_u32_b32 v135, -1, 0
	v_mbcnt_hi_u32_b32 v135, -1, v135
	s_or_b32 s34, s30, s60
	v_and_or_b32 v128, v135, 15, s71
	s_lshl_b32 s10, s10, 4
	v_readlane_b32 s72, v251, 6
	v_ashrrev_i32_e32 v146, 2, v135
	s_add_u32 s30, s61, s10
	v_lshlrev_b64 v[132:133], 12, v[128:129]
	v_readlane_b32 s73, v251, 7
	v_and_b32_e32 v130, -4, v146
	s_addc_u32 s31, s62, 0
	v_lshl_add_u64 v[132:133], s[72:73], 0, v[132:133]
	s_lshl_b32 s10, s34, 2
	v_ashrrev_i32_e32 v131, 31, v130
	v_lshl_add_u64 v[132:133], v[132:133], 0, s[10:11]
	v_lshl_add_u64 v[144:145], v[130:131], 2, v[132:133]
	global_load_dwordx4 v[136:139], v[144:145], off
	global_load_dwordx4 v[140:143], v[144:145], off offset:64
	v_and_b32_e32 v132, 16, v135
	v_and_b32_e32 v133, -8, v146
	v_add_u32_e32 v132, v133, v132
	v_ashrrev_i32_e32 v133, 31, v132
	v_lshlrev_b64 v[146:147], 11, v[128:129]
	v_lshl_add_u64 v[132:133], v[132:133], 1, s[8:9]
	s_mov_b32 s35, s11
	s_lshl_b32 s34, s34, 1
	v_lshl_add_u64 v[146:147], v[132:133], 0, v[146:147]
	v_lshl_add_u64 v[146:147], v[146:147], 0, s[34:35]
	v_cmp_gt_u32_e32 vcc, 16, v135
	v_readlane_b32 s74, v251, 8
	v_readlane_b32 s75, v251, 9
	v_readlane_b32 s76, v251, 10
	v_readlane_b32 s77, v251, 11
	v_readlane_b32 s78, v251, 12
	v_readlane_b32 s79, v251, 13
	v_readlane_b32 s80, v251, 14
	v_readlane_b32 s81, v251, 15
	v_readlane_b32 s82, v251, 16
	v_readlane_b32 s83, v251, 17
	v_readlane_b32 s84, v251, 18
	v_readlane_b32 s85, v251, 19
	v_readlane_b32 s86, v251, 20
	v_readlane_b32 s87, v251, 21
	s_waitcnt vmcnt(0)
	v_pk_add_f32 v[138:139], v[122:123], v[138:139]
	v_pk_add_f32 v[136:137], v[120:121], v[136:137]
	v_pk_add_f32 v[142:143], v[126:127], v[142:143]
	v_pk_add_f32 v[140:141], v[124:125], v[140:141]
	v_cvt_pk_bf16_f32 v120, v136, v137
	v_cvt_pk_bf16_f32 v121, v138, v139
	v_cvt_pk_bf16_f32 v122, v140, v141
	v_cvt_pk_bf16_f32 v123, v142, v143
	s_nop 0
	v_permlane16_swap_b32_e32 v120, v122
	v_permlane16_swap_b32_e32 v121, v123
	global_store_dwordx4 v[146:147], v[120:123], off sc1
	global_load_dwordx4 v[120:123], v[144:145], off offset:512
	s_nop 0
	global_load_dwordx4 v[124:127], v[144:145], off offset:576
	v_mul_f32_e32 v137, v137, v137
	v_fmac_f32_e32 v137, v136, v136
	v_fmac_f32_e32 v137, v138, v138
	v_fmac_f32_e32 v137, v139, v139
	v_fmac_f32_e32 v137, v140, v140
	v_fmac_f32_e32 v137, v141, v141
	v_fmac_f32_e32 v137, v142, v142
	v_fmac_f32_e32 v137, v143, v143
	s_waitcnt vmcnt(1)
	v_pk_add_f32 v[116:117], v[116:117], v[120:121]
	v_pk_add_f32 v[118:119], v[118:119], v[122:123]
	s_waitcnt vmcnt(0)
	v_pk_add_f32 v[122:123], v[112:113], v[124:125]
	v_cvt_pk_bf16_f32 v112, v116, v117
	v_mul_f32_e32 v117, v117, v117
	v_fmac_f32_e32 v117, v116, v116
	v_fmac_f32_e32 v117, v118, v118
	v_pk_add_f32 v[120:121], v[114:115], v[126:127]
	v_fmac_f32_e32 v117, v119, v119
	v_cvt_pk_bf16_f32 v113, v118, v119
	v_cvt_pk_bf16_f32 v114, v122, v123
	v_cvt_pk_bf16_f32 v115, v120, v121
	v_fmac_f32_e32 v117, v122, v122
	v_permlane16_swap_b32_e32 v112, v114
	v_permlane16_swap_b32_e32 v113, v115
	v_fmac_f32_e32 v117, v123, v123
	global_store_dwordx4 v[146:147], v[112:115], off offset:256 sc1
	v_fmac_f32_e32 v117, v120, v120
	v_fmac_f32_e32 v117, v121, v121
	v_mbcnt_lo_u32_b32 v112, -1, 0
	v_mbcnt_hi_u32_b32 v112, -1, v112
	v_add_f32_e32 v113, v137, v117
	v_lshlrev_b32_e32 v112, 2, v112
	v_xor_b32_e32 v112, 64, v112
	v_mov_b32_e32 v112, v113
	s_nop 1
	v_permlane16_swap_b32_e32 v112, v113
	v_mbcnt_lo_u32_b32 v114, -1, 0
	v_mbcnt_hi_u32_b32 v114, -1, v114
	s_waitcnt lgkmcnt(0)
	v_add_f32_e32 v112, v113, v112
	v_lshlrev_b32_e32 v114, 2, v114
	v_xor_b32_e32 v113, 0x80, v114
	ds_bpermute_b32 v113, v113, v112
	s_and_saveexec_b64 s[36:37], vcc
	s_cbranch_execz .LBB0_985
	s_waitcnt lgkmcnt(0)
	v_add_f32_e32 v114, v112, v113
	v_lshlrev_b64 v[112:113], 6, v[128:129]
	v_lshl_add_u64 v[112:113], s[30:31], 0, v[112:113]
	global_store_dword v[112:113], v114, off
.LBB0_985:
	s_or_b64 exec, exec, s[36:37]
	v_or_b32_e32 v112, 16, v128
	s_waitcnt lgkmcnt(0)
	v_mov_b32_e32 v113, v129
	v_readlane_b32 s72, v251, 6
	v_lshlrev_b64 v[114:115], 12, v[112:113]
	v_readlane_b32 s73, v251, 7
	v_lshlrev_b64 v[124:125], 11, v[112:113]
	v_lshl_add_u64 v[124:125], v[132:133], 0, v[124:125]
	v_lshl_add_u64 v[114:115], s[72:73], 0, v[114:115]
	v_lshl_add_u64 v[114:115], v[114:115], 0, s[10:11]
	v_lshl_add_u64 v[122:123], v[130:131], 2, v[114:115]
	global_load_dwordx4 v[114:117], v[122:123], off
	global_load_dwordx4 v[118:121], v[122:123], off offset:64
	v_lshl_add_u64 v[124:125], v[124:125], 0, s[34:35]
	v_readlane_b32 s74, v251, 8
	v_readlane_b32 s75, v251, 9
	v_readlane_b32 s76, v251, 10
	v_readlane_b32 s77, v251, 11
	v_readlane_b32 s78, v251, 12
	v_readlane_b32 s79, v251, 13
	v_readlane_b32 s80, v251, 14
	v_readlane_b32 s81, v251, 15
	v_readlane_b32 s82, v251, 16
	v_readlane_b32 s83, v251, 17
	v_readlane_b32 s84, v251, 18
	v_readlane_b32 s85, v251, 19
	v_readlane_b32 s86, v251, 20
	v_readlane_b32 s87, v251, 21
	s_waitcnt vmcnt(1)
	v_pk_add_f32 v[116:117], v[106:107], v[116:117]
	v_pk_add_f32 v[114:115], v[104:105], v[114:115]
	s_waitcnt vmcnt(0)
	v_pk_add_f32 v[120:121], v[110:111], v[120:121]
	v_pk_add_f32 v[118:119], v[108:109], v[118:119]
	v_cvt_pk_bf16_f32 v104, v114, v115
	v_cvt_pk_bf16_f32 v105, v116, v117
	v_cvt_pk_bf16_f32 v106, v118, v119
	v_cvt_pk_bf16_f32 v107, v120, v121
	s_nop 0
	v_permlane16_swap_b32_e32 v104, v106
	v_permlane16_swap_b32_e32 v105, v107
	global_store_dwordx4 v[124:125], v[104:107], off sc1
	global_load_dwordx4 v[104:107], v[122:123], off offset:512
	s_nop 0
	global_load_dwordx4 v[108:111], v[122:123], off offset:576
	v_mul_f32_e32 v115, v115, v115
	v_fmac_f32_e32 v115, v114, v114
	v_fmac_f32_e32 v115, v116, v116
	v_fmac_f32_e32 v115, v117, v117
	v_fmac_f32_e32 v115, v118, v118
	v_fmac_f32_e32 v115, v119, v119
	v_fmac_f32_e32 v115, v120, v120
	v_fmac_f32_e32 v115, v121, v121
	s_waitcnt vmcnt(1)
; __device__ __forceinline__ u32x2 pack4(f32x4 v) { u32x2 r; r.x = cvt_pk(v[0], v[1]); r.y = cvt_pk(v[2], v[3]); return r; }
; __device__ __forceinline__ float shfl_xor_f(float v, int mask) { const int l = lane_fresh(); return __int_as_float(__builtin_amdgcn_ds_bpermute((l ^ mask) << 2, __float_as_int(v))); }
; __device__ __forceinline__ void phaseE(const Params& p, const int wv, const int rep) {
;     ...
;     for (int ai = 0; ai < 2; ++ai)
; #pragma unroll
;       for (int m = 0; m < 4; ++m) {
;         const int row = brow + ai * 128 + wr * 64 + m * 16 + fr;
;         float ss = 0.f;
; #pragma unroll
;         for (int bj = 0; bj < 2; ++bj)
;           {
;             const int cb = bcol + bj * 128 + wc * 32;
;             f32x4 v0 = acc[ai][bj][m][0] + *(const f32x4*)(p.in[0] + (size_t)row * 1024 + cb + fq * 4);
;             f32x4 v1 = acc[ai][bj][m][1] + *(const f32x4*)(p.in[0] + (size_t)row * 1024 + cb + 16 + fq * 4);
;             store_pair16(H2B + (size_t)row * 1024 + cb, pack4(v0), pack4(v1), fq);
;             ss += v0[0] * v0[0] + v0[1] * v0[1] + v0[2] * v0[2] + v0[3] * v0[3] + v1[0] * v1[0] + v1[1] * v1[1] + v1[2] * v1[2] + v1[3] * v1[3];
;           }
;         ss += shfl_xor_f(ss, 16); ss += shfl_xor_f(ss, 32);
;         if (fq == 0) PS[(size_t)row * 16 + pn * 4 + wc] = ss;
	v_pk_add_f32 v[100:101], v[100:101], v[104:105]
	v_pk_add_f32 v[102:103], v[102:103], v[106:107]
	s_waitcnt vmcnt(0)
	v_pk_add_f32 v[106:107], v[96:97], v[108:109]
	v_cvt_pk_bf16_f32 v96, v100, v101
	v_mul_f32_e32 v101, v101, v101
	v_fmac_f32_e32 v101, v100, v100
	v_fmac_f32_e32 v101, v102, v102
	v_pk_add_f32 v[104:105], v[98:99], v[110:111]
	v_fmac_f32_e32 v101, v103, v103
	v_cvt_pk_bf16_f32 v97, v102, v103
	v_cvt_pk_bf16_f32 v98, v106, v107
	v_cvt_pk_bf16_f32 v99, v104, v105
	v_fmac_f32_e32 v101, v106, v106
	v_permlane16_swap_b32_e32 v96, v98
	v_permlane16_swap_b32_e32 v97, v99
	v_fmac_f32_e32 v101, v107, v107
	global_store_dwordx4 v[124:125], v[96:99], off offset:256 sc1
	v_fmac_f32_e32 v101, v104, v104
	v_fmac_f32_e32 v101, v105, v105
	v_mbcnt_lo_u32_b32 v96, -1, 0
	v_mbcnt_hi_u32_b32 v96, -1, v96
	v_add_f32_e32 v97, v115, v101
	v_lshlrev_b32_e32 v96, 2, v96
	v_xor_b32_e32 v96, 64, v96
	v_mov_b32_e32 v96, v97
	s_nop 1
	v_permlane16_swap_b32_e32 v96, v97
	v_mbcnt_lo_u32_b32 v98, -1, 0
	v_mbcnt_hi_u32_b32 v98, -1, v98
	s_waitcnt lgkmcnt(0)
	v_add_f32_e32 v96, v97, v96
	v_lshlrev_b32_e32 v98, 2, v98
	v_xor_b32_e32 v97, 0x80, v98
	ds_bpermute_b32 v97, v97, v96
	s_and_saveexec_b64 s[36:37], vcc
	s_cbranch_execz .LBB0_987
	s_waitcnt lgkmcnt(0)
	v_add_f32_e32 v98, v96, v97
	v_lshlrev_b64 v[96:97], 6, v[112:113]
	v_lshl_add_u64 v[96:97], s[30:31], 0, v[96:97]
	global_store_dword v[96:97], v98, off
.LBB0_987:
	s_or_b64 exec, exec, s[36:37]
	v_or_b32_e32 v96, 32, v128
	s_waitcnt lgkmcnt(0)
	v_mov_b32_e32 v97, v129
	v_readlane_b32 s72, v251, 6
	v_lshlrev_b64 v[98:99], 12, v[96:97]
	v_readlane_b32 s73, v251, 7
	v_lshlrev_b64 v[108:109], 11, v[96:97]
	s_mov_b32 s35, s11
	v_lshl_add_u64 v[98:99], s[72:73], 0, v[98:99]
	v_lshl_add_u64 v[98:99], v[98:99], 0, s[10:11]
	v_lshl_add_u64 v[106:107], v[130:131], 2, v[98:99]
	global_load_dwordx4 v[98:101], v[106:107], off
	global_load_dwordx4 v[102:105], v[106:107], off offset:64
	v_lshl_add_u64 v[108:109], v[132:133], 0, v[108:109]
	v_lshl_add_u64 v[108:109], v[108:109], 0, s[34:35]
	v_readlane_b32 s74, v251, 8
	v_readlane_b32 s75, v251, 9
	v_readlane_b32 s76, v251, 10
	v_readlane_b32 s77, v251, 11
	v_readlane_b32 s78, v251, 12
	v_readlane_b32 s79, v251, 13
	v_readlane_b32 s80, v251, 14
	v_readlane_b32 s81, v251, 15
	v_readlane_b32 s82, v251, 16
	v_readlane_b32 s83, v251, 17
	v_readlane_b32 s84, v251, 18
	v_readlane_b32 s85, v251, 19
	v_readlane_b32 s86, v251, 20
	v_readlane_b32 s87, v251, 21
	s_waitcnt vmcnt(1)
	v_pk_add_f32 v[100:101], v[90:91], v[100:101]
	v_pk_add_f32 v[98:99], v[88:89], v[98:99]
	s_waitcnt vmcnt(0)
	v_pk_add_f32 v[104:105], v[94:95], v[104:105]
	v_pk_add_f32 v[102:103], v[92:93], v[102:103]
	v_cvt_pk_bf16_f32 v88, v98, v99
	v_cvt_pk_bf16_f32 v89, v100, v101
	v_cvt_pk_bf16_f32 v90, v102, v103
	v_cvt_pk_bf16_f32 v91, v104, v105
	s_nop 0
	v_permlane16_swap_b32_e32 v88, v90
	v_permlane16_swap_b32_e32 v89, v91
	global_store_dwordx4 v[108:109], v[88:91], off sc1
	global_load_dwordx4 v[88:91], v[106:107], off offset:512
	s_nop 0
	global_load_dwordx4 v[92:95], v[106:107], off offset:576
	v_mul_f32_e32 v99, v99, v99
	v_fmac_f32_e32 v99, v98, v98
	v_fmac_f32_e32 v99, v100, v100
	v_fmac_f32_e32 v99, v101, v101
	v_fmac_f32_e32 v99, v102, v102
	v_fmac_f32_e32 v99, v103, v103
	v_fmac_f32_e32 v99, v104, v104
	v_fmac_f32_e32 v99, v105, v105
	s_waitcnt vmcnt(1)
	v_pk_add_f32 v[84:85], v[84:85], v[88:89]
	v_pk_add_f32 v[86:87], v[86:87], v[90:91]
	s_waitcnt vmcnt(0)
	v_pk_add_f32 v[90:91], v[80:81], v[92:93]
	v_cvt_pk_bf16_f32 v80, v84, v85
	v_mul_f32_e32 v85, v85, v85
	v_fmac_f32_e32 v85, v84, v84
	v_fmac_f32_e32 v85, v86, v86
	v_pk_add_f32 v[88:89], v[82:83], v[94:95]
	v_fmac_f32_e32 v85, v87, v87
	v_cvt_pk_bf16_f32 v81, v86, v87
	v_cvt_pk_bf16_f32 v82, v90, v91
	v_cvt_pk_bf16_f32 v83, v88, v89
	v_fmac_f32_e32 v85, v90, v90
	v_permlane16_swap_b32_e32 v80, v82
	v_permlane16_swap_b32_e32 v81, v83
	v_fmac_f32_e32 v85, v91, v91
	global_store_dwordx4 v[108:109], v[80:83], off offset:256 sc1
	v_fmac_f32_e32 v85, v88, v88
	v_fmac_f32_e32 v85, v89, v89
	v_mbcnt_lo_u32_b32 v80, -1, 0
	v_mbcnt_hi_u32_b32 v80, -1, v80
	v_add_f32_e32 v81, v99, v85
	v_lshlrev_b32_e32 v80, 2, v80
	v_xor_b32_e32 v80, 64, v80
	v_mov_b32_e32 v80, v81
	s_nop 1
	v_permlane16_swap_b32_e32 v80, v81
	v_mbcnt_lo_u32_b32 v82, -1, 0
	v_mbcnt_hi_u32_b32 v82, -1, v82
	s_waitcnt lgkmcnt(0)
	v_add_f32_e32 v80, v81, v80
	v_lshlrev_b32_e32 v82, 2, v82
	v_xor_b32_e32 v81, 0x80, v82
	ds_bpermute_b32 v81, v81, v80
	s_and_saveexec_b64 s[36:37], vcc
	s_cbranch_execz .LBB0_989
	s_waitcnt lgkmcnt(0)
	v_add_f32_e32 v82, v80, v81
	v_lshlrev_b64 v[80:81], 6, v[96:97]
	v_lshl_add_u64 v[80:81], s[30:31], 0, v[80:81]
	global_store_dword v[80:81], v82, off
; __device__ __forceinline__ u32x2 pack4(f32x4 v) { u32x2 r; r.x = cvt_pk(v[0], v[1]); r.y = cvt_pk(v[2], v[3]); return r; }
; __device__ __forceinline__ float shfl_xor_f(float v, int mask) { const int l = lane_fresh(); return __int_as_float(__builtin_amdgcn_ds_bpermute((l ^ mask) << 2, __float_as_int(v))); }
; __device__ __forceinline__ void phaseE(const Params& p, const int wv, const int rep) {
;     ...
;     for (int ai = 0; ai < 2; ++ai)
; #pragma unroll
;       for (int m = 0; m < 4; ++m) {
;         const int row = brow + ai * 128 + wr * 64 + m * 16 + fr;
;         float ss = 0.f;
; #pragma unroll
;         for (int bj = 0; bj < 2; ++bj)
;           {
;             const int cb = bcol + bj * 128 + wc * 32;
;             f32x4 v0 = acc[ai][bj][m][0] + *(const f32x4*)(p.in[0] + (size_t)row * 1024 + cb + fq * 4);
;             f32x4 v1 = acc[ai][bj][m][1] + *(const f32x4*)(p.in[0] + (size_t)row * 1024 + cb + 16 + fq * 4);
;             store_pair16(H2B + (size_t)row * 1024 + cb, pack4(v0), pack4(v1), fq);
;             ss += v0[0] * v0[0] + v0[1] * v0[1] + v0[2] * v0[2] + v0[3] * v0[3] + v1[0] * v1[0] + v1[1] * v1[1] + v1[2] * v1[2] + v1[3] * v1[3];
;           }
;         ss += shfl_xor_f(ss, 16); ss += shfl_xor_f(ss, 32);
;         if (fq == 0) PS[(size_t)row * 16 + pn * 4 + wc] = ss;
.LBB0_989:
	s_or_b64 exec, exec, s[36:37]
	v_or_b32_e32 v80, 48, v128
	s_waitcnt lgkmcnt(0)
	v_mov_b32_e32 v81, v129
	v_readlane_b32 s72, v251, 6
	v_lshlrev_b64 v[82:83], 12, v[80:81]
	v_readlane_b32 s73, v251, 7
	v_lshlrev_b64 v[92:93], 11, v[80:81]
	v_lshl_add_u64 v[92:93], v[132:133], 0, v[92:93]
	v_lshl_add_u64 v[82:83], s[72:73], 0, v[82:83]
	v_lshl_add_u64 v[82:83], v[82:83], 0, s[10:11]
	v_lshl_add_u64 v[90:91], v[130:131], 2, v[82:83]
	global_load_dwordx4 v[82:85], v[90:91], off
	global_load_dwordx4 v[86:89], v[90:91], off offset:64
	v_lshl_add_u64 v[92:93], v[92:93], 0, s[34:35]
	v_readlane_b32 s74, v251, 8
	v_readlane_b32 s75, v251, 9
	v_readlane_b32 s76, v251, 10
	v_readlane_b32 s77, v251, 11
	v_readlane_b32 s78, v251, 12
	v_readlane_b32 s79, v251, 13
	v_readlane_b32 s80, v251, 14
	v_readlane_b32 s81, v251, 15
	v_readlane_b32 s82, v251, 16
	v_readlane_b32 s83, v251, 17
	v_readlane_b32 s84, v251, 18
	v_readlane_b32 s85, v251, 19
	v_readlane_b32 s86, v251, 20
	v_readlane_b32 s87, v251, 21
	s_waitcnt vmcnt(1)
	v_pk_add_f32 v[84:85], v[74:75], v[84:85]
	v_pk_add_f32 v[82:83], v[72:73], v[82:83]
	s_waitcnt vmcnt(0)
	v_pk_add_f32 v[88:89], v[78:79], v[88:89]
	v_pk_add_f32 v[86:87], v[76:77], v[86:87]
	v_cvt_pk_bf16_f32 v72, v82, v83
	v_cvt_pk_bf16_f32 v73, v84, v85
	v_cvt_pk_bf16_f32 v74, v86, v87
	v_cvt_pk_bf16_f32 v75, v88, v89
	s_nop 0
	v_permlane16_swap_b32_e32 v72, v74
	v_permlane16_swap_b32_e32 v73, v75
	global_store_dwordx4 v[92:93], v[72:75], off sc1
	global_load_dwordx4 v[72:75], v[90:91], off offset:512
	s_nop 0
	global_load_dwordx4 v[76:79], v[90:91], off offset:576
	v_mul_f32_e32 v83, v83, v83
	v_fmac_f32_e32 v83, v82, v82
	v_fmac_f32_e32 v83, v84, v84
	v_fmac_f32_e32 v83, v85, v85
	v_fmac_f32_e32 v83, v86, v86
	v_fmac_f32_e32 v83, v87, v87
	v_fmac_f32_e32 v83, v88, v88
	v_fmac_f32_e32 v83, v89, v89
	s_waitcnt vmcnt(1)
	v_pk_add_f32 v[68:69], v[68:69], v[72:73]
	v_pk_add_f32 v[70:71], v[70:71], v[74:75]
	s_waitcnt vmcnt(0)
	v_pk_add_f32 v[74:75], v[64:65], v[76:77]
	v_cvt_pk_bf16_f32 v64, v68, v69
	v_mul_f32_e32 v69, v69, v69
	v_fmac_f32_e32 v69, v68, v68
	v_fmac_f32_e32 v69, v70, v70
	v_pk_add_f32 v[72:73], v[66:67], v[78:79]
	v_fmac_f32_e32 v69, v71, v71
	v_cvt_pk_bf16_f32 v65, v70, v71
	v_cvt_pk_bf16_f32 v66, v74, v75
	v_cvt_pk_bf16_f32 v67, v72, v73
	v_fmac_f32_e32 v69, v74, v74
	v_permlane16_swap_b32_e32 v64, v66
	v_permlane16_swap_b32_e32 v65, v67
	v_fmac_f32_e32 v69, v75, v75
	global_store_dwordx4 v[92:93], v[64:67], off offset:256 sc1
	v_fmac_f32_e32 v69, v72, v72
	v_fmac_f32_e32 v69, v73, v73
	v_mbcnt_lo_u32_b32 v64, -1, 0
	v_mbcnt_hi_u32_b32 v64, -1, v64
	v_add_f32_e32 v65, v83, v69
	v_lshlrev_b32_e32 v64, 2, v64
	v_xor_b32_e32 v64, 64, v64
	v_mov_b32_e32 v64, v65
	s_nop 1
	v_permlane16_swap_b32_e32 v64, v65
	v_mbcnt_lo_u32_b32 v66, -1, 0
	v_mbcnt_hi_u32_b32 v66, -1, v66
	s_waitcnt lgkmcnt(0)
	v_add_f32_e32 v64, v65, v64
	v_lshlrev_b32_e32 v66, 2, v66
	v_xor_b32_e32 v65, 0x80, v66
	ds_bpermute_b32 v65, v65, v64
	s_and_saveexec_b64 s[36:37], vcc
	s_cbranch_execz .LBB0_991
	s_waitcnt lgkmcnt(0)
	v_add_f32_e32 v66, v64, v65
	v_lshlrev_b64 v[64:65], 6, v[80:81]
	v_lshl_add_u64 v[64:65], s[30:31], 0, v[64:65]
	global_store_dword v[64:65], v66, off
.LBB0_991:
	s_or_b64 exec, exec, s[36:37]
	v_add_u32_e32 v64, 0x80, v128
	s_waitcnt lgkmcnt(0)
	v_mov_b32_e32 v65, v129
	v_readlane_b32 s72, v251, 6
	v_lshlrev_b64 v[66:67], 12, v[64:65]
	v_readlane_b32 s73, v251, 7
	v_lshlrev_b64 v[76:77], 11, v[64:65]
	s_mov_b32 s35, s11
	v_lshl_add_u64 v[66:67], s[72:73], 0, v[66:67]
	v_lshl_add_u64 v[66:67], v[66:67], 0, s[10:11]
	v_lshl_add_u64 v[74:75], v[130:131], 2, v[66:67]
	global_load_dwordx4 v[66:69], v[74:75], off
	global_load_dwordx4 v[70:73], v[74:75], off offset:64
	v_lshl_add_u64 v[76:77], v[132:133], 0, v[76:77]
	v_lshl_add_u64 v[76:77], v[76:77], 0, s[34:35]
	v_readlane_b32 s74, v251, 8
	v_readlane_b32 s75, v251, 9
	v_readlane_b32 s76, v251, 10
	v_readlane_b32 s77, v251, 11
	v_readlane_b32 s78, v251, 12
	v_readlane_b32 s79, v251, 13
	v_readlane_b32 s80, v251, 14
	v_readlane_b32 s81, v251, 15
	v_readlane_b32 s82, v251, 16
	v_readlane_b32 s83, v251, 17
	v_readlane_b32 s84, v251, 18
	v_readlane_b32 s85, v251, 19
	v_readlane_b32 s86, v251, 20
	v_readlane_b32 s87, v251, 21
	s_waitcnt vmcnt(1)
	v_pk_add_f32 v[68:69], v[58:59], v[68:69]
	v_pk_add_f32 v[66:67], v[56:57], v[66:67]
	s_waitcnt vmcnt(0)
	v_pk_add_f32 v[72:73], v[62:63], v[72:73]
	v_pk_add_f32 v[70:71], v[60:61], v[70:71]
	v_cvt_pk_bf16_f32 v56, v66, v67
	v_cvt_pk_bf16_f32 v57, v68, v69
	v_cvt_pk_bf16_f32 v58, v70, v71
	v_cvt_pk_bf16_f32 v59, v72, v73
	s_nop 0
	v_permlane16_swap_b32_e32 v56, v58
	v_permlane16_swap_b32_e32 v57, v59
	global_store_dwordx4 v[76:77], v[56:59], off sc1
	global_load_dwordx4 v[56:59], v[74:75], off offset:512
	s_nop 0
	global_load_dwordx4 v[60:63], v[74:75], off offset:576
	v_mul_f32_e32 v67, v67, v67
	v_fmac_f32_e32 v67, v66, v66
	v_fmac_f32_e32 v67, v68, v68
	v_fmac_f32_e32 v67, v69, v69
	v_fmac_f32_e32 v67, v70, v70
	v_fmac_f32_e32 v67, v71, v71
	v_fmac_f32_e32 v67, v72, v72
	v_fmac_f32_e32 v67, v73, v73
	s_waitcnt vmcnt(1)
	v_pk_add_f32 v[52:53], v[52:53], v[56:57]
	v_pk_add_f32 v[54:55], v[54:55], v[58:59]
	s_waitcnt vmcnt(0)
	v_pk_add_f32 v[58:59], v[48:49], v[60:61]
	v_cvt_pk_bf16_f32 v48, v52, v53
	v_mul_f32_e32 v53, v53, v53
	v_fmac_f32_e32 v53, v52, v52
	v_fmac_f32_e32 v53, v54, v54
	v_pk_add_f32 v[56:57], v[50:51], v[62:63]
	v_fmac_f32_e32 v53, v55, v55
	v_cvt_pk_bf16_f32 v49, v54, v55
	v_cvt_pk_bf16_f32 v50, v58, v59
	v_cvt_pk_bf16_f32 v51, v56, v57
	v_fmac_f32_e32 v53, v58, v58
	v_permlane16_swap_b32_e32 v48, v50
	v_permlane16_swap_b32_e32 v49, v51
	v_fmac_f32_e32 v53, v59, v59
	global_store_dwordx4 v[76:77], v[48:51], off offset:256 sc1
	v_fmac_f32_e32 v53, v56, v56
	v_fmac_f32_e32 v53, v57, v57
	v_mbcnt_lo_u32_b32 v48, -1, 0
	v_mbcnt_hi_u32_b32 v48, -1, v48
	v_add_f32_e32 v49, v67, v53
	v_lshlrev_b32_e32 v48, 2, v48
	v_xor_b32_e32 v48, 64, v48
	v_mov_b32_e32 v48, v49
	s_nop 1
	v_permlane16_swap_b32_e32 v48, v49
	v_mbcnt_lo_u32_b32 v50, -1, 0
	v_mbcnt_hi_u32_b32 v50, -1, v50
	s_waitcnt lgkmcnt(0)
	v_add_f32_e32 v48, v49, v48
	v_lshlrev_b32_e32 v50, 2, v50
	v_xor_b32_e32 v49, 0x80, v50
	ds_bpermute_b32 v49, v49, v48
	s_and_saveexec_b64 s[36:37], vcc
	s_cbranch_execz .LBB0_993
	s_waitcnt lgkmcnt(0)
	v_add_f32_e32 v50, v48, v49
	v_lshlrev_b64 v[48:49], 6, v[64:65]
	v_lshl_add_u64 v[48:49], s[30:31], 0, v[48:49]
	global_store_dword v[48:49], v50, off
; __device__ __forceinline__ u32x2 pack4(f32x4 v) { u32x2 r; r.x = cvt_pk(v[0], v[1]); r.y = cvt_pk(v[2], v[3]); return r; }
; __device__ __forceinline__ float shfl_xor_f(float v, int mask) { const int l = lane_fresh(); return __int_as_float(__builtin_amdgcn_ds_bpermute((l ^ mask) << 2, __float_as_int(v))); }
; __device__ __forceinline__ void phaseE(const Params& p, const int wv, const int rep) {
;     ...
;     for (int ai = 0; ai < 2; ++ai)
; #pragma unroll
;       for (int m = 0; m < 4; ++m) {
;         const int row = brow + ai * 128 + wr * 64 + m * 16 + fr;
;         float ss = 0.f;
; #pragma unroll
;         for (int bj = 0; bj < 2; ++bj)
;           {
;             const int cb = bcol + bj * 128 + wc * 32;
;             f32x4 v0 = acc[ai][bj][m][0] + *(const f32x4*)(p.in[0] + (size_t)row * 1024 + cb + fq * 4);
;             f32x4 v1 = acc[ai][bj][m][1] + *(const f32x4*)(p.in[0] + (size_t)row * 1024 + cb + 16 + fq * 4);
;             store_pair16(H2B + (size_t)row * 1024 + cb, pack4(v0), pack4(v1), fq);
;             ss += v0[0] * v0[0] + v0[1] * v0[1] + v0[2] * v0[2] + v0[3] * v0[3] + v1[0] * v1[0] + v1[1] * v1[1] + v1[2] * v1[2] + v1[3] * v1[3];
;           }
;         ss += shfl_xor_f(ss, 16); ss += shfl_xor_f(ss, 32);
;         if (fq == 0) PS[(size_t)row * 16 + pn * 4 + wc] = ss;
.LBB0_993:
	s_or_b64 exec, exec, s[36:37]
	v_add_u32_e32 v48, 0x90, v128
	s_waitcnt lgkmcnt(0)
	v_mov_b32_e32 v49, v129
	v_readlane_b32 s72, v251, 6
	v_lshlrev_b64 v[50:51], 12, v[48:49]
	v_readlane_b32 s73, v251, 7
	v_lshlrev_b64 v[60:61], 11, v[48:49]
	v_lshl_add_u64 v[60:61], v[132:133], 0, v[60:61]
	v_lshl_add_u64 v[50:51], s[72:73], 0, v[50:51]
	v_lshl_add_u64 v[50:51], v[50:51], 0, s[10:11]
	v_lshl_add_u64 v[58:59], v[130:131], 2, v[50:51]
	global_load_dwordx4 v[50:53], v[58:59], off
	global_load_dwordx4 v[54:57], v[58:59], off offset:64
	v_lshl_add_u64 v[60:61], v[60:61], 0, s[34:35]
	v_readlane_b32 s74, v251, 8
	v_readlane_b32 s75, v251, 9
	v_readlane_b32 s76, v251, 10
	v_readlane_b32 s77, v251, 11
	v_readlane_b32 s78, v251, 12
	v_readlane_b32 s79, v251, 13
	v_readlane_b32 s80, v251, 14
	v_readlane_b32 s81, v251, 15
	v_readlane_b32 s82, v251, 16
	v_readlane_b32 s83, v251, 17
	v_readlane_b32 s84, v251, 18
	v_readlane_b32 s85, v251, 19
	v_readlane_b32 s86, v251, 20
	v_readlane_b32 s87, v251, 21
	s_waitcnt vmcnt(1)
	v_pk_add_f32 v[52:53], v[42:43], v[52:53]
	v_pk_add_f32 v[50:51], v[40:41], v[50:51]
	s_waitcnt vmcnt(0)
	v_pk_add_f32 v[56:57], v[46:47], v[56:57]
	v_pk_add_f32 v[54:55], v[44:45], v[54:55]
	v_cvt_pk_bf16_f32 v40, v50, v51
	v_cvt_pk_bf16_f32 v41, v52, v53
	v_cvt_pk_bf16_f32 v42, v54, v55
	v_cvt_pk_bf16_f32 v43, v56, v57
	s_nop 0
	v_permlane16_swap_b32_e32 v40, v42
	v_permlane16_swap_b32_e32 v41, v43
	global_store_dwordx4 v[60:61], v[40:43], off sc1
	global_load_dwordx4 v[40:43], v[58:59], off offset:512
	s_nop 0
	global_load_dwordx4 v[44:47], v[58:59], off offset:576
	v_mul_f32_e32 v51, v51, v51
	v_fmac_f32_e32 v51, v50, v50
	v_fmac_f32_e32 v51, v52, v52
	v_fmac_f32_e32 v51, v53, v53
	v_fmac_f32_e32 v51, v54, v54
	v_fmac_f32_e32 v51, v55, v55
	v_fmac_f32_e32 v51, v56, v56
	v_fmac_f32_e32 v51, v57, v57
	s_waitcnt vmcnt(1)
	v_pk_add_f32 v[36:37], v[36:37], v[40:41]
	v_pk_add_f32 v[38:39], v[38:39], v[42:43]
	s_waitcnt vmcnt(0)
	v_pk_add_f32 v[42:43], v[32:33], v[44:45]
	v_cvt_pk_bf16_f32 v32, v36, v37
	v_mul_f32_e32 v37, v37, v37
	v_fmac_f32_e32 v37, v36, v36
	v_fmac_f32_e32 v37, v38, v38
	v_pk_add_f32 v[40:41], v[34:35], v[46:47]
	v_fmac_f32_e32 v37, v39, v39
	v_cvt_pk_bf16_f32 v33, v38, v39
	v_cvt_pk_bf16_f32 v34, v42, v43
	v_cvt_pk_bf16_f32 v35, v40, v41
	v_fmac_f32_e32 v37, v42, v42
	v_permlane16_swap_b32_e32 v32, v34
	v_permlane16_swap_b32_e32 v33, v35
	v_fmac_f32_e32 v37, v43, v43
	global_store_dwordx4 v[60:61], v[32:35], off offset:256 sc1
	v_fmac_f32_e32 v37, v40, v40
	v_fmac_f32_e32 v37, v41, v41
	v_mbcnt_lo_u32_b32 v32, -1, 0
	v_mbcnt_hi_u32_b32 v32, -1, v32
	v_add_f32_e32 v33, v51, v37
	v_lshlrev_b32_e32 v32, 2, v32
	v_xor_b32_e32 v32, 64, v32
	v_mov_b32_e32 v32, v33
	s_nop 1
	v_permlane16_swap_b32_e32 v32, v33
	v_mbcnt_lo_u32_b32 v34, -1, 0
	v_mbcnt_hi_u32_b32 v34, -1, v34
	s_waitcnt lgkmcnt(0)
	v_add_f32_e32 v32, v33, v32
	v_lshlrev_b32_e32 v34, 2, v34
	v_xor_b32_e32 v33, 0x80, v34
	ds_bpermute_b32 v33, v33, v32
	s_and_saveexec_b64 s[36:37], vcc
	s_cbranch_execz .LBB0_995
	s_waitcnt lgkmcnt(0)
	v_add_f32_e32 v34, v32, v33
	v_lshlrev_b64 v[32:33], 6, v[48:49]
	v_lshl_add_u64 v[32:33], s[30:31], 0, v[32:33]
	global_store_dword v[32:33], v34, off
; __device__ __forceinline__ u32x2 pack4(f32x4 v) { u32x2 r; r.x = cvt_pk(v[0], v[1]); r.y = cvt_pk(v[2], v[3]); return r; }
; __device__ __forceinline__ float shfl_xor_f(float v, int mask) { const int l = lane_fresh(); return __int_as_float(__builtin_amdgcn_ds_bpermute((l ^ mask) << 2, __float_as_int(v))); }
; __device__ __forceinline__ void phaseE(const Params& p, const int wv, const int rep) {
;     ...
;     for (int ai = 0; ai < 2; ++ai)
; #pragma unroll
;       for (int m = 0; m < 4; ++m) {
;         const int row = brow + ai * 128 + wr * 64 + m * 16 + fr;
;         float ss = 0.f;
; #pragma unroll
;         for (int bj = 0; bj < 2; ++bj)
;           {
;             const int cb = bcol + bj * 128 + wc * 32;
;             f32x4 v0 = acc[ai][bj][m][0] + *(const f32x4*)(p.in[0] + (size_t)row * 1024 + cb + fq * 4);
;             f32x4 v1 = acc[ai][bj][m][1] + *(const f32x4*)(p.in[0] + (size_t)row * 1024 + cb + 16 + fq * 4);
;             store_pair16(H2B + (size_t)row * 1024 + cb, pack4(v0), pack4(v1), fq);
;             ss += v0[0] * v0[0] + v0[1] * v0[1] + v0[2] * v0[2] + v0[3] * v0[3] + v1[0] * v1[0] + v1[1] * v1[1] + v1[2] * v1[2] + v1[3] * v1[3];
;           }
;         ss += shfl_xor_f(ss, 16); ss += shfl_xor_f(ss, 32);
;         if (fq == 0) PS[(size_t)row * 16 + pn * 4 + wc] = ss;
.LBB0_995:
	s_or_b64 exec, exec, s[36:37]
	v_add_u32_e32 v32, 0xa0, v128
	s_waitcnt lgkmcnt(0)
	v_mov_b32_e32 v33, v129
	v_readlane_b32 s72, v251, 6
	v_lshlrev_b64 v[34:35], 12, v[32:33]
	v_readlane_b32 s73, v251, 7
	v_lshlrev_b64 v[44:45], 11, v[32:33]
	s_mov_b32 s35, s11
	v_lshl_add_u64 v[34:35], s[72:73], 0, v[34:35]
	v_lshl_add_u64 v[34:35], v[34:35], 0, s[10:11]
	v_lshl_add_u64 v[42:43], v[130:131], 2, v[34:35]
	global_load_dwordx4 v[34:37], v[42:43], off
	global_load_dwordx4 v[38:41], v[42:43], off offset:64
	v_lshl_add_u64 v[44:45], v[132:133], 0, v[44:45]
	v_lshl_add_u64 v[44:45], v[44:45], 0, s[34:35]
	v_readlane_b32 s74, v251, 8
	v_readlane_b32 s75, v251, 9
	v_readlane_b32 s76, v251, 10
	v_readlane_b32 s77, v251, 11
	v_readlane_b32 s78, v251, 12
	v_readlane_b32 s79, v251, 13
	v_readlane_b32 s80, v251, 14
	v_readlane_b32 s81, v251, 15
	v_readlane_b32 s82, v251, 16
	v_readlane_b32 s83, v251, 17
	v_readlane_b32 s84, v251, 18
	v_readlane_b32 s85, v251, 19
	v_readlane_b32 s86, v251, 20
	v_readlane_b32 s87, v251, 21
	s_waitcnt vmcnt(1)
	v_pk_add_f32 v[36:37], v[26:27], v[36:37]
	v_pk_add_f32 v[34:35], v[24:25], v[34:35]
	s_waitcnt vmcnt(0)
	v_pk_add_f32 v[40:41], v[30:31], v[40:41]
	v_pk_add_f32 v[38:39], v[28:29], v[38:39]
	v_cvt_pk_bf16_f32 v24, v34, v35
	v_cvt_pk_bf16_f32 v25, v36, v37
	v_cvt_pk_bf16_f32 v26, v38, v39
	v_cvt_pk_bf16_f32 v27, v40, v41
	s_nop 0
	v_permlane16_swap_b32_e32 v24, v26
	v_permlane16_swap_b32_e32 v25, v27
	global_store_dwordx4 v[44:45], v[24:27], off sc1
	global_load_dwordx4 v[24:27], v[42:43], off offset:512
	s_nop 0
	global_load_dwordx4 v[28:31], v[42:43], off offset:576
	v_mul_f32_e32 v35, v35, v35
	v_fmac_f32_e32 v35, v34, v34
	v_fmac_f32_e32 v35, v36, v36
	v_fmac_f32_e32 v35, v37, v37
	v_fmac_f32_e32 v35, v38, v38
	v_fmac_f32_e32 v35, v39, v39
	v_fmac_f32_e32 v35, v40, v40
	v_fmac_f32_e32 v35, v41, v41
	s_waitcnt vmcnt(1)
	v_pk_add_f32 v[20:21], v[20:21], v[24:25]
	v_pk_add_f32 v[22:23], v[22:23], v[26:27]
	s_waitcnt vmcnt(0)
	v_pk_add_f32 v[26:27], v[16:17], v[28:29]
	v_cvt_pk_bf16_f32 v16, v20, v21
	v_mul_f32_e32 v21, v21, v21
	v_fmac_f32_e32 v21, v20, v20
	v_fmac_f32_e32 v21, v22, v22
	v_pk_add_f32 v[24:25], v[18:19], v[30:31]
	v_fmac_f32_e32 v21, v23, v23
	v_cvt_pk_bf16_f32 v17, v22, v23
	v_cvt_pk_bf16_f32 v18, v26, v27
	v_cvt_pk_bf16_f32 v19, v24, v25
	v_fmac_f32_e32 v21, v26, v26
	v_permlane16_swap_b32_e32 v16, v18
	v_permlane16_swap_b32_e32 v17, v19
	v_fmac_f32_e32 v21, v27, v27
	global_store_dwordx4 v[44:45], v[16:19], off offset:256 sc1
	v_fmac_f32_e32 v21, v24, v24
	v_fmac_f32_e32 v21, v25, v25
	v_mbcnt_lo_u32_b32 v16, -1, 0
	v_mbcnt_hi_u32_b32 v16, -1, v16
	v_add_f32_e32 v17, v35, v21
	v_lshlrev_b32_e32 v16, 2, v16
	v_xor_b32_e32 v16, 64, v16
	v_mov_b32_e32 v16, v17
	s_nop 1
	v_permlane16_swap_b32_e32 v16, v17
	v_mbcnt_lo_u32_b32 v18, -1, 0
	v_mbcnt_hi_u32_b32 v18, -1, v18
	s_waitcnt lgkmcnt(0)
	v_add_f32_e32 v16, v17, v16
	v_lshlrev_b32_e32 v18, 2, v18
	v_xor_b32_e32 v17, 0x80, v18
	ds_bpermute_b32 v17, v17, v16
	s_and_saveexec_b64 s[36:37], vcc
	s_cbranch_execz .LBB0_997
	s_waitcnt lgkmcnt(0)
	v_add_f32_e32 v18, v16, v17
	v_lshlrev_b64 v[16:17], 6, v[32:33]
	v_lshl_add_u64 v[16:17], s[30:31], 0, v[16:17]
	global_store_dword v[16:17], v18, off
.LBB0_997:
	s_or_b64 exec, exec, s[36:37]
	v_add_u32_e32 v128, 0xb0, v128
	v_readlane_b32 s72, v251, 6
	s_waitcnt lgkmcnt(0)
	v_lshlrev_b64 v[16:17], 12, v[128:129]
	v_readlane_b32 s73, v251, 7
	v_lshlrev_b64 v[26:27], 11, v[128:129]
	v_lshl_add_u64 v[26:27], v[132:133], 0, v[26:27]
	v_lshl_add_u64 v[16:17], s[72:73], 0, v[16:17]
	v_lshl_add_u64 v[16:17], v[16:17], 0, s[10:11]
	v_lshl_add_u64 v[24:25], v[130:131], 2, v[16:17]
	global_load_dwordx4 v[16:19], v[24:25], off
	global_load_dwordx4 v[20:23], v[24:25], off offset:64
	v_lshl_add_u64 v[26:27], v[26:27], 0, s[34:35]
	v_readlane_b32 s74, v251, 8
	v_readlane_b32 s75, v251, 9
	v_readlane_b32 s76, v251, 10
	v_readlane_b32 s77, v251, 11
	v_readlane_b32 s78, v251, 12
	v_readlane_b32 s79, v251, 13
	v_readlane_b32 s80, v251, 14
	v_readlane_b32 s81, v251, 15
	v_readlane_b32 s82, v251, 16
	v_readlane_b32 s83, v251, 17
	v_readlane_b32 s84, v251, 18
	v_readlane_b32 s85, v251, 19
	v_readlane_b32 s86, v251, 20
	v_readlane_b32 s87, v251, 21
	s_waitcnt vmcnt(1)
	v_pk_add_f32 v[18:19], v[10:11], v[18:19]
	v_pk_add_f32 v[16:17], v[8:9], v[16:17]
	s_waitcnt vmcnt(0)
	v_pk_add_f32 v[22:23], v[14:15], v[22:23]
	v_pk_add_f32 v[20:21], v[12:13], v[20:21]
	v_cvt_pk_bf16_f32 v8, v16, v17
	v_cvt_pk_bf16_f32 v9, v18, v19
	v_cvt_pk_bf16_f32 v10, v20, v21
	v_cvt_pk_bf16_f32 v11, v22, v23
	s_nop 0
	v_permlane16_swap_b32_e32 v8, v10
	v_permlane16_swap_b32_e32 v9, v11
	global_store_dwordx4 v[26:27], v[8:11], off sc1
	global_load_dwordx4 v[8:11], v[24:25], off offset:512
	s_nop 0
	global_load_dwordx4 v[12:15], v[24:25], off offset:576
	v_mul_f32_e32 v17, v17, v17
	v_fmac_f32_e32 v17, v16, v16
	v_fmac_f32_e32 v17, v18, v18
	v_fmac_f32_e32 v17, v19, v19
	v_fmac_f32_e32 v17, v20, v20
	v_fmac_f32_e32 v17, v21, v21
	v_fmac_f32_e32 v17, v22, v22
	v_fmac_f32_e32 v17, v23, v23
	s_waitcnt vmcnt(1)
	v_pk_add_f32 v[4:5], v[4:5], v[8:9]
	v_pk_add_f32 v[6:7], v[6:7], v[10:11]
	s_waitcnt vmcnt(0)
	v_pk_add_f32 v[10:11], v[0:1], v[12:13]
	v_cvt_pk_bf16_f32 v0, v4, v5
	v_mul_f32_e32 v5, v5, v5
	v_fmac_f32_e32 v5, v4, v4
	v_fmac_f32_e32 v5, v6, v6
	v_pk_add_f32 v[8:9], v[2:3], v[14:15]
	v_fmac_f32_e32 v5, v7, v7
	v_cvt_pk_bf16_f32 v1, v6, v7
	v_cvt_pk_bf16_f32 v2, v10, v11
	v_cvt_pk_bf16_f32 v3, v8, v9
	v_fmac_f32_e32 v5, v10, v10
	v_permlane16_swap_b32_e32 v0, v2
	v_permlane16_swap_b32_e32 v1, v3
	v_fmac_f32_e32 v5, v11, v11
	global_store_dwordx4 v[26:27], v[0:3], off offset:256 sc1
	v_fmac_f32_e32 v5, v8, v8
	v_fmac_f32_e32 v5, v9, v9
	v_mbcnt_lo_u32_b32 v0, -1, 0
	v_mbcnt_hi_u32_b32 v0, -1, v0
	v_add_f32_e32 v1, v17, v5
	v_lshlrev_b32_e32 v0, 2, v0
	v_xor_b32_e32 v0, 64, v0
	v_mov_b32_e32 v0, v1
	s_nop 1
	v_permlane16_swap_b32_e32 v0, v1
	v_mbcnt_lo_u32_b32 v2, -1, 0
	v_mbcnt_hi_u32_b32 v2, -1, v2
	s_waitcnt lgkmcnt(0)
	v_add_f32_e32 v0, v1, v0
	v_lshlrev_b32_e32 v2, 2, v2
	v_xor_b32_e32 v1, 0x80, v2
	ds_bpermute_b32 v1, v1, v0
	s_and_saveexec_b64 s[34:35], vcc
	s_cbranch_execz .LBB0_976
	s_waitcnt lgkmcnt(0)
	v_add_f32_e32 v2, v0, v1
	v_lshlrev_b64 v[0:1], 6, v[128:129]
	v_lshl_add_u64 v[0:1], s[30:31], 0, v[0:1]
	global_store_dword v[0:1], v2, off
	s_branch .LBB0_976

; __device__ __forceinline__ u32x2 pack4(f32x4 v) { u32x2 r; r.x = cvt_pk(v[0], v[1]); r.y = cvt_pk(v[2], v[3]); return r; }
; __device__ __forceinline__ int lane_fresh() { int l; asm volatile("v_mbcnt_lo_u32_b32 %0, -1, 0\n\tv_mbcnt_hi_u32_b32 %0, -1, %0" : "=v"(l)); return l; }
; #define MFMA16(a, b, c) __builtin_amdgcn_mfma_f32_16x16x32_bf16((a), (b), (c), 0, 0, 0)
; template <int NT, class FA, class FB, class FL>
; __device__ __forceinline__ void skgemm(FA aptr, FB bptr, FL ldf, const int KS, const int wv) {
;   float* part = (float*)g_shm;
;   const int lane = lane_fresh(), fr = lane & 15, fq = lane >> 4;
;   __syncthreads();
; #pragma unroll
;   for (int i = 0; i < NT; ++i) {
;     f32x4 acc = {0.f, 0.f, 0.f, 0.f};
;     const int ld = ldf(i);
;     const u16* ap = aptr(i) + (size_t)fr * ld + wv * KS + fq * 8;
;     const u16* bp = bptr(i) + (size_t)fr * ld + wv * KS + fq * 8;
; #pragma unroll 8
;     for (int k = 0; k < KS; k += 32) acc = MFMA16(*(const bf16x8*)(bp + k), *(const bf16x8*)(ap + k), acc);
;     *(f32x4*)(part + ((i * 8 + wv) * 64 + lane) * 4) = acc;
;   }
;   __syncthreads();
; }
; __device__ __forceinline__ f32x4 skreduce(int i) {
;   const float* part = (const float*)g_shm;
;   const int lane = lane_fresh();
;   f32x4 s = {0.f, 0.f, 0.f, 0.f};
; #pragma unroll
;   for (int w = 0; w < 8; ++w) s += *(const f32x4*)(part + ((i * 8 + w) * 64 + lane) * 4);
;   return s;
; }
; __device__ __forceinline__ void phaseE(const Params& p, const int wv, const int rep) {
;     ...
;   for (int gb = blockIdx.x; gb < 256; gb += gridDim.x) {
;     const int task0 = gb * 2, mt = task0 >> 6, nt0 = task0 & 63;
;     const u16* Ab = MERGED + (size_t)(TP + mt * 16) * 1024;
;     skgemm<2>([&](int) { return Ab; }, [&](int i) { return WOUT + (size_t)((nt0 + i) * 16) * 1024; }, [&](int) { return 1024; }, 128, wv);
;     if (wv < 2) {
;       const int lane_e = lane_fresh(), fr = lane_e & 15, fq = lane_e >> 4;
;       const int ntl = nt0 + wv, row = TP + mt * 16 + fr, col = ntl * 16 + fq * 4;
;       f32x4 v = skreduce(wv) + *(const f32x4*)(p.in[1] + (size_t)(row - TP) * 1024 + col);
;       *(u32x2*)(H2B + (size_t)row * 1024 + col) = pack4(v);
;       float ss = v[0] * v[0] + v[1] * v[1] + v[2] * v[2] + v[3] * v[3];
;       ss += shfl_xor_f(ss, 16); ss += shfl_xor_f(ss, 32);
;       if (fq == 0) PSS[(size_t)(row - TP) * 64 + ntl] = ss;
;     }
.Leh_skip:
	s_barrier
	global_load_dwordx4 v[2:5], v[40:41], off
	global_load_dwordx4 v[6:9], v[38:39], off
	v_add_co_u32_e32 v22, vcc, s22, v40
	v_lshl_add_u64 v[42:43], v[40:41], 0, s[14:15]
	s_nop 0
	v_addc_co_u32_e32 v23, vcc, 0, v41, vcc
	global_load_dwordx4 v[10:13], v[22:23], off
	global_load_dwordx4 v[14:17], v[40:41], off offset:64
	global_load_dwordx4 v[18:21], v[38:39], off offset:64
	v_lshl_add_u32 v0, v44, 4, s18
	global_load_dwordx4 v[22:25], v[42:43], off offset:64
	global_load_dwordx4 v[26:29], v[40:41], off offset:128
	global_load_dwordx4 v[30:33], v[38:39], off offset:128
	global_load_dwordx4 v[34:37], v[42:43], off offset:192
	s_and_b64 vcc, exec, s[4:5]
	s_waitcnt vmcnt(7)
	v_mfma_f32_16x16x32_bf16 v[2:5], v[2:5], v[6:9], 0
	s_waitcnt vmcnt(6)
	v_mfma_f32_16x16x32_bf16 v[6:9], v[10:13], v[6:9], 0
	global_load_dwordx4 v[10:13], v[42:43], off offset:128
	s_waitcnt vmcnt(5)
	v_mfma_f32_16x16x32_bf16 v[2:5], v[14:17], v[18:21], v[2:5]
	global_load_dwordx4 v[14:17], v[40:41], off offset:192
	s_waitcnt vmcnt(5)
	v_mfma_f32_16x16x32_bf16 v[6:9], v[22:25], v[18:21], v[6:9]
	global_load_dwordx4 v[18:21], v[38:39], off offset:192
	s_waitcnt vmcnt(4)
	v_mfma_f32_16x16x32_bf16 v[2:5], v[26:29], v[30:33], v[2:5]
	s_waitcnt vmcnt(2)
	v_mfma_f32_16x16x32_bf16 v[6:9], v[10:13], v[30:33], v[6:9]
	s_waitcnt vmcnt(0)
	v_mfma_f32_16x16x32_bf16 v[2:5], v[14:17], v[18:21], v[2:5]
	v_mfma_f32_16x16x32_bf16 v[6:9], v[34:37], v[18:21], v[6:9]
	s_nop 6
	ds_write_b128 v0, v[2:5]
	ds_write_b128 v0, v[6:9] offset:8192
	s_waitcnt lgkmcnt(0)
	s_barrier
	s_cbranch_vccnz .LBB0_1002
	v_mbcnt_lo_u32_b32 v44, -1, 0
	v_mbcnt_hi_u32_b32 v44, -1, v44
	s_or_b32 s0, s0, s90
	v_and_or_b32 v40, v44, 15, s16
	v_ashrrev_i32_e32 v0, 2, v44
	v_add_u32_e32 v2, 0xffffc000, v40
	v_and_b32_e32 v0, -4, v0
	v_ashrrev_i32_e32 v3, 31, v2
	v_readlane_b32 s52, v251, 6
	v_lshl_add_u32 v42, s0, 4, v0
	v_lshlrev_b64 v[4:5], 12, v[2:3]
	v_readlane_b32 s54, v251, 8
	v_readlane_b32 s55, v251, 9
	v_ashrrev_i32_e32 v43, 31, v42
	v_mbcnt_lo_u32_b32 v0, -1, 0
	v_mbcnt_hi_u32_b32 v0, -1, v0
	v_ashrrev_i32_e32 v41, 31, v40
	v_lshl_add_u64 v[4:5], s[54:55], 0, v[4:5]
	v_lshl_add_u64 v[4:5], v[42:43], 2, v[4:5]
	v_mov_b32_e32 v4, v104
	v_mov_b32_e32 v5, v105
	v_mov_b32_e32 v6, v106
	v_mov_b32_e32 v7, v107
	v_lshl_add_u32 v0, v0, 4, s19
	ds_read_b128 v[8:11], v0
	ds_read_b128 v[12:15], v0 offset:1024
	ds_read_b128 v[16:19], v0 offset:2048
	ds_read_b128 v[20:23], v0 offset:3072
	ds_read_b128 v[24:27], v0 offset:4096
	ds_read_b128 v[28:31], v0 offset:5120
	ds_read_b128 v[32:35], v0 offset:6144
	ds_read_b128 v[36:39], v0 offset:7168
	s_waitcnt lgkmcnt(7)
	v_pk_add_f32 v[10:11], v[10:11], 0 op_sel_hi:[1,0]
	v_pk_add_f32 v[8:9], v[8:9], 0 op_sel_hi:[1,0]
	s_waitcnt lgkmcnt(6)
	v_pk_add_f32 v[10:11], v[10:11], v[14:15]
	v_pk_add_f32 v[8:9], v[8:9], v[12:13]
	s_waitcnt lgkmcnt(5)
	v_pk_add_f32 v[10:11], v[10:11], v[18:19]
	v_pk_add_f32 v[8:9], v[8:9], v[16:17]
	s_waitcnt lgkmcnt(4)
	v_pk_add_f32 v[10:11], v[10:11], v[22:23]
	v_pk_add_f32 v[8:9], v[8:9], v[20:21]
	s_waitcnt lgkmcnt(3)
	v_pk_add_f32 v[10:11], v[10:11], v[26:27]
	v_pk_add_f32 v[8:9], v[8:9], v[24:25]
	s_waitcnt lgkmcnt(2)
	v_pk_add_f32 v[10:11], v[10:11], v[30:31]
	v_pk_add_f32 v[8:9], v[8:9], v[28:29]
	s_waitcnt lgkmcnt(1)
	v_pk_add_f32 v[10:11], v[10:11], v[34:35]
	v_pk_add_f32 v[8:9], v[8:9], v[32:33]
	v_lshlrev_b64 v[40:41], 11, v[40:41]
	s_waitcnt lgkmcnt(0)
	v_pk_add_f32 v[10:11], v[10:11], v[38:39]
	v_pk_add_f32 v[8:9], v[8:9], v[36:37]
	v_lshl_add_u64 v[40:41], s[8:9], 0, v[40:41]
	v_lshl_add_u64 v[40:41], v[42:43], 1, v[40:41]
	v_cmp_gt_u32_e32 vcc, 16, v44
	v_readlane_b32 s53, v251, 7
	v_readlane_b32 s56, v251, 10
	v_readlane_b32 s57, v251, 11
	v_readlane_b32 s58, v251, 12
	v_readlane_b32 s59, v251, 13
	v_readlane_b32 s60, v251, 14
	v_readlane_b32 s61, v251, 15
	v_readlane_b32 s62, v251, 16
	v_readlane_b32 s63, v251, 17
	v_readlane_b32 s64, v251, 18
	v_readlane_b32 s65, v251, 19
	v_readlane_b32 s66, v251, 20
	v_readlane_b32 s67, v251, 21
	s_waitcnt vmcnt(0)
	v_pk_add_f32 v[6:7], v[10:11], v[6:7]
	v_pk_add_f32 v[4:5], v[8:9], v[4:5]
	v_cvt_pk_bf16_f32 v9, v6, v7
	v_cvt_pk_bf16_f32 v8, v4, v5
	v_mul_f32_e32 v0, v5, v5
	global_store_dwordx2 v[40:41], v[8:9], off
	v_fmac_f32_e32 v0, v4, v4
	v_mbcnt_lo_u32_b32 v4, -1, 0
	v_mbcnt_hi_u32_b32 v4, -1, v4
	v_fmac_f32_e32 v0, v6, v6
	v_lshlrev_b32_e32 v4, 2, v4
	v_fmac_f32_e32 v0, v7, v7
	v_xor_b32_e32 v4, 64, v4
	v_mov_b32_e32 v4, v0
	s_nop 1
	v_permlane16_swap_b32_e32 v4, v0
	v_mbcnt_lo_u32_b32 v5, -1, 0
	v_mbcnt_hi_u32_b32 v5, -1, v5
	s_waitcnt lgkmcnt(0)
	v_add_f32_e32 v0, v0, v4
	v_lshlrev_b32_e32 v5, 2, v5
	v_xor_b32_e32 v4, 0x80, v5
	ds_bpermute_b32 v4, v4, v0
	s_and_saveexec_b64 s[16:17], vcc
	s_cbranch_execz .LBB0_1001
	v_lshlrev_b64 v[2:3], 8, v[2:3]
	v_lshl_add_u64 v[2:3], s[10:11], 0, v[2:3]
	s_lshl_b32 s0, s0, 2
	s_waitcnt lgkmcnt(0)
	v_add_f32_e32 v0, v0, v4
	v_lshl_add_u64 v[2:3], v[2:3], 0, s[0:1]
	global_store_dword v[2:3], v0, off
	s_branch .LBB0_1001

; __device__ __forceinline__ f32x4 unpack4(u32x2 w) { return (f32x4){bflo(w.x), bfhi(w.x), bflo(w.y), bfhi(w.y)}; }
; __device__ __forceinline__ float shfl_xor_f(float v, int mask) { const int l = lane_fresh(); return __int_as_float(__builtin_amdgcn_ds_bpermute((l ^ mask) << 2, __float_as_int(v))); }
; __device__ __forceinline__ void load_pair16(const u16* rowp32, int fq, u32x2& a, u32x2& b) {
;   const u32x4 w = *(const u32x4*)(rowp32 + ((fq & 1) * 16 + (fq >> 1) * 8));
;   auto rx = __builtin_amdgcn_permlane16_swap(w.x, w.z, false, false);
;   auto ry = __builtin_amdgcn_permlane16_swap(w.y, w.w, false, false);
;   a = (u32x2){rx[0], ry[0]}; b = (u32x2){rx[1], ry[1]};
; }
; __device__ __forceinline__ void phaseG(const Params& p, const int wv, const int rep, unsigned* bar, const bool fused) {
;     ...
;             const int rrow = ai * 128 + wr * 64 + m * 16 + fr;
;             float ss = 0.f;
; #pragma unroll
;             for (int bj = 0; bj < 2; ++bj) {
;               u32x2 hp[2];
;               load_pair16(H2 + (size_t)(brow + rrow) * 1024 + bcol + bj * 128 + wc * 32, fq, hp[0], hp[1]);
; #pragma unroll
;               for (int n = 0; n < 2; ++n) {
;                 f32x4 v = acc[ai][bj][m][n] + unpack4(hp[n]);
;                 acc[ai][bj][m][n] = v;
;                 ss += v[0] * v[0] + v[1] * v[1] + v[2] * v[2] + v[3] * v[3];
;               }
;             }
;             ss += shfl_xor_f(ss, 16); ss += shfl_xor_f(ss, 32);
;             if (fq == 0) red[rrow * 4 + wc] = ss;
;           }
.LBB0_1147:
	s_or_b64 exec, exec, s[4:5]
	v_or_b32_e32 v143, 16, v142
	v_add_u32_e32 v128, s87, v143
	s_waitcnt lgkmcnt(0)
	v_lshlrev_b64 v[120:121], 11, v[128:129]
	v_lshl_add_u64 v[124:125], v[138:139], 0, v[120:121]
	s_waitcnt vmcnt(12)
	v_mov_b32_e32 v120, v168
	v_mov_b32_e32 v121, v169
	v_mov_b32_e32 v122, v170
	v_mov_b32_e32 v123, v171
	s_nop 0
	v_mov_b32_e32 v124, v172
	v_mov_b32_e32 v125, v173
	v_mov_b32_e32 v126, v174
	v_mov_b32_e32 v127, v175
	v_mbcnt_lo_u32_b32 v128, -1, 0
	v_mbcnt_hi_u32_b32 v128, -1, v128
	v_mov_b32_e32 v145, v122
	v_mov_b32_e32 v147, v123
	s_nop 0
	v_permlane16_swap_b32_e32 v120, v145
	v_permlane16_swap_b32_e32 v121, v147
	v_permlane16_swap_b32_e32 v124, v126
	v_permlane16_swap_b32_e32 v125, v127
	v_lshlrev_b32_e32 v122, 16, v120
	v_and_b32_e32 v123, 0xffff0000, v120
	v_lshlrev_b32_e32 v144, 16, v145
	v_and_b32_e32 v145, 0xffff0000, v145
	v_lshlrev_b32_e32 v120, 16, v121
	v_and_b32_e32 v121, 0xffff0000, v121
	v_lshlrev_b32_e32 v146, 16, v147
	v_and_b32_e32 v147, 0xffff0000, v147
	v_lshlrev_b32_e32 v148, 16, v124
	v_and_b32_e32 v149, 0xffff0000, v124
	v_lshlrev_b32_e32 v152, 16, v126
	v_and_b32_e32 v153, 0xffff0000, v126
	v_lshlrev_b32_e32 v154, 16, v127
	v_and_b32_e32 v155, 0xffff0000, v127
	v_pk_add_f32 v[126:127], v[96:97], v[122:123]
	v_pk_add_f32 v[122:123], v[100:101], v[144:145]
	v_lshlrev_b32_e32 v150, 16, v125
	v_and_b32_e32 v151, 0xffff0000, v125
	v_pk_add_f32 v[124:125], v[98:99], v[120:121]
	v_pk_add_f32 v[120:121], v[102:103], v[146:147]
	v_pk_add_f32 v[102:103], v[104:105], v[148:149]
	v_mul_f32_e32 v104, v127, v127
	v_mul_f32_e32 v105, v123, v123
	v_pk_add_f32 v[100:101], v[106:107], v[150:151]
	v_pk_add_f32 v[98:99], v[108:109], v[152:153]
	v_mul_f32_e32 v106, v103, v103
	v_fmac_f32_e32 v104, v126, v126
	v_fmac_f32_e32 v105, v122, v122
	v_mul_f32_e32 v107, v99, v99
	v_fmac_f32_e32 v106, v102, v102
	v_fmac_f32_e32 v104, v124, v124
	v_fmac_f32_e32 v105, v120, v120
	v_pk_add_f32 v[96:97], v[110:111], v[154:155]
	v_fmac_f32_e32 v107, v98, v98
	v_fmac_f32_e32 v106, v100, v100
	v_fmac_f32_e32 v104, v125, v125
	v_fmac_f32_e32 v105, v121, v121
	v_fmac_f32_e32 v107, v96, v96
	v_fmac_f32_e32 v106, v101, v101
	v_add_f32_e32 v104, v104, v105
	v_lshlrev_b32_e32 v128, 2, v128
	v_fmac_f32_e32 v107, v97, v97
	v_add_f32_e32 v104, v104, v106
	v_xor_b32_e32 v128, 64, v128
	v_add_f32_e32 v104, v107, v104
	v_mov_b32_e32 v105, v104
	s_nop 1
	v_permlane16_swap_b32_e32 v105, v104
	v_mbcnt_lo_u32_b32 v106, -1, 0
	v_mbcnt_hi_u32_b32 v106, -1, v106
	s_waitcnt lgkmcnt(0)
	v_add_f32_e32 v104, v104, v105
	v_lshlrev_b32_e32 v106, 2, v106
	v_xor_b32_e32 v105, 0x80, v106
	ds_bpermute_b32 v105, v105, v104
	s_and_saveexec_b64 s[4:5], vcc
	s_cbranch_execz .LBB0_1149
	s_waitcnt lgkmcnt(0)
	v_add_f32_e32 v104, v104, v105
	v_lshl_add_u32 v105, v143, 4, s77
	ds_write_b32 v105, v104
.LBB0_1149:
	s_or_b64 exec, exec, s[4:5]
	v_or_b32_e32 v143, 32, v142
	v_add_u32_e32 v128, s87, v143
	s_waitcnt lgkmcnt(0)
	v_lshlrev_b64 v[104:105], 11, v[128:129]
	v_lshl_add_u64 v[108:109], v[138:139], 0, v[104:105]
	s_waitcnt vmcnt(10)
	v_mov_b32_e32 v104, v176
	v_mov_b32_e32 v105, v177
	v_mov_b32_e32 v106, v178
	v_mov_b32_e32 v107, v179
	s_nop 0
	v_mov_b32_e32 v108, v180
	v_mov_b32_e32 v109, v181
	v_mov_b32_e32 v110, v182
	v_mov_b32_e32 v111, v183
	v_mbcnt_lo_u32_b32 v128, -1, 0
	v_mbcnt_hi_u32_b32 v128, -1, v128
	v_mov_b32_e32 v145, v106
	v_mov_b32_e32 v147, v107
	s_nop 0
	v_permlane16_swap_b32_e32 v104, v145
	v_permlane16_swap_b32_e32 v105, v147
	v_permlane16_swap_b32_e32 v108, v110
	v_permlane16_swap_b32_e32 v109, v111
	v_lshlrev_b32_e32 v106, 16, v104
	v_and_b32_e32 v107, 0xffff0000, v104
	v_lshlrev_b32_e32 v144, 16, v145
	v_and_b32_e32 v145, 0xffff0000, v145
	v_lshlrev_b32_e32 v104, 16, v105
	v_and_b32_e32 v105, 0xffff0000, v105
	v_lshlrev_b32_e32 v146, 16, v147
	v_and_b32_e32 v147, 0xffff0000, v147
	v_lshlrev_b32_e32 v148, 16, v108
	v_and_b32_e32 v149, 0xffff0000, v108
	v_lshlrev_b32_e32 v152, 16, v110
	v_and_b32_e32 v153, 0xffff0000, v110
	v_lshlrev_b32_e32 v154, 16, v111
	v_and_b32_e32 v155, 0xffff0000, v111
	v_pk_add_f32 v[110:111], v[80:81], v[106:107]
	v_pk_add_f32 v[106:107], v[84:85], v[144:145]
	v_lshlrev_b32_e32 v150, 16, v109
	v_and_b32_e32 v151, 0xffff0000, v109
	v_pk_add_f32 v[108:109], v[82:83], v[104:105]
	v_pk_add_f32 v[104:105], v[86:87], v[146:147]
	v_pk_add_f32 v[86:87], v[88:89], v[148:149]
	v_mul_f32_e32 v88, v111, v111
	v_mul_f32_e32 v89, v107, v107
	v_pk_add_f32 v[84:85], v[90:91], v[150:151]
	v_pk_add_f32 v[82:83], v[92:93], v[152:153]
	v_mul_f32_e32 v90, v87, v87
	v_fmac_f32_e32 v88, v110, v110
	v_fmac_f32_e32 v89, v106, v106
	v_mul_f32_e32 v91, v83, v83
	v_fmac_f32_e32 v90, v86, v86
	v_fmac_f32_e32 v88, v108, v108
	v_fmac_f32_e32 v89, v104, v104
	v_pk_add_f32 v[80:81], v[94:95], v[154:155]
	v_fmac_f32_e32 v91, v82, v82
	v_fmac_f32_e32 v90, v84, v84
	v_fmac_f32_e32 v88, v109, v109
	v_fmac_f32_e32 v89, v105, v105
	v_fmac_f32_e32 v91, v80, v80
	v_fmac_f32_e32 v90, v85, v85
	v_add_f32_e32 v88, v88, v89
	v_lshlrev_b32_e32 v128, 2, v128
	v_fmac_f32_e32 v91, v81, v81
	v_add_f32_e32 v88, v88, v90
	v_xor_b32_e32 v128, 64, v128
	v_add_f32_e32 v88, v91, v88
	v_mov_b32_e32 v89, v88
	s_nop 1
	v_permlane16_swap_b32_e32 v89, v88
	v_mbcnt_lo_u32_b32 v90, -1, 0
	v_mbcnt_hi_u32_b32 v90, -1, v90
	s_waitcnt lgkmcnt(0)
	v_add_f32_e32 v88, v88, v89
	v_lshlrev_b32_e32 v90, 2, v90
	v_xor_b32_e32 v89, 0x80, v90
	ds_bpermute_b32 v89, v89, v88
	s_and_saveexec_b64 s[4:5], vcc
	s_cbranch_execz .LBB0_1151
	s_waitcnt lgkmcnt(0)
	v_add_f32_e32 v88, v88, v89
	v_lshl_add_u32 v89, v143, 4, s77
	ds_write_b32 v89, v88
; __device__ __forceinline__ f32x4 unpack4(u32x2 w) { return (f32x4){bflo(w.x), bfhi(w.x), bflo(w.y), bfhi(w.y)}; }
; __device__ __forceinline__ float shfl_xor_f(float v, int mask) { const int l = lane_fresh(); return __int_as_float(__builtin_amdgcn_ds_bpermute((l ^ mask) << 2, __float_as_int(v))); }
; __device__ __forceinline__ void load_pair16(const u16* rowp32, int fq, u32x2& a, u32x2& b) {
;   const u32x4 w = *(const u32x4*)(rowp32 + ((fq & 1) * 16 + (fq >> 1) * 8));
;   auto rx = __builtin_amdgcn_permlane16_swap(w.x, w.z, false, false);
;   auto ry = __builtin_amdgcn_permlane16_swap(w.y, w.w, false, false);
;   a = (u32x2){rx[0], ry[0]}; b = (u32x2){rx[1], ry[1]};
; }
; __device__ __forceinline__ void phaseG(const Params& p, const int wv, const int rep, unsigned* bar, const bool fused) {
;     ...
;             const int rrow = ai * 128 + wr * 64 + m * 16 + fr;
;             float ss = 0.f;
; #pragma unroll
;             for (int bj = 0; bj < 2; ++bj) {
;               u32x2 hp[2];
;               load_pair16(H2 + (size_t)(brow + rrow) * 1024 + bcol + bj * 128 + wc * 32, fq, hp[0], hp[1]);
; #pragma unroll
;               for (int n = 0; n < 2; ++n) {
;                 f32x4 v = acc[ai][bj][m][n] + unpack4(hp[n]);
;                 acc[ai][bj][m][n] = v;
;                 ss += v[0] * v[0] + v[1] * v[1] + v[2] * v[2] + v[3] * v[3];
;               }
;             }
;             ss += shfl_xor_f(ss, 16); ss += shfl_xor_f(ss, 32);
;             if (fq == 0) red[rrow * 4 + wc] = ss;
;           }
.LBB0_1151:
	s_or_b64 exec, exec, s[4:5]
	v_or_b32_e32 v143, 48, v142
	v_add_u32_e32 v128, s87, v143
	s_waitcnt lgkmcnt(0)
	v_lshlrev_b64 v[88:89], 11, v[128:129]
	v_lshl_add_u64 v[92:93], v[138:139], 0, v[88:89]
	s_waitcnt vmcnt(8)
	v_mov_b32_e32 v88, v184
	v_mov_b32_e32 v89, v185
	v_mov_b32_e32 v90, v186
	v_mov_b32_e32 v91, v187
	s_nop 0
	v_mov_b32_e32 v92, v188
	v_mov_b32_e32 v93, v189
	v_mov_b32_e32 v94, v190
	v_mov_b32_e32 v95, v191
	v_mbcnt_lo_u32_b32 v128, -1, 0
	v_mbcnt_hi_u32_b32 v128, -1, v128
	v_mov_b32_e32 v145, v90
	v_mov_b32_e32 v147, v91
	s_nop 0
	v_permlane16_swap_b32_e32 v88, v145
	v_permlane16_swap_b32_e32 v89, v147
	v_permlane16_swap_b32_e32 v92, v94
	v_permlane16_swap_b32_e32 v93, v95
	v_lshlrev_b32_e32 v90, 16, v88
	v_and_b32_e32 v91, 0xffff0000, v88
	v_lshlrev_b32_e32 v144, 16, v145
	v_and_b32_e32 v145, 0xffff0000, v145
	v_lshlrev_b32_e32 v88, 16, v89
	v_and_b32_e32 v89, 0xffff0000, v89
	v_lshlrev_b32_e32 v146, 16, v147
	v_and_b32_e32 v147, 0xffff0000, v147
	v_lshlrev_b32_e32 v148, 16, v92
	v_and_b32_e32 v149, 0xffff0000, v92
	v_lshlrev_b32_e32 v152, 16, v94
	v_and_b32_e32 v153, 0xffff0000, v94
	v_lshlrev_b32_e32 v154, 16, v95
	v_and_b32_e32 v155, 0xffff0000, v95
	v_pk_add_f32 v[94:95], v[64:65], v[90:91]
	v_pk_add_f32 v[90:91], v[68:69], v[144:145]
	v_lshlrev_b32_e32 v150, 16, v93
	v_and_b32_e32 v151, 0xffff0000, v93
	v_pk_add_f32 v[92:93], v[66:67], v[88:89]
	v_pk_add_f32 v[88:89], v[70:71], v[146:147]
	v_pk_add_f32 v[70:71], v[72:73], v[148:149]
	v_mul_f32_e32 v72, v95, v95
	v_mul_f32_e32 v73, v91, v91
	v_pk_add_f32 v[68:69], v[74:75], v[150:151]
	v_pk_add_f32 v[66:67], v[76:77], v[152:153]
	v_mul_f32_e32 v74, v71, v71
	v_fmac_f32_e32 v72, v94, v94
	v_fmac_f32_e32 v73, v90, v90
	v_mul_f32_e32 v75, v67, v67
	v_fmac_f32_e32 v74, v70, v70
	v_fmac_f32_e32 v72, v92, v92
	v_fmac_f32_e32 v73, v88, v88
	v_pk_add_f32 v[64:65], v[78:79], v[154:155]
	v_fmac_f32_e32 v75, v66, v66
	v_fmac_f32_e32 v74, v68, v68
	v_fmac_f32_e32 v72, v93, v93
	v_fmac_f32_e32 v73, v89, v89
	v_fmac_f32_e32 v75, v64, v64
	v_fmac_f32_e32 v74, v69, v69
	v_add_f32_e32 v72, v72, v73
	v_lshlrev_b32_e32 v128, 2, v128
	v_fmac_f32_e32 v75, v65, v65
	v_add_f32_e32 v72, v72, v74
	v_xor_b32_e32 v128, 64, v128
	v_add_f32_e32 v72, v75, v72
	v_mov_b32_e32 v73, v72
	s_nop 1
	v_permlane16_swap_b32_e32 v73, v72
	v_mbcnt_lo_u32_b32 v74, -1, 0
	v_mbcnt_hi_u32_b32 v74, -1, v74
	s_waitcnt lgkmcnt(0)
	v_add_f32_e32 v72, v72, v73
	v_lshlrev_b32_e32 v74, 2, v74
	v_xor_b32_e32 v73, 0x80, v74
	ds_bpermute_b32 v73, v73, v72
	s_and_saveexec_b64 s[4:5], vcc
	s_cbranch_execz .LBB0_1153
	s_waitcnt lgkmcnt(0)
	v_add_f32_e32 v72, v72, v73
	v_lshl_add_u32 v73, v143, 4, s77
	ds_write_b32 v73, v72
.LBB0_1153:
	s_or_b64 exec, exec, s[4:5]
	v_add_u32_e32 v143, 0x80, v142
	v_add_u32_e32 v128, s87, v143
	s_waitcnt lgkmcnt(0)
	v_lshlrev_b64 v[72:73], 11, v[128:129]
	v_lshl_add_u64 v[76:77], v[138:139], 0, v[72:73]
	s_waitcnt vmcnt(6)
	v_mov_b32_e32 v72, v192
	v_mov_b32_e32 v73, v193
	v_mov_b32_e32 v74, v194
	v_mov_b32_e32 v75, v195
	s_nop 0
	v_mov_b32_e32 v76, v196
	v_mov_b32_e32 v77, v197
	v_mov_b32_e32 v78, v198
	v_mov_b32_e32 v79, v199
	v_mbcnt_lo_u32_b32 v128, -1, 0
	v_mbcnt_hi_u32_b32 v128, -1, v128
	v_mov_b32_e32 v145, v74
	v_mov_b32_e32 v147, v75
	s_nop 0
	v_permlane16_swap_b32_e32 v72, v145
	v_permlane16_swap_b32_e32 v73, v147
	v_permlane16_swap_b32_e32 v76, v78
	v_permlane16_swap_b32_e32 v77, v79
	v_lshlrev_b32_e32 v74, 16, v72
	v_and_b32_e32 v75, 0xffff0000, v72
	v_lshlrev_b32_e32 v144, 16, v145
	v_and_b32_e32 v145, 0xffff0000, v145
	v_lshlrev_b32_e32 v72, 16, v73
	v_and_b32_e32 v73, 0xffff0000, v73
	v_lshlrev_b32_e32 v146, 16, v147
	v_and_b32_e32 v147, 0xffff0000, v147
	v_lshlrev_b32_e32 v148, 16, v76
	v_and_b32_e32 v149, 0xffff0000, v76
	v_lshlrev_b32_e32 v152, 16, v78
	v_and_b32_e32 v153, 0xffff0000, v78
	v_lshlrev_b32_e32 v154, 16, v79
	v_and_b32_e32 v155, 0xffff0000, v79
	v_pk_add_f32 v[78:79], v[48:49], v[74:75]
	v_pk_add_f32 v[74:75], v[52:53], v[144:145]
	v_lshlrev_b32_e32 v150, 16, v77
	v_and_b32_e32 v151, 0xffff0000, v77
	v_pk_add_f32 v[76:77], v[50:51], v[72:73]
	v_pk_add_f32 v[72:73], v[54:55], v[146:147]
	v_pk_add_f32 v[54:55], v[56:57], v[148:149]
	v_mul_f32_e32 v56, v79, v79
	v_mul_f32_e32 v57, v75, v75
	v_pk_add_f32 v[52:53], v[58:59], v[150:151]
	v_pk_add_f32 v[50:51], v[60:61], v[152:153]
	v_mul_f32_e32 v58, v55, v55
	v_fmac_f32_e32 v56, v78, v78
	v_fmac_f32_e32 v57, v74, v74
	v_mul_f32_e32 v59, v51, v51
	v_fmac_f32_e32 v58, v54, v54
	v_fmac_f32_e32 v56, v76, v76
	v_fmac_f32_e32 v57, v72, v72
	v_pk_add_f32 v[48:49], v[62:63], v[154:155]
	v_fmac_f32_e32 v59, v50, v50
	v_fmac_f32_e32 v58, v52, v52
	v_fmac_f32_e32 v56, v77, v77
	v_fmac_f32_e32 v57, v73, v73
	v_fmac_f32_e32 v59, v48, v48
	v_fmac_f32_e32 v58, v53, v53
	v_add_f32_e32 v56, v56, v57
	v_lshlrev_b32_e32 v128, 2, v128
	v_fmac_f32_e32 v59, v49, v49
	v_add_f32_e32 v56, v56, v58
	v_xor_b32_e32 v128, 64, v128
	v_add_f32_e32 v56, v59, v56
	v_mov_b32_e32 v57, v56
	s_nop 1
	v_permlane16_swap_b32_e32 v57, v56
	v_mbcnt_lo_u32_b32 v58, -1, 0
	v_mbcnt_hi_u32_b32 v58, -1, v58
	s_waitcnt lgkmcnt(0)
	v_add_f32_e32 v56, v56, v57
	v_lshlrev_b32_e32 v58, 2, v58
	v_xor_b32_e32 v57, 0x80, v58
	ds_bpermute_b32 v57, v57, v56
	s_and_saveexec_b64 s[4:5], vcc
	s_cbranch_execz .LBB0_1155
	s_waitcnt lgkmcnt(0)
	v_add_f32_e32 v56, v56, v57
	v_lshl_add_u32 v57, v143, 4, s77
	ds_write_b32 v57, v56
; __device__ __forceinline__ f32x4 unpack4(u32x2 w) { return (f32x4){bflo(w.x), bfhi(w.x), bflo(w.y), bfhi(w.y)}; }
; __device__ __forceinline__ float shfl_xor_f(float v, int mask) { const int l = lane_fresh(); return __int_as_float(__builtin_amdgcn_ds_bpermute((l ^ mask) << 2, __float_as_int(v))); }
; __device__ __forceinline__ void load_pair16(const u16* rowp32, int fq, u32x2& a, u32x2& b) {
;   const u32x4 w = *(const u32x4*)(rowp32 + ((fq & 1) * 16 + (fq >> 1) * 8));
;   auto rx = __builtin_amdgcn_permlane16_swap(w.x, w.z, false, false);
;   auto ry = __builtin_amdgcn_permlane16_swap(w.y, w.w, false, false);
;   a = (u32x2){rx[0], ry[0]}; b = (u32x2){rx[1], ry[1]};
; }
; __device__ __forceinline__ void phaseG(const Params& p, const int wv, const int rep, unsigned* bar, const bool fused) {
;     ...
;             const int rrow = ai * 128 + wr * 64 + m * 16 + fr;
;             float ss = 0.f;
; #pragma unroll
;             for (int bj = 0; bj < 2; ++bj) {
;               u32x2 hp[2];
;               load_pair16(H2 + (size_t)(brow + rrow) * 1024 + bcol + bj * 128 + wc * 32, fq, hp[0], hp[1]);
; #pragma unroll
;               for (int n = 0; n < 2; ++n) {
;                 f32x4 v = acc[ai][bj][m][n] + unpack4(hp[n]);
;                 acc[ai][bj][m][n] = v;
;                 ss += v[0] * v[0] + v[1] * v[1] + v[2] * v[2] + v[3] * v[3];
;               }
;             }
;             ss += shfl_xor_f(ss, 16); ss += shfl_xor_f(ss, 32);
;             if (fq == 0) red[rrow * 4 + wc] = ss;
;           }
.LBB0_1155:
	s_or_b64 exec, exec, s[4:5]
	v_add_u32_e32 v143, 0x90, v142
	v_add_u32_e32 v128, s87, v143
	s_waitcnt lgkmcnt(0)
	v_lshlrev_b64 v[56:57], 11, v[128:129]
	v_lshl_add_u64 v[60:61], v[138:139], 0, v[56:57]
	s_waitcnt vmcnt(4)
	v_mov_b32_e32 v56, v200
	v_mov_b32_e32 v57, v201
	v_mov_b32_e32 v58, v202
	v_mov_b32_e32 v59, v203
	s_nop 0
	v_mov_b32_e32 v60, v204
	v_mov_b32_e32 v61, v205
	v_mov_b32_e32 v62, v206
	v_mov_b32_e32 v63, v207
	v_mbcnt_lo_u32_b32 v128, -1, 0
	v_mbcnt_hi_u32_b32 v128, -1, v128
	v_mov_b32_e32 v145, v58
	v_mov_b32_e32 v147, v59
	s_nop 0
	v_permlane16_swap_b32_e32 v56, v145
	v_permlane16_swap_b32_e32 v57, v147
	v_permlane16_swap_b32_e32 v60, v62
	v_permlane16_swap_b32_e32 v61, v63
	v_lshlrev_b32_e32 v58, 16, v56
	v_and_b32_e32 v59, 0xffff0000, v56
	v_lshlrev_b32_e32 v144, 16, v145
	v_and_b32_e32 v145, 0xffff0000, v145
	v_lshlrev_b32_e32 v56, 16, v57
	v_and_b32_e32 v57, 0xffff0000, v57
	v_lshlrev_b32_e32 v146, 16, v147
	v_and_b32_e32 v147, 0xffff0000, v147
	v_lshlrev_b32_e32 v148, 16, v60
	v_and_b32_e32 v149, 0xffff0000, v60
	v_lshlrev_b32_e32 v152, 16, v62
	v_and_b32_e32 v153, 0xffff0000, v62
	v_lshlrev_b32_e32 v154, 16, v63
	v_and_b32_e32 v155, 0xffff0000, v63
	v_pk_add_f32 v[62:63], v[32:33], v[58:59]
	v_pk_add_f32 v[58:59], v[36:37], v[144:145]
	v_lshlrev_b32_e32 v150, 16, v61
	v_and_b32_e32 v151, 0xffff0000, v61
	v_pk_add_f32 v[60:61], v[34:35], v[56:57]
	v_pk_add_f32 v[56:57], v[38:39], v[146:147]
	v_pk_add_f32 v[38:39], v[40:41], v[148:149]
	v_mul_f32_e32 v40, v63, v63
	v_mul_f32_e32 v41, v59, v59
	v_pk_add_f32 v[36:37], v[42:43], v[150:151]
	v_pk_add_f32 v[34:35], v[44:45], v[152:153]
	v_mul_f32_e32 v42, v39, v39
	v_fmac_f32_e32 v40, v62, v62
	v_fmac_f32_e32 v41, v58, v58
	v_mul_f32_e32 v43, v35, v35
	v_fmac_f32_e32 v42, v38, v38
	v_fmac_f32_e32 v40, v60, v60
	v_fmac_f32_e32 v41, v56, v56
	v_pk_add_f32 v[32:33], v[46:47], v[154:155]
	v_fmac_f32_e32 v43, v34, v34
	v_fmac_f32_e32 v42, v36, v36
	v_fmac_f32_e32 v40, v61, v61
	v_fmac_f32_e32 v41, v57, v57
	v_fmac_f32_e32 v43, v32, v32
	v_fmac_f32_e32 v42, v37, v37
	v_add_f32_e32 v40, v40, v41
	v_lshlrev_b32_e32 v128, 2, v128
	v_fmac_f32_e32 v43, v33, v33
	v_add_f32_e32 v40, v40, v42
	v_xor_b32_e32 v128, 64, v128
	v_add_f32_e32 v40, v43, v40
	v_mov_b32_e32 v41, v40
	s_nop 1
	v_permlane16_swap_b32_e32 v41, v40
	v_mbcnt_lo_u32_b32 v42, -1, 0
	v_mbcnt_hi_u32_b32 v42, -1, v42
	s_waitcnt lgkmcnt(0)
	v_add_f32_e32 v40, v40, v41
	v_lshlrev_b32_e32 v42, 2, v42
	v_xor_b32_e32 v41, 0x80, v42
	ds_bpermute_b32 v41, v41, v40
	s_and_saveexec_b64 s[4:5], vcc
	s_cbranch_execz .LBB0_1157
	s_waitcnt lgkmcnt(0)
	v_add_f32_e32 v40, v40, v41
	v_lshl_add_u32 v41, v143, 4, s77
	ds_write_b32 v41, v40
; __device__ __forceinline__ f32x4 unpack4(u32x2 w) { return (f32x4){bflo(w.x), bfhi(w.x), bflo(w.y), bfhi(w.y)}; }
; __device__ __forceinline__ float shfl_xor_f(float v, int mask) { const int l = lane_fresh(); return __int_as_float(__builtin_amdgcn_ds_bpermute((l ^ mask) << 2, __float_as_int(v))); }
; __device__ __forceinline__ void load_pair16(const u16* rowp32, int fq, u32x2& a, u32x2& b) {
;   const u32x4 w = *(const u32x4*)(rowp32 + ((fq & 1) * 16 + (fq >> 1) * 8));
;   auto rx = __builtin_amdgcn_permlane16_swap(w.x, w.z, false, false);
;   auto ry = __builtin_amdgcn_permlane16_swap(w.y, w.w, false, false);
;   a = (u32x2){rx[0], ry[0]}; b = (u32x2){rx[1], ry[1]};
; }
; __device__ __forceinline__ void phaseG(const Params& p, const int wv, const int rep, unsigned* bar, const bool fused) {
;     ...
;             const int rrow = ai * 128 + wr * 64 + m * 16 + fr;
;             float ss = 0.f;
; #pragma unroll
;             for (int bj = 0; bj < 2; ++bj) {
;               u32x2 hp[2];
;               load_pair16(H2 + (size_t)(brow + rrow) * 1024 + bcol + bj * 128 + wc * 32, fq, hp[0], hp[1]);
; #pragma unroll
;               for (int n = 0; n < 2; ++n) {
;                 f32x4 v = acc[ai][bj][m][n] + unpack4(hp[n]);
;                 acc[ai][bj][m][n] = v;
;                 ss += v[0] * v[0] + v[1] * v[1] + v[2] * v[2] + v[3] * v[3];
;               }
;             }
;             ss += shfl_xor_f(ss, 16); ss += shfl_xor_f(ss, 32);
;             if (fq == 0) red[rrow * 4 + wc] = ss;
;           }
.LBB0_1157:
	s_or_b64 exec, exec, s[4:5]
	v_add_u32_e32 v143, 0xa0, v142
	v_add_u32_e32 v128, s87, v143
	s_waitcnt lgkmcnt(0)
	v_lshlrev_b64 v[40:41], 11, v[128:129]
	v_lshl_add_u64 v[44:45], v[138:139], 0, v[40:41]
	s_waitcnt vmcnt(2)
	v_mov_b32_e32 v40, v208
	v_mov_b32_e32 v41, v209
	v_mov_b32_e32 v42, v210
	v_mov_b32_e32 v43, v211
	s_nop 0
	v_mov_b32_e32 v44, v212
	v_mov_b32_e32 v45, v213
	v_mov_b32_e32 v46, v214
	v_mov_b32_e32 v47, v215
	v_mbcnt_lo_u32_b32 v128, -1, 0
	v_mbcnt_hi_u32_b32 v128, -1, v128
	v_mov_b32_e32 v145, v42
	v_mov_b32_e32 v147, v43
	s_nop 0
	v_permlane16_swap_b32_e32 v40, v145
	v_permlane16_swap_b32_e32 v41, v147
	v_permlane16_swap_b32_e32 v44, v46
	v_permlane16_swap_b32_e32 v45, v47
	v_lshlrev_b32_e32 v42, 16, v40
	v_and_b32_e32 v43, 0xffff0000, v40
	v_lshlrev_b32_e32 v144, 16, v145
	v_and_b32_e32 v145, 0xffff0000, v145
	v_lshlrev_b32_e32 v40, 16, v41
	v_and_b32_e32 v41, 0xffff0000, v41
	v_lshlrev_b32_e32 v146, 16, v147
	v_and_b32_e32 v147, 0xffff0000, v147
	v_lshlrev_b32_e32 v148, 16, v44
	v_and_b32_e32 v149, 0xffff0000, v44
	v_lshlrev_b32_e32 v152, 16, v46
	v_and_b32_e32 v153, 0xffff0000, v46
	v_lshlrev_b32_e32 v154, 16, v47
	v_and_b32_e32 v155, 0xffff0000, v47
	v_pk_add_f32 v[46:47], v[16:17], v[42:43]
	v_pk_add_f32 v[42:43], v[20:21], v[144:145]
	v_lshlrev_b32_e32 v150, 16, v45
	v_and_b32_e32 v151, 0xffff0000, v45
	v_pk_add_f32 v[44:45], v[18:19], v[40:41]
	v_pk_add_f32 v[40:41], v[22:23], v[146:147]
	v_pk_add_f32 v[22:23], v[24:25], v[148:149]
	v_mul_f32_e32 v24, v47, v47
	v_mul_f32_e32 v25, v43, v43
	v_pk_add_f32 v[20:21], v[26:27], v[150:151]
	v_pk_add_f32 v[18:19], v[28:29], v[152:153]
	v_mul_f32_e32 v26, v23, v23
	v_fmac_f32_e32 v24, v46, v46
	v_fmac_f32_e32 v25, v42, v42
	v_mul_f32_e32 v27, v19, v19
	v_fmac_f32_e32 v26, v22, v22
	v_fmac_f32_e32 v24, v44, v44
	v_fmac_f32_e32 v25, v40, v40
	v_pk_add_f32 v[16:17], v[30:31], v[154:155]
	v_fmac_f32_e32 v27, v18, v18
	v_fmac_f32_e32 v26, v20, v20
	v_fmac_f32_e32 v24, v45, v45
	v_fmac_f32_e32 v25, v41, v41
	v_fmac_f32_e32 v27, v16, v16
	v_fmac_f32_e32 v26, v21, v21
	v_add_f32_e32 v24, v24, v25
	v_lshlrev_b32_e32 v128, 2, v128
	v_fmac_f32_e32 v27, v17, v17
	v_add_f32_e32 v24, v24, v26
	v_xor_b32_e32 v128, 64, v128
	v_add_f32_e32 v24, v27, v24
	v_mov_b32_e32 v25, v24
	s_nop 1
	v_permlane16_swap_b32_e32 v25, v24
	v_mbcnt_lo_u32_b32 v26, -1, 0
	v_mbcnt_hi_u32_b32 v26, -1, v26
	s_waitcnt lgkmcnt(0)
	v_add_f32_e32 v24, v24, v25
	v_lshlrev_b32_e32 v26, 2, v26
	v_xor_b32_e32 v25, 0x80, v26
	ds_bpermute_b32 v25, v25, v24
	s_and_saveexec_b64 s[4:5], vcc
	s_cbranch_execz .LBB0_1159
	s_waitcnt lgkmcnt(0)
	v_add_f32_e32 v24, v24, v25
	v_lshl_add_u32 v25, v143, 4, s77
	ds_write_b32 v25, v24
.LBB0_1159:
	s_or_b64 exec, exec, s[4:5]
	v_add_u32_e32 v142, 0xb0, v142
	v_add_u32_e32 v128, s87, v142
	s_waitcnt lgkmcnt(0)
	v_lshlrev_b64 v[24:25], 11, v[128:129]
	v_lshl_add_u64 v[28:29], v[138:139], 0, v[24:25]
	s_waitcnt vmcnt(0)
	v_mov_b32_e32 v24, v216
	v_mov_b32_e32 v25, v217
	v_mov_b32_e32 v26, v218
	v_mov_b32_e32 v27, v219
	s_nop 0
	v_mov_b32_e32 v28, v220
	v_mov_b32_e32 v29, v221
	v_mov_b32_e32 v30, v222
	v_mov_b32_e32 v31, v223
	v_mbcnt_lo_u32_b32 v128, -1, 0
	v_mbcnt_hi_u32_b32 v128, -1, v128
	v_mov_b32_e32 v139, v26
	v_mov_b32_e32 v143, v27
	s_nop 0
	v_permlane16_swap_b32_e32 v24, v139
	v_permlane16_swap_b32_e32 v25, v143
	v_permlane16_swap_b32_e32 v28, v30
	v_permlane16_swap_b32_e32 v29, v31
	v_lshlrev_b32_e32 v26, 16, v24
	v_and_b32_e32 v27, 0xffff0000, v24
	v_lshlrev_b32_e32 v138, 16, v139
	v_and_b32_e32 v139, 0xffff0000, v139
	v_lshlrev_b32_e32 v24, 16, v25
	v_and_b32_e32 v25, 0xffff0000, v25
	v_lshlrev_b32_e32 v144, 16, v143
	v_and_b32_e32 v145, 0xffff0000, v143
	v_lshlrev_b32_e32 v146, 16, v28
	v_and_b32_e32 v147, 0xffff0000, v28
	v_lshlrev_b32_e32 v150, 16, v30
	v_and_b32_e32 v151, 0xffff0000, v30
	v_lshlrev_b32_e32 v152, 16, v31
	v_and_b32_e32 v153, 0xffff0000, v31
	v_pk_add_f32 v[30:31], v[0:1], v[26:27]
	v_pk_add_f32 v[26:27], v[4:5], v[138:139]
	v_lshlrev_b32_e32 v148, 16, v29
	v_and_b32_e32 v149, 0xffff0000, v29
	v_pk_add_f32 v[28:29], v[2:3], v[24:25]
	v_pk_add_f32 v[24:25], v[6:7], v[144:145]
	v_pk_add_f32 v[6:7], v[8:9], v[146:147]
	v_mul_f32_e32 v8, v31, v31
	v_mul_f32_e32 v9, v27, v27
	v_pk_add_f32 v[4:5], v[10:11], v[148:149]
	v_pk_add_f32 v[2:3], v[12:13], v[150:151]
	v_mul_f32_e32 v10, v7, v7
	v_fmac_f32_e32 v8, v30, v30
	v_fmac_f32_e32 v9, v26, v26
	v_mul_f32_e32 v11, v3, v3
	v_fmac_f32_e32 v10, v6, v6
	v_fmac_f32_e32 v8, v28, v28
	v_fmac_f32_e32 v9, v24, v24
	v_pk_add_f32 v[0:1], v[14:15], v[152:153]
	v_fmac_f32_e32 v11, v2, v2
	v_fmac_f32_e32 v10, v4, v4
	v_fmac_f32_e32 v8, v29, v29
	v_fmac_f32_e32 v9, v25, v25
	v_fmac_f32_e32 v11, v0, v0
	v_fmac_f32_e32 v10, v5, v5
	v_add_f32_e32 v8, v8, v9
	v_lshlrev_b32_e32 v128, 2, v128
	v_fmac_f32_e32 v11, v1, v1
	v_add_f32_e32 v8, v8, v10
	v_xor_b32_e32 v128, 64, v128
	v_add_f32_e32 v8, v11, v8
	v_mov_b32_e32 v9, v8
	s_nop 1
	v_permlane16_swap_b32_e32 v9, v8
	v_mbcnt_lo_u32_b32 v10, -1, 0
	v_mbcnt_hi_u32_b32 v10, -1, v10
	s_waitcnt lgkmcnt(0)
	v_add_f32_e32 v8, v8, v9
	v_lshlrev_b32_e32 v10, 2, v10
	v_xor_b32_e32 v9, 0x80, v10
	ds_bpermute_b32 v9, v9, v8
	s_and_saveexec_b64 s[4:5], vcc
	s_cbranch_execz .LBB0_1161
	s_waitcnt lgkmcnt(0)
	v_add_f32_e32 v8, v8, v9
	v_lshl_add_u32 v9, v142, 4, s77
	ds_write_b32 v9, v8

; __device__ __forceinline__ f32x4 unpack4(u32x2 w) { return (f32x4){bflo(w.x), bfhi(w.x), bflo(w.y), bfhi(w.y)}; }
; __device__ __forceinline__ int lane_fresh() { int l; asm volatile("v_mbcnt_lo_u32_b32 %0, -1, 0\n\tv_mbcnt_hi_u32_b32 %0, -1, %0" : "=v"(l)); return l; }
; __device__ __forceinline__ float shfl_xor_f(float v, int mask) { const int l = lane_fresh(); return __int_as_float(__builtin_amdgcn_ds_bpermute((l ^ mask) << 2, __float_as_int(v))); }
; __device__ __forceinline__ f32x4 skreduce(int i) {
;   const float* part = (const float*)g_shm;
;   const int lane = lane_fresh();
;   f32x4 s = {0.f, 0.f, 0.f, 0.f};
; #pragma unroll
;   for (int w = 0; w < 8; ++w) s += *(const f32x4*)(part + ((i * 8 + w) * 64 + lane) * 4);
;   return s;
; }
; __device__ __forceinline__ void phaseG(const Params& p, const int wv, const int rep, unsigned* bar, const bool fused) {
;     ...
;       if (wv < 2) {
;         const int lane_e = lane_fresh(), fr = lane_e & 15, fq = lane_e >> 4;
;         const int row = TP + mt * 16 + fr, col = (nt0 + wv) * 16 + fq * 4;
;         const size_t o = (size_t)row * 1024 + col;
;         f32x4 v = skreduce(wv) + unpack4(*(const u32x2*)(H2 + o));
;         float* yo = p.out + O_Y + o;
; #pragma unroll
;         for (int e = 0; e < 4; ++e) __hip_atomic_store(yo + e, v[e], __ATOMIC_RELAXED, __HIP_MEMORY_SCOPE_AGENT);
;         float ss = v[0] * v[0] + v[1] * v[1] + v[2] * v[2] + v[3] * v[3];
;         ss += shfl_xor_f(ss, 16); ss += shfl_xor_f(ss, 32);
;         if (fq == 0) __hip_atomic_store(XSS + (size_t)(row - TP) * 64 + nt0 + wv, ss, __ATOMIC_RELAXED, __HIP_MEMORY_SCOPE_AGENT);
;       }
.LBB0_1191:
	s_andn2_b64 vcc, exec, s[24:25]
	s_cbranch_vccnz .LBB0_1182
	s_and_b64 vcc, exec, s[4:5]
	s_cbranch_vccnz .LBB0_1196
	v_mbcnt_lo_u32_b32 v4, -1, 0
	v_mbcnt_hi_u32_b32 v4, -1, v4
	s_or_b32 s19, s2, s41
	v_ashrrev_i32_e32 v1, 2, v4
	v_and_or_b32 v0, v4, 15, s20
	v_and_b32_e32 v1, -4, v1
	v_lshl_add_u32 v2, s19, 4, v1
	v_ashrrev_i32_e32 v1, 31, v0
	v_lshlrev_b64 v[6:7], 10, v[0:1]
	v_ashrrev_i32_e32 v3, 31, v2
	v_lshl_add_u64 v[2:3], v[6:7], 0, v[2:3]
	v_lshl_add_u64 v[6:7], v[2:3], 1, s[8:9]
	v_mbcnt_lo_u32_b32 v8, -1, 0
	v_mbcnt_hi_u32_b32 v8, -1, v8
	v_mov_b32_e32 v40, v248
	v_mov_b32_e32 v41, v249
	v_lshl_add_u32 v36, v8, 4, s34
	ds_read_b128 v[6:9], v36
	ds_read_b128 v[10:13], v36 offset:1024
	ds_read_b128 v[16:19], v36 offset:2048
	ds_read_b128 v[20:23], v36 offset:3072
	ds_read_b128 v[24:27], v36 offset:4096
	ds_read_b128 v[28:31], v36 offset:5120
	ds_read_b128 v[32:35], v36 offset:6144
	ds_read_b128 v[36:39], v36 offset:7168
	s_waitcnt lgkmcnt(7)
	v_pk_add_f32 v[6:7], v[6:7], 0 op_sel_hi:[1,0]
	v_pk_add_f32 v[8:9], v[8:9], 0 op_sel_hi:[1,0]
	s_waitcnt lgkmcnt(6)
	v_pk_add_f32 v[6:7], v[6:7], v[10:11]
	v_pk_add_f32 v[8:9], v[8:9], v[12:13]
	s_waitcnt lgkmcnt(5)
	v_pk_add_f32 v[6:7], v[6:7], v[16:17]
	v_pk_add_f32 v[8:9], v[8:9], v[18:19]
	s_waitcnt lgkmcnt(4)
	v_pk_add_f32 v[6:7], v[6:7], v[20:21]
	v_pk_add_f32 v[8:9], v[8:9], v[22:23]
	s_waitcnt lgkmcnt(3)
	v_pk_add_f32 v[6:7], v[6:7], v[24:25]
	v_pk_add_f32 v[8:9], v[8:9], v[26:27]
	s_waitcnt lgkmcnt(2)
	v_pk_add_f32 v[6:7], v[6:7], v[28:29]
	v_pk_add_f32 v[8:9], v[8:9], v[30:31]
	s_waitcnt lgkmcnt(1)
	v_pk_add_f32 v[6:7], v[6:7], v[32:33]
	v_pk_add_f32 v[8:9], v[8:9], v[34:35]
	s_waitcnt lgkmcnt(0)
	v_pk_add_f32 v[6:7], v[6:7], v[36:37]
	v_lshl_add_u64 v[2:3], v[2:3], 2, s[48:49]
	v_pk_add_f32 v[8:9], v[8:9], v[38:39]
	v_cmp_gt_u32_e32 vcc, 16, v4
	s_waitcnt vmcnt(0)
	v_lshlrev_b32_e32 v10, 16, v40
	v_and_b32_e32 v11, 0xffff0000, v40
	v_lshlrev_b32_e32 v12, 16, v41
	v_and_b32_e32 v13, 0xffff0000, v41
	v_pk_add_f32 v[6:7], v[6:7], v[10:11]
	v_pk_add_f32 v[8:9], v[8:9], v[12:13]
	global_store_dword v[2:3], v6, off sc1
	global_store_dword v[2:3], v7, off offset:4 sc1
	global_store_dword v[2:3], v8, off offset:8 sc1
	global_store_dword v[2:3], v9, off offset:12 sc1
	v_mul_f32_e32 v2, v7, v7
	v_mbcnt_lo_u32_b32 v3, -1, 0
	v_mbcnt_hi_u32_b32 v3, -1, v3
	v_fmac_f32_e32 v2, v6, v6
	v_lshlrev_b32_e32 v3, 2, v3
	v_fmac_f32_e32 v2, v8, v8
	v_xor_b32_e32 v3, 64, v3
	v_fmac_f32_e32 v2, v9, v9
	v_mov_b32_e32 v3, v2
	s_nop 1
	v_permlane16_swap_b32_e32 v3, v2
	v_mbcnt_lo_u32_b32 v6, -1, 0
	v_mbcnt_hi_u32_b32 v6, -1, v6
	s_waitcnt lgkmcnt(0)
	v_add_f32_e32 v2, v2, v3
	v_lshlrev_b32_e32 v6, 2, v6
	v_xor_b32_e32 v3, 0x80, v6
	ds_bpermute_b32 v3, v3, v2
	s_and_saveexec_b64 s[24:25], vcc
	s_cbranch_execz .LBB0_1195
	v_lshlrev_b64 v[0:1], 8, v[0:1]
	v_lshl_add_u64 v[0:1], s[10:11], 0, v[0:1]
	s_lshl_b32 s2, s2, 2
	v_lshl_add_u64 v[0:1], v[0:1], 0, s[2:3]
	s_mov_b32 s19, s3
	v_lshl_add_u64 v[0:1], v[0:1], 0, s[18:19]
	v_add_co_u32_e32 v0, vcc, 0xffc00000, v0
	s_waitcnt lgkmcnt(0)
	v_add_f32_e32 v2, v2, v3
	v_addc_co_u32_e32 v1, vcc, -1, v1, vcc
	global_store_dword v[0:1], v2, off sc1
